# first K-iteration of every GEMM loop peeled with zero accumulator operand; explicit accumulator zeroing removed
# speedup vs baseline: 1.0253x; 1.0028x over previous
; #define PG8_STAGE(bufoff, gbase, voff) do { _Pragma("unroll") for (int _i = 0; _i < 2; ++_i) \
;         __builtin_amdgcn_global_load_lds((const unsigned*)((const char*)(gbase) + (voff)[_i]), (PG8_LAS unsigned*)(lds + (bufoff) + ldsw + _i * 8192), 16, 0, 0); } while (0)
; #define PG8_LDA(dst, b, h) do { _Pragma("unroll") for (int m = 0; m < 4; ++m) _Pragma("unroll") for (int k = 0; k < 2; ++k) dst[m][k] = *(const PG8_LAS bf16x8*)(lds + PG8_SA(b, h) + aoff + m * 2048 + k * 1024); } while (0)
; #define PG8_LDB(dst, b, h) do { _Pragma("unroll") for (int n = 0; n < 2; ++n) _Pragma("unroll") for (int k = 0; k < 2; ++k) dst[n][k] = *(const PG8_LAS bf16x8*)(lds + PG8_SB(b, h) + boff + n * 2048 + k * 1024); } while (0)
; #define PG8_WAIT_V(n) asm volatile("s_waitcnt vmcnt(" #n ")" ::: "memory")
; #define PG8_WAIT_L(n) asm volatile("s_waitcnt lgkmcnt(" #n ")" ::: "memory")
; #define PG8_BAR __builtin_amdgcn_s_barrier()
; #define PG8_SCHED __builtin_amdgcn_sched_barrier(0)
; template <class Epi, class Sched, bool ALIGN_EPI = false, bool SP2 = false>
; __device__ __forceinline__ void gemm_phase(PG8_LAS unsigned char* lds, const Gemm g, const Sched& S, const Epi& E) {
;     ...
;         const bool has_next = S.next(ui + 1, nxt);
;         const char* nA = has_next ? (const char*)g.A + (size_t)nxt.pm * tstep : cA; const char* nB = has_next ? (const char*)g.Bt + (size_t)nxt.pn * tstep : cB;
;         for (int t = 0; t < nt; t += 2) {
;             const bool last = (t == nt - 2);
;             const char* a1 = cA + (size_t)(t + 1) * kstep;
;             const char* a2 = last ? nA : cA + (size_t)(t + 2) * kstep; const char* b2 = last ? nB : cB + (size_t)(t + 2) * kstep;
;             const char* a3 = a2 + kstep; const char* b3 = b2 + kstep;
;             if (last && has_next) S.a_ready(nxt);
;             if constexpr (SP2) {
;             PG8_LDB(B0, 0, 0); PG8_LDB(B1, 0, 1); PG8_SCHED; PG8_LDA(At, 0, 0); PG8_STAGE(PG8_SA(1, 1), a1 + hstep, voffA);
;             PG8_WAIT_V(8); PG8_WAIT_L(0); PG8_BAR; PG8_MMA(0, 0, At, B0); PG8_MMA(0, 1, At, B1); PG8_BAR; PG8_SCHED;
;             PG8_LDA(At, 0, 1); PG8_STAGE(PG8_SB(0, 0), b2, voffB); PG8_STAGE(PG8_SB(0, 1), b2 + hstep, voffB); PG8_STAGE(PG8_SA(0, 0), a2, voffA);
;             PG8_WAIT_V(8); PG8_WAIT_L(0); PG8_BAR; PG8_MMA(1, 0, At, B0); PG8_MMA(1, 1, At, B1); PG8_BAR; PG8_SCHED;
.LBB0_126:
	s_ashr_i32 s73, s72, 31
	s_lshl_b64 s[12:13], s[72:73], 20
	s_add_u32 s82, s40, s12
	s_addc_u32 s83, s41, s13
	s_and_b64 s[12:13], s[4:5], exec
	s_cselect_b32 s12, s83, s91
	s_cselect_b32 s13, s82, s90
	s_ashr_i32 s71, s70, 31
	s_lshl_b64 s[66:67], s[70:71], 20
	s_add_u32 s86, s78, s66
	s_addc_u32 s87, s79, s67
	s_and_b64 s[66:67], s[4:5], exec
	s_cselect_b32 s71, s87, s93
	s_cselect_b32 s73, s86, s92
	s_add_u32 s90, s90, 0x80080
	s_addc_u32 s91, s91, 0
	s_add_u32 vcc_lo, s92, 0x100
	s_addc_u32 vcc_hi, s93, 0
	s_mov_b32 s66, -2
	ds_read_b128 v[146:149], v167
	ds_read_b128 v[150:153], v167 offset:1024
	ds_read_b128 v[168:171], v167 offset:2048
	ds_read_b128 v[178:181], v167 offset:3072
	ds_read_b128 v[182:185], v173
	ds_read_b128 v[186:189], v173 offset:1024
	ds_read_b128 v[190:193], v173 offset:2048
	ds_read_b128 v[194:197], v173 offset:3072
	s_add_u32 s67, s90, 0xfff80080
	s_addc_u32 s74, s91, -1
	s_cmp_eq_u32 s66, 28
	s_cselect_b32 s95, s12, s74
	s_cselect_b32 s94, s13, s67
	s_cselect_b32 s93, s71, vcc_hi
	s_cselect_b32 s92, s73, vcc_lo
	v_lshl_add_u64 v[156:157], s[90:91], 0, v[138:139]
	s_add_i32 m0, s15, 0xc000
	ds_read_b128 v[198:201], v175
	ds_read_b128 v[202:205], v175 offset:1024
	ds_read_b128 v[206:209], v175 offset:2048
	ds_read_b128 v[210:213], v175 offset:3072
	ds_read_b128 v[218:221], v175 offset:4096
	ds_read_b128 v[224:227], v175 offset:5120
	ds_read_b128 v[228:231], v175 offset:6144
	ds_read_b128 v[232:235], v175 offset:7168
	global_load_lds_dwordx4 v[156:157], off
	v_lshl_add_u64 v[156:157], s[90:91], 0, v[140:141]
	s_add_i32 m0, s15, 0xe000
	s_nop 0
	global_load_lds_dwordx4 v[156:157], off
	s_waitcnt vmcnt(8)
	s_waitcnt lgkmcnt(0)
	s_setprio 1
	s_barrier
	v_mfma_f32_16x16x32_bf16 v[124:127], v[146:149], v[198:201], 0
	v_mfma_f32_16x16x32_bf16 v[120:123], v[168:171], v[198:201], 0
	v_mfma_f32_16x16x32_bf16 v[108:111], v[146:149], v[206:209], 0
	v_mfma_f32_16x16x32_bf16 v[104:107], v[168:171], v[206:209], 0
	v_mfma_f32_16x16x32_bf16 v[92:95], v[146:149], v[218:221], 0
	v_mfma_f32_16x16x32_bf16 v[88:91], v[168:171], v[218:221], 0
	v_mfma_f32_16x16x32_bf16 v[76:79], v[146:149], v[228:231], 0
	v_mfma_f32_16x16x32_bf16 v[72:75], v[168:171], v[228:231], 0
	v_mfma_f32_16x16x32_bf16 v[124:127], v[150:153], v[202:205], v[124:127]
	v_mfma_f32_16x16x32_bf16 v[120:123], v[178:181], v[202:205], v[120:123]
	v_mfma_f32_16x16x32_bf16 v[108:111], v[150:153], v[210:213], v[108:111]
	v_mfma_f32_16x16x32_bf16 v[104:107], v[178:181], v[210:213], v[104:107]
	v_mfma_f32_16x16x32_bf16 v[92:95], v[150:153], v[224:227], v[92:95]
	v_mfma_f32_16x16x32_bf16 v[88:91], v[178:181], v[224:227], v[88:91]
	v_mfma_f32_16x16x32_bf16 v[76:79], v[150:153], v[232:235], v[76:79]
	v_mfma_f32_16x16x32_bf16 v[72:75], v[178:181], v[232:235], v[72:75]
	v_mfma_f32_16x16x32_bf16 v[116:119], v[182:185], v[198:201], 0
	v_mfma_f32_16x16x32_bf16 v[112:115], v[190:193], v[198:201], 0
	v_mfma_f32_16x16x32_bf16 v[100:103], v[182:185], v[206:209], 0
	v_mfma_f32_16x16x32_bf16 v[96:99], v[190:193], v[206:209], 0
	v_mfma_f32_16x16x32_bf16 v[84:87], v[182:185], v[218:221], 0
	v_mfma_f32_16x16x32_bf16 v[80:83], v[190:193], v[218:221], 0
	v_mfma_f32_16x16x32_bf16 v[68:71], v[182:185], v[228:231], 0
	v_mfma_f32_16x16x32_bf16 v[64:67], v[190:193], v[228:231], 0
	v_mfma_f32_16x16x32_bf16 v[116:119], v[186:189], v[202:205], v[116:119]
	v_mfma_f32_16x16x32_bf16 v[112:115], v[194:197], v[202:205], v[112:115]
	v_mfma_f32_16x16x32_bf16 v[100:103], v[186:189], v[210:213], v[100:103]
	v_mfma_f32_16x16x32_bf16 v[96:99], v[194:197], v[210:213], v[96:99]
	v_mfma_f32_16x16x32_bf16 v[84:87], v[186:189], v[224:227], v[84:87]
	v_mfma_f32_16x16x32_bf16 v[80:83], v[194:197], v[224:227], v[80:83]
	v_mfma_f32_16x16x32_bf16 v[68:71], v[186:189], v[232:235], v[68:71]
	v_mfma_f32_16x16x32_bf16 v[64:67], v[194:197], v[232:235], v[64:67]
	s_barrier
	s_setprio 0
	s_add_i32 s67, s81, s3
	v_lshl_add_u64 v[156:157], s[92:93], 0, v[132:133]
	s_mov_b32 m0, s67
	ds_read_b128 v[198:201], v175 offset:16384
	ds_read_b128 v[202:205], v175 offset:17408
	ds_read_b128 v[206:209], v175 offset:18432
	ds_read_b128 v[210:213], v175 offset:19456
	ds_read_b128 v[218:221], v175 offset:20480
	ds_read_b128 v[224:227], v175 offset:21504
	ds_read_b128 v[228:231], v175 offset:22528
	ds_read_b128 v[232:235], v175 offset:23552
	global_load_lds_dwordx4 v[156:157], off
	s_add_i32 m0, s67, 0x2000
	s_add_u32 s74, s92, 0x80000
	v_lshl_add_u64 v[160:161], s[92:93], 0, v[128:129]
	s_addc_u32 s75, s93, 0
	s_add_i32 s67, s89, s3
	global_load_lds_dwordx4 v[160:161], off
	v_lshl_add_u64 v[164:165], s[74:75], 0, v[132:133]
	s_mov_b32 m0, s67
	v_lshl_add_u64 v[214:215], s[94:95], 0, v[130:131]
	global_load_lds_dwordx4 v[164:165], off
	v_lshl_add_u64 v[164:165], s[74:75], 0, v[128:129]
	s_add_i32 m0, s67, 0x2000
	s_nop 0
	global_load_lds_dwordx4 v[164:165], off
	v_lshl_add_u64 v[164:165], s[94:95], 0, v[134:135]
	s_mov_b32 m0, s15
	s_nop 0
	global_load_lds_dwordx4 v[164:165], off
	s_mov_b32 m0, s34
	s_nop 0
	global_load_lds_dwordx4 v[214:215], off
	s_waitcnt vmcnt(8)
	s_waitcnt lgkmcnt(0)
	s_setprio 1
	s_barrier
; #define PG8_STAGE(bufoff, gbase, voff) do { _Pragma("unroll") for (int _i = 0; _i < 2; ++_i) \
;         __builtin_amdgcn_global_load_lds((const unsigned*)((const char*)(gbase) + (voff)[_i]), (PG8_LAS unsigned*)(lds + (bufoff) + ldsw + _i * 8192), 16, 0, 0); } while (0)
; #define PG8_LDA(dst, b, h) do { _Pragma("unroll") for (int m = 0; m < 4; ++m) _Pragma("unroll") for (int k = 0; k < 2; ++k) dst[m][k] = *(const PG8_LAS bf16x8*)(lds + PG8_SA(b, h) + aoff + m * 2048 + k * 1024); } while (0)
; #define PG8_LDB(dst, b, h) do { _Pragma("unroll") for (int n = 0; n < 2; ++n) _Pragma("unroll") for (int k = 0; k < 2; ++k) dst[n][k] = *(const PG8_LAS bf16x8*)(lds + PG8_SB(b, h) + boff + n * 2048 + k * 1024); } while (0)
; #define PG8_MMA(ai, bj, At, Bt) do { __builtin_amdgcn_s_setprio(1); _Pragma("unroll") for (int m = 0; m < 4; ++m) _Pragma("unroll") for (int n = 0; n < 2; ++n) _Pragma("unroll") for (int k = 0; k < 2; ++k) \
;         acc[ai][bj][m][n] = __builtin_amdgcn_mfma_f32_16x16x32_bf16(Bt[n][k], At[m][k], acc[ai][bj][m][n], 0, 0, 0); __builtin_amdgcn_s_setprio(0); } while (0)
; #define PG8_WAIT_V(n) asm volatile("s_waitcnt vmcnt(" #n ")" ::: "memory")
; #define PG8_WAIT_L(n) asm volatile("s_waitcnt lgkmcnt(" #n ")" ::: "memory")
; #define PG8_BAR __builtin_amdgcn_s_barrier()
; #define PG8_SCHED __builtin_amdgcn_sched_barrier(0)
; template <class Epi, class Sched, bool ALIGN_EPI = false, bool SP2 = false>
; __device__ __forceinline__ void gemm_phase(PG8_LAS unsigned char* lds, const Gemm g, const Sched& S, const Epi& E) {
;     ...
;             PG8_WAIT_V(8); PG8_WAIT_L(0); PG8_BAR; PG8_MMA(1, 0, At, B0); PG8_MMA(1, 1, At, B1); PG8_BAR; PG8_SCHED;
;             PG8_LDB(B0, 1, 0); PG8_LDB(B1, 1, 1); PG8_SCHED; PG8_LDA(At, 1, 0); PG8_STAGE(PG8_SA(0, 1), a2 + hstep, voffA);
;             PG8_WAIT_V(8); PG8_WAIT_L(0); PG8_BAR; PG8_MMA(0, 0, At, B0); PG8_MMA(0, 1, At, B1); PG8_BAR; PG8_SCHED;
	v_mfma_f32_16x16x32_bf16 v[60:63], v[146:149], v[198:201], 0
	v_mfma_f32_16x16x32_bf16 v[56:59], v[168:171], v[198:201], 0
	v_mfma_f32_16x16x32_bf16 v[44:47], v[146:149], v[206:209], 0
	v_mfma_f32_16x16x32_bf16 v[40:43], v[168:171], v[206:209], 0
	v_mfma_f32_16x16x32_bf16 v[28:31], v[146:149], v[218:221], 0
	v_mfma_f32_16x16x32_bf16 v[24:27], v[168:171], v[218:221], 0
	v_mfma_f32_16x16x32_bf16 v[12:15], v[146:149], v[228:231], 0
	v_mfma_f32_16x16x32_bf16 v[8:11], v[168:171], v[228:231], 0
	v_mfma_f32_16x16x32_bf16 v[60:63], v[150:153], v[202:205], v[60:63]
	v_mfma_f32_16x16x32_bf16 v[56:59], v[178:181], v[202:205], v[56:59]
	v_mfma_f32_16x16x32_bf16 v[44:47], v[150:153], v[210:213], v[44:47]
	v_mfma_f32_16x16x32_bf16 v[40:43], v[178:181], v[210:213], v[40:43]
	v_mfma_f32_16x16x32_bf16 v[28:31], v[150:153], v[224:227], v[28:31]
	v_mfma_f32_16x16x32_bf16 v[24:27], v[178:181], v[224:227], v[24:27]
	v_mfma_f32_16x16x32_bf16 v[12:15], v[150:153], v[232:235], v[12:15]
	v_mfma_f32_16x16x32_bf16 v[8:11], v[178:181], v[232:235], v[8:11]
	v_mfma_f32_16x16x32_bf16 v[52:55], v[182:185], v[198:201], 0
	v_mfma_f32_16x16x32_bf16 v[48:51], v[190:193], v[198:201], 0
	v_mfma_f32_16x16x32_bf16 v[36:39], v[182:185], v[206:209], 0
	v_mfma_f32_16x16x32_bf16 v[32:35], v[190:193], v[206:209], 0
	v_mfma_f32_16x16x32_bf16 v[20:23], v[182:185], v[218:221], 0
	v_mfma_f32_16x16x32_bf16 v[16:19], v[190:193], v[218:221], 0
	v_mfma_f32_16x16x32_bf16 v[4:7], v[182:185], v[228:231], 0
	v_mfma_f32_16x16x32_bf16 v[0:3], v[190:193], v[228:231], 0
	v_mfma_f32_16x16x32_bf16 v[52:55], v[186:189], v[202:205], v[52:55]
	v_mfma_f32_16x16x32_bf16 v[48:51], v[194:197], v[202:205], v[48:51]
	v_mfma_f32_16x16x32_bf16 v[36:39], v[186:189], v[210:213], v[36:39]
	v_mfma_f32_16x16x32_bf16 v[32:35], v[194:197], v[210:213], v[32:35]
	v_mfma_f32_16x16x32_bf16 v[20:23], v[186:189], v[224:227], v[20:23]
	v_mfma_f32_16x16x32_bf16 v[16:19], v[194:197], v[224:227], v[16:19]
	v_mfma_f32_16x16x32_bf16 v[4:7], v[186:189], v[232:235], v[4:7]
	v_mfma_f32_16x16x32_bf16 v[0:3], v[194:197], v[232:235], v[0:3]
	s_barrier
	s_setprio 0
	s_add_i32 s67, 0, 0x18000
	v_add_u32_e32 v154, s67, v159
	s_add_i32 s76, 0, 0x1c000
	ds_read_b128 v[146:149], v154
	ds_read_b128 v[150:153], v154 offset:1024
	ds_read_b128 v[168:171], v154 offset:2048
	ds_read_b128 v[178:181], v154 offset:3072
	v_add_u32_e32 v154, s76, v159
	ds_read_b128 v[182:185], v154
	ds_read_b128 v[186:189], v154 offset:1024
	ds_read_b128 v[190:193], v154 offset:2048
	ds_read_b128 v[194:197], v154 offset:3072
	s_add_u32 s74, s94, 0x80000
	s_addc_u32 s75, s95, 0
	s_mov_b32 m0, s35
	v_lshl_add_u64 v[236:237], s[74:75], 0, v[134:135]
	ds_read_b128 v[198:201], v175 offset:32768
	ds_read_b128 v[202:205], v175 offset:33792
	ds_read_b128 v[206:209], v175 offset:34816
	ds_read_b128 v[210:213], v175 offset:35840
	ds_read_b128 v[218:221], v175 offset:36864
	ds_read_b128 v[224:227], v175 offset:37888
	ds_read_b128 v[228:231], v175 offset:38912
	ds_read_b128 v[232:235], v175 offset:39936
	global_load_lds_dwordx4 v[236:237], off
	v_lshl_add_u64 v[236:237], s[74:75], 0, v[130:131]
	s_mov_b32 m0, s63
	s_nop 0
	global_load_lds_dwordx4 v[236:237], off
	s_waitcnt vmcnt(8)
	s_waitcnt lgkmcnt(0)
	s_setprio 1
	s_barrier
	v_mfma_f32_16x16x32_bf16 v[124:127], v[146:149], v[198:201], v[124:127]
	v_mfma_f32_16x16x32_bf16 v[120:123], v[168:171], v[198:201], v[120:123]
	v_mfma_f32_16x16x32_bf16 v[108:111], v[146:149], v[206:209], v[108:111]
	v_mfma_f32_16x16x32_bf16 v[104:107], v[168:171], v[206:209], v[104:107]
	v_mfma_f32_16x16x32_bf16 v[92:95], v[146:149], v[218:221], v[92:95]
	v_mfma_f32_16x16x32_bf16 v[88:91], v[168:171], v[218:221], v[88:91]
	v_mfma_f32_16x16x32_bf16 v[76:79], v[146:149], v[228:231], v[76:79]
	v_mfma_f32_16x16x32_bf16 v[72:75], v[168:171], v[228:231], v[72:75]
	v_mfma_f32_16x16x32_bf16 v[124:127], v[150:153], v[202:205], v[124:127]
	v_mfma_f32_16x16x32_bf16 v[120:123], v[178:181], v[202:205], v[120:123]
	v_mfma_f32_16x16x32_bf16 v[108:111], v[150:153], v[210:213], v[108:111]
	v_mfma_f32_16x16x32_bf16 v[104:107], v[178:181], v[210:213], v[104:107]
	v_mfma_f32_16x16x32_bf16 v[92:95], v[150:153], v[224:227], v[92:95]
	v_mfma_f32_16x16x32_bf16 v[88:91], v[178:181], v[224:227], v[88:91]
	v_mfma_f32_16x16x32_bf16 v[76:79], v[150:153], v[232:235], v[76:79]
	v_mfma_f32_16x16x32_bf16 v[72:75], v[178:181], v[232:235], v[72:75]
	v_mfma_f32_16x16x32_bf16 v[116:119], v[182:185], v[198:201], v[116:119]
	v_mfma_f32_16x16x32_bf16 v[112:115], v[190:193], v[198:201], v[112:115]
	v_mfma_f32_16x16x32_bf16 v[100:103], v[182:185], v[206:209], v[100:103]
	v_mfma_f32_16x16x32_bf16 v[96:99], v[190:193], v[206:209], v[96:99]
	v_mfma_f32_16x16x32_bf16 v[84:87], v[182:185], v[218:221], v[84:87]
	v_mfma_f32_16x16x32_bf16 v[80:83], v[190:193], v[218:221], v[80:83]
	v_mfma_f32_16x16x32_bf16 v[68:71], v[182:185], v[228:231], v[68:71]
	v_mfma_f32_16x16x32_bf16 v[64:67], v[190:193], v[228:231], v[64:67]
	v_mfma_f32_16x16x32_bf16 v[116:119], v[186:189], v[202:205], v[116:119]
	v_mfma_f32_16x16x32_bf16 v[112:115], v[194:197], v[202:205], v[112:115]
	v_mfma_f32_16x16x32_bf16 v[100:103], v[186:189], v[210:213], v[100:103]
	v_mfma_f32_16x16x32_bf16 v[96:99], v[194:197], v[210:213], v[96:99]
	v_mfma_f32_16x16x32_bf16 v[84:87], v[186:189], v[224:227], v[84:87]
	v_mfma_f32_16x16x32_bf16 v[80:83], v[194:197], v[224:227], v[80:83]
	v_mfma_f32_16x16x32_bf16 v[68:71], v[186:189], v[232:235], v[68:71]
	v_mfma_f32_16x16x32_bf16 v[64:67], v[194:197], v[232:235], v[64:67]
	s_barrier
; #define PG8_STAGE(bufoff, gbase, voff) do { _Pragma("unroll") for (int _i = 0; _i < 2; ++_i) \
;         __builtin_amdgcn_global_load_lds((const unsigned*)((const char*)(gbase) + (voff)[_i]), (PG8_LAS unsigned*)(lds + (bufoff) + ldsw + _i * 8192), 16, 0, 0); } while (0)
; #define PG8_LDA(dst, b, h) do { _Pragma("unroll") for (int m = 0; m < 4; ++m) _Pragma("unroll") for (int k = 0; k < 2; ++k) dst[m][k] = *(const PG8_LAS bf16x8*)(lds + PG8_SA(b, h) + aoff + m * 2048 + k * 1024); } while (0)
; #define PG8_MMA(ai, bj, At, Bt) do { __builtin_amdgcn_s_setprio(1); _Pragma("unroll") for (int m = 0; m < 4; ++m) _Pragma("unroll") for (int n = 0; n < 2; ++n) _Pragma("unroll") for (int k = 0; k < 2; ++k) \
;         acc[ai][bj][m][n] = __builtin_amdgcn_mfma_f32_16x16x32_bf16(Bt[n][k], At[m][k], acc[ai][bj][m][n], 0, 0, 0); __builtin_amdgcn_s_setprio(0); } while (0)
; #define PG8_WAIT_V(n) asm volatile("s_waitcnt vmcnt(" #n ")" ::: "memory")
; #define PG8_WAIT_L(n) asm volatile("s_waitcnt lgkmcnt(" #n ")" ::: "memory")
; #define PG8_BAR __builtin_amdgcn_s_barrier()
; #define PG8_SCHED __builtin_amdgcn_sched_barrier(0)
; template <class Epi, class Sched, bool ALIGN_EPI = false, bool SP2 = false>
; __device__ __forceinline__ void gemm_phase(PG8_LAS unsigned char* lds, const Gemm g, const Sched& S, const Epi& E) {
;     ...
;         for (int t = 0; t < nt; t += 2) {
;             const bool last = (t == nt - 2);
;             const char* a1 = cA + (size_t)(t + 1) * kstep;
;             const char* a2 = last ? nA : cA + (size_t)(t + 2) * kstep; const char* b2 = last ? nB : cB + (size_t)(t + 2) * kstep;
;     ...
;             PG8_LDA(At, 1, 1); PG8_STAGE(PG8_SB(1, 0), b3, voffB); PG8_STAGE(PG8_SB(1, 1), b3 + hstep, voffB); PG8_STAGE(PG8_SA(1, 0), a3, voffA);
;             PG8_WAIT_V(8); PG8_WAIT_L(0); PG8_BAR; PG8_MMA(1, 0, At, B0); PG8_MMA(1, 1, At, B1); PG8_BAR; PG8_SCHED;
	s_setprio 0
	s_add_i32 s67, s67, s3
	v_lshl_add_u64 v[156:157], v[156:157], 0, s[8:9]
	s_mov_b32 m0, s67
	ds_read_b128 v[198:201], v175 offset:49152
	ds_read_b128 v[202:205], v175 offset:50176
	ds_read_b128 v[206:209], v175 offset:51200
	ds_read_b128 v[210:213], v175 offset:52224
	ds_read_b128 v[218:221], v175 offset:53248
	ds_read_b128 v[224:227], v175 offset:54272
	ds_read_b128 v[228:231], v175 offset:55296
	ds_read_b128 v[232:235], v175 offset:56320
	global_load_lds_dwordx4 v[156:157], off
	s_add_i32 m0, s67, 0x2000
	s_add_u32 s74, s92, 0x80080
	v_lshl_add_u64 v[156:157], v[160:161], 0, s[8:9]
	s_addc_u32 s75, s93, 0
	s_add_i32 s67, s76, s3
	global_load_lds_dwordx4 v[156:157], off
	v_lshl_add_u64 v[156:157], s[74:75], 0, v[132:133]
	s_mov_b32 m0, s67
	s_nop 0
	global_load_lds_dwordx4 v[156:157], off
	v_lshl_add_u64 v[156:157], s[74:75], 0, v[128:129]
	s_add_i32 m0, s67, 0x2000
	s_nop 0
	global_load_lds_dwordx4 v[156:157], off
	v_lshl_add_u64 v[156:157], v[164:165], 0, s[8:9]
	s_mov_b32 m0, s69
	s_nop 0
	global_load_lds_dwordx4 v[156:157], off
	v_lshl_add_u64 v[156:157], v[214:215], 0, s[8:9]
	s_mov_b32 m0, s80
	s_nop 0
	global_load_lds_dwordx4 v[156:157], off
	s_waitcnt vmcnt(8)
	s_waitcnt lgkmcnt(0)
	s_setprio 1
	s_barrier
	v_mfma_f32_16x16x32_bf16 v[60:63], v[146:149], v[198:201], v[60:63]
	v_mfma_f32_16x16x32_bf16 v[56:59], v[168:171], v[198:201], v[56:59]
	v_mfma_f32_16x16x32_bf16 v[44:47], v[146:149], v[206:209], v[44:47]
	v_mfma_f32_16x16x32_bf16 v[40:43], v[168:171], v[206:209], v[40:43]
	v_mfma_f32_16x16x32_bf16 v[28:31], v[146:149], v[218:221], v[28:31]
	v_mfma_f32_16x16x32_bf16 v[24:27], v[168:171], v[218:221], v[24:27]
	v_mfma_f32_16x16x32_bf16 v[12:15], v[146:149], v[228:231], v[12:15]
	v_mfma_f32_16x16x32_bf16 v[8:11], v[168:171], v[228:231], v[8:11]
	v_mfma_f32_16x16x32_bf16 v[60:63], v[150:153], v[202:205], v[60:63]
	v_mfma_f32_16x16x32_bf16 v[56:59], v[178:181], v[202:205], v[56:59]
	v_mfma_f32_16x16x32_bf16 v[44:47], v[150:153], v[210:213], v[44:47]
	v_mfma_f32_16x16x32_bf16 v[40:43], v[178:181], v[210:213], v[40:43]
	v_mfma_f32_16x16x32_bf16 v[28:31], v[150:153], v[224:227], v[28:31]
	v_mfma_f32_16x16x32_bf16 v[24:27], v[178:181], v[224:227], v[24:27]
	v_mfma_f32_16x16x32_bf16 v[12:15], v[150:153], v[232:235], v[12:15]
	v_mfma_f32_16x16x32_bf16 v[8:11], v[178:181], v[232:235], v[8:11]
	v_mfma_f32_16x16x32_bf16 v[52:55], v[182:185], v[198:201], v[52:55]
	v_mfma_f32_16x16x32_bf16 v[48:51], v[190:193], v[198:201], v[48:51]
	v_mfma_f32_16x16x32_bf16 v[36:39], v[182:185], v[206:209], v[36:39]
	v_mfma_f32_16x16x32_bf16 v[32:35], v[190:193], v[206:209], v[32:35]
	v_mfma_f32_16x16x32_bf16 v[20:23], v[182:185], v[218:221], v[20:23]
	v_mfma_f32_16x16x32_bf16 v[16:19], v[190:193], v[218:221], v[16:19]
	v_mfma_f32_16x16x32_bf16 v[4:7], v[182:185], v[228:231], v[4:7]
	v_mfma_f32_16x16x32_bf16 v[0:3], v[190:193], v[228:231], v[0:3]
	v_mfma_f32_16x16x32_bf16 v[52:55], v[186:189], v[202:205], v[52:55]
	v_mfma_f32_16x16x32_bf16 v[48:51], v[194:197], v[202:205], v[48:51]
	v_mfma_f32_16x16x32_bf16 v[36:39], v[186:189], v[210:213], v[36:39]
	v_mfma_f32_16x16x32_bf16 v[32:35], v[194:197], v[210:213], v[32:35]
	v_mfma_f32_16x16x32_bf16 v[20:23], v[186:189], v[224:227], v[20:23]
	v_mfma_f32_16x16x32_bf16 v[16:19], v[194:197], v[224:227], v[16:19]
	v_mfma_f32_16x16x32_bf16 v[4:7], v[186:189], v[232:235], v[4:7]
	v_mfma_f32_16x16x32_bf16 v[0:3], v[194:197], v[232:235], v[0:3]
	s_barrier
	s_setprio 0
	s_add_i32 s66, s66, 2
	s_add_u32 s90, s90, 0x100
	s_addc_u32 s91, s91, 0
	s_add_u32 vcc_lo, vcc_lo, 0x100
	s_addc_u32 vcc_hi, vcc_hi, 0
	s_cmp_gt_u32 s66, 29

; #define PG8_STAGE(bufoff, gbase, voff) do { _Pragma("unroll") for (int _i = 0; _i < 2; ++_i) \
;         __builtin_amdgcn_global_load_lds((const unsigned*)((const char*)(gbase) + (voff)[_i]), (PG8_LAS unsigned*)(lds + (bufoff) + ldsw + _i * 8192), 16, 0, 0); } while (0)
; #define PG8_LDA(dst, b, h) do { _Pragma("unroll") for (int m = 0; m < 4; ++m) _Pragma("unroll") for (int k = 0; k < 2; ++k) dst[m][k] = *(const PG8_LAS bf16x8*)(lds + PG8_SA(b, h) + aoff + m * 2048 + k * 1024); } while (0)
; #define PG8_LDB(dst, b, h) do { _Pragma("unroll") for (int n = 0; n < 2; ++n) _Pragma("unroll") for (int k = 0; k < 2; ++k) dst[n][k] = *(const PG8_LAS bf16x8*)(lds + PG8_SB(b, h) + boff + n * 2048 + k * 1024); } while (0)
; #define PG8_MMA(ai, bj, At, Bt) do { __builtin_amdgcn_s_setprio(1); _Pragma("unroll") for (int m = 0; m < 4; ++m) _Pragma("unroll") for (int n = 0; n < 2; ++n) _Pragma("unroll") for (int k = 0; k < 2; ++k) \
;         acc[ai][bj][m][n] = __builtin_amdgcn_mfma_f32_16x16x32_bf16(Bt[n][k], At[m][k], acc[ai][bj][m][n], 0, 0, 0); __builtin_amdgcn_s_setprio(0); } while (0)
; #define PG8_WAIT_V(n) asm volatile("s_waitcnt vmcnt(" #n ")" ::: "memory")
; #define PG8_WAIT_L(n) asm volatile("s_waitcnt lgkmcnt(" #n ")" ::: "memory")
; #define PG8_BAR __builtin_amdgcn_s_barrier()
; #define PG8_SCHED __builtin_amdgcn_sched_barrier(0)
; template <class Epi, class Sched, bool ALIGN_EPI = false, bool SP2 = false>
; __device__ __forceinline__ void gemm_phase(PG8_LAS unsigned char* lds, const Gemm g, const Sched& S, const Epi& E) {
;     ...
;             const char* a1 = cA + (size_t)(t + 1) * kstep;
;             const char* a2 = last ? nA : cA + (size_t)(t + 2) * kstep; const char* b2 = last ? nB : cB + (size_t)(t + 2) * kstep;
;             const char* a3 = a2 + kstep; const char* b3 = b2 + kstep;
;             if (last && has_next) S.a_ready(nxt);
;             if constexpr (SP2) {
;             PG8_LDB(B0, 0, 0); PG8_LDB(B1, 0, 1); PG8_SCHED; PG8_LDA(At, 0, 0); PG8_STAGE(PG8_SA(1, 1), a1 + hstep, voffA);
;             PG8_WAIT_V(8); PG8_WAIT_L(0); PG8_BAR; PG8_MMA(0, 0, At, B0); PG8_MMA(0, 1, At, B1); PG8_BAR; PG8_SCHED;
;             PG8_LDA(At, 0, 1); PG8_STAGE(PG8_SB(0, 0), b2, voffB); PG8_STAGE(PG8_SB(0, 1), b2 + hstep, voffB); PG8_STAGE(PG8_SA(0, 0), a2, voffA);
.LBB0_247:
	s_add_u32 s22, s82, 0x100
	s_addc_u32 vcc_lo, s83, 0
	s_mov_b32 s66, -2
	s_waitcnt lgkmcnt(0)
	ds_read_b128 v[128:131], v220
	ds_read_b128 v[132:135], v220 offset:1024
	ds_read_b128 v[136:139], v220 offset:2048
	ds_read_b128 v[140:143], v220 offset:3072
	ds_read_b128 v[144:147], v221
	ds_read_b128 v[148:151], v221 offset:1024
	ds_read_b128 v[152:155], v221 offset:2048
	ds_read_b128 v[156:159], v221 offset:3072
	s_add_u32 s10, s92, 0x100
	s_addc_u32 s11, s93, 0
	s_cmpk_eq_i32 s66, 0x54
	s_cselect_b32 s95, s89, s11
	s_cselect_b32 s94, s88, s10
	s_cselect_b32 s83, s91, vcc_lo
	s_cselect_b32 s82, s90, s22
	v_lshl_add_u64 v[204:205], s[92:93], 0, v[192:193]
	s_add_i32 m0, s15, 0xc000
	ds_read_b128 v[160:163], v223
	ds_read_b128 v[164:167], v223 offset:1024
	ds_read_b128 v[168:171], v223 offset:2048
	ds_read_b128 v[172:175], v223 offset:3072
	ds_read_b128 v[176:179], v223 offset:4096
	ds_read_b128 v[180:183], v223 offset:5120
	ds_read_b128 v[184:187], v223 offset:6144
	ds_read_b128 v[200:203], v223 offset:7168
	global_load_lds_dwordx4 v[204:205], off
	v_lshl_add_u64 v[204:205], s[92:93], 0, v[194:195]
	s_add_i32 m0, s15, 0xe000
	s_nop 0
	global_load_lds_dwordx4 v[204:205], off
	s_waitcnt vmcnt(8)
	s_waitcnt lgkmcnt(0)
	s_setprio 1
	s_barrier
	v_mfma_f32_16x16x32_bf16 v[124:127], v[128:131], v[160:163], 0
	v_mfma_f32_16x16x32_bf16 v[120:123], v[136:139], v[160:163], 0
	v_mfma_f32_16x16x32_bf16 v[108:111], v[128:131], v[168:171], 0
	v_mfma_f32_16x16x32_bf16 v[104:107], v[136:139], v[168:171], 0
	v_mfma_f32_16x16x32_bf16 v[92:95], v[128:131], v[176:179], 0
	v_mfma_f32_16x16x32_bf16 v[88:91], v[136:139], v[176:179], 0
	v_mfma_f32_16x16x32_bf16 v[76:79], v[128:131], v[184:187], 0
	v_mfma_f32_16x16x32_bf16 v[72:75], v[136:139], v[184:187], 0
	v_mfma_f32_16x16x32_bf16 v[124:127], v[132:135], v[164:167], v[124:127]
	v_mfma_f32_16x16x32_bf16 v[120:123], v[140:143], v[164:167], v[120:123]
	v_mfma_f32_16x16x32_bf16 v[108:111], v[132:135], v[172:175], v[108:111]
	v_mfma_f32_16x16x32_bf16 v[104:107], v[140:143], v[172:175], v[104:107]
	v_mfma_f32_16x16x32_bf16 v[92:95], v[132:135], v[180:183], v[92:95]
	v_mfma_f32_16x16x32_bf16 v[88:91], v[140:143], v[180:183], v[88:91]
	v_mfma_f32_16x16x32_bf16 v[76:79], v[132:135], v[200:203], v[76:79]
	v_mfma_f32_16x16x32_bf16 v[72:75], v[140:143], v[200:203], v[72:75]
	v_mfma_f32_16x16x32_bf16 v[116:119], v[144:147], v[160:163], 0
	v_mfma_f32_16x16x32_bf16 v[112:115], v[152:155], v[160:163], 0
	v_mfma_f32_16x16x32_bf16 v[100:103], v[144:147], v[168:171], 0
	v_mfma_f32_16x16x32_bf16 v[96:99], v[152:155], v[168:171], 0
	v_mfma_f32_16x16x32_bf16 v[84:87], v[144:147], v[176:179], 0
	v_mfma_f32_16x16x32_bf16 v[80:83], v[152:155], v[176:179], 0
	v_mfma_f32_16x16x32_bf16 v[68:71], v[144:147], v[184:187], 0
	v_mfma_f32_16x16x32_bf16 v[64:67], v[152:155], v[184:187], 0
	v_mfma_f32_16x16x32_bf16 v[116:119], v[148:151], v[164:167], v[116:119]
	v_mfma_f32_16x16x32_bf16 v[112:115], v[156:159], v[164:167], v[112:115]
	v_mfma_f32_16x16x32_bf16 v[100:103], v[148:151], v[172:175], v[100:103]
	v_mfma_f32_16x16x32_bf16 v[96:99], v[156:159], v[172:175], v[96:99]
	v_mfma_f32_16x16x32_bf16 v[84:87], v[148:151], v[180:183], v[84:87]
	v_mfma_f32_16x16x32_bf16 v[80:83], v[156:159], v[180:183], v[80:83]
	v_mfma_f32_16x16x32_bf16 v[68:71], v[148:151], v[200:203], v[68:71]
	v_mfma_f32_16x16x32_bf16 v[64:67], v[156:159], v[200:203], v[64:67]
	s_barrier
	s_setprio 0
	s_add_i32 s67, s73, s14
	v_lshl_add_u64 v[204:205], s[82:83], 0, v[188:189]
	s_mov_b32 m0, s67
	ds_read_b128 v[160:163], v223 offset:16384
	ds_read_b128 v[164:167], v223 offset:17408
	ds_read_b128 v[168:171], v223 offset:18432
	ds_read_b128 v[172:175], v223 offset:19456
	ds_read_b128 v[176:179], v223 offset:20480
	ds_read_b128 v[180:183], v223 offset:21504
	ds_read_b128 v[184:187], v223 offset:22528
	ds_read_b128 v[200:203], v223 offset:23552
	global_load_lds_dwordx4 v[204:205], off
	s_add_i32 m0, s67, 0x2000
	s_add_u32 s74, s82, 0x160000
	v_lshl_add_u64 v[206:207], s[82:83], 0, v[190:191]
	s_addc_u32 s75, s83, 0
	s_add_i32 s67, s80, s14
	global_load_lds_dwordx4 v[206:207], off
	v_lshl_add_u64 v[208:209], s[74:75], 0, v[188:189]
	s_mov_b32 m0, s67
	v_lshl_add_u64 v[210:211], s[94:95], 0, v[190:191]
	global_load_lds_dwordx4 v[208:209], off
	v_lshl_add_u64 v[208:209], s[74:75], 0, v[190:191]
	s_add_i32 m0, s67, 0x2000
	s_nop 0
	global_load_lds_dwordx4 v[208:209], off
	v_lshl_add_u64 v[208:209], s[94:95], 0, v[188:189]
	s_mov_b32 m0, s15
	s_nop 0
	global_load_lds_dwordx4 v[208:209], off
	s_mov_b32 m0, s34
	s_nop 0
	global_load_lds_dwordx4 v[210:211], off
	s_waitcnt vmcnt(8)
	s_waitcnt lgkmcnt(0)
	s_setprio 1
	s_barrier
; #define PG8_STAGE(bufoff, gbase, voff) do { _Pragma("unroll") for (int _i = 0; _i < 2; ++_i) \
;         __builtin_amdgcn_global_load_lds((const unsigned*)((const char*)(gbase) + (voff)[_i]), (PG8_LAS unsigned*)(lds + (bufoff) + ldsw + _i * 8192), 16, 0, 0); } while (0)
; #define PG8_LDA(dst, b, h) do { _Pragma("unroll") for (int m = 0; m < 4; ++m) _Pragma("unroll") for (int k = 0; k < 2; ++k) dst[m][k] = *(const PG8_LAS bf16x8*)(lds + PG8_SA(b, h) + aoff + m * 2048 + k * 1024); } while (0)
; #define PG8_LDB(dst, b, h) do { _Pragma("unroll") for (int n = 0; n < 2; ++n) _Pragma("unroll") for (int k = 0; k < 2; ++k) dst[n][k] = *(const PG8_LAS bf16x8*)(lds + PG8_SB(b, h) + boff + n * 2048 + k * 1024); } while (0)
; #define PG8_MMA(ai, bj, At, Bt) do { __builtin_amdgcn_s_setprio(1); _Pragma("unroll") for (int m = 0; m < 4; ++m) _Pragma("unroll") for (int n = 0; n < 2; ++n) _Pragma("unroll") for (int k = 0; k < 2; ++k) \
;         acc[ai][bj][m][n] = __builtin_amdgcn_mfma_f32_16x16x32_bf16(Bt[n][k], At[m][k], acc[ai][bj][m][n], 0, 0, 0); __builtin_amdgcn_s_setprio(0); } while (0)
; #define PG8_WAIT_V(n) asm volatile("s_waitcnt vmcnt(" #n ")" ::: "memory")
; #define PG8_WAIT_L(n) asm volatile("s_waitcnt lgkmcnt(" #n ")" ::: "memory")
; #define PG8_BAR __builtin_amdgcn_s_barrier()
; #define PG8_SCHED __builtin_amdgcn_sched_barrier(0)
; template <class Epi, class Sched, bool ALIGN_EPI = false, bool SP2 = false>
; __device__ __forceinline__ void gemm_phase(PG8_LAS unsigned char* lds, const Gemm g, const Sched& S, const Epi& E) {
;     ...
;             PG8_WAIT_V(8); PG8_WAIT_L(0); PG8_BAR; PG8_MMA(1, 0, At, B0); PG8_MMA(1, 1, At, B1); PG8_BAR; PG8_SCHED;
;             PG8_LDB(B0, 1, 0); PG8_LDB(B1, 1, 1); PG8_SCHED; PG8_LDA(At, 1, 0); PG8_STAGE(PG8_SA(0, 1), a2 + hstep, voffA);
;             PG8_WAIT_V(8); PG8_WAIT_L(0); PG8_BAR; PG8_MMA(0, 0, At, B0); PG8_MMA(0, 1, At, B1); PG8_BAR; PG8_SCHED;
	v_mfma_f32_16x16x32_bf16 v[60:63], v[128:131], v[160:163], 0
	v_mfma_f32_16x16x32_bf16 v[56:59], v[136:139], v[160:163], 0
	v_mfma_f32_16x16x32_bf16 v[44:47], v[128:131], v[168:171], 0
	v_mfma_f32_16x16x32_bf16 v[40:43], v[136:139], v[168:171], 0
	v_mfma_f32_16x16x32_bf16 v[28:31], v[128:131], v[176:179], 0
	v_mfma_f32_16x16x32_bf16 v[24:27], v[136:139], v[176:179], 0
	v_mfma_f32_16x16x32_bf16 v[12:15], v[128:131], v[184:187], 0
	v_mfma_f32_16x16x32_bf16 v[8:11], v[136:139], v[184:187], 0
	v_mfma_f32_16x16x32_bf16 v[60:63], v[132:135], v[164:167], v[60:63]
	v_mfma_f32_16x16x32_bf16 v[56:59], v[140:143], v[164:167], v[56:59]
	v_mfma_f32_16x16x32_bf16 v[44:47], v[132:135], v[172:175], v[44:47]
	v_mfma_f32_16x16x32_bf16 v[40:43], v[140:143], v[172:175], v[40:43]
	v_mfma_f32_16x16x32_bf16 v[28:31], v[132:135], v[180:183], v[28:31]
	v_mfma_f32_16x16x32_bf16 v[24:27], v[140:143], v[180:183], v[24:27]
	v_mfma_f32_16x16x32_bf16 v[12:15], v[132:135], v[200:203], v[12:15]
	v_mfma_f32_16x16x32_bf16 v[8:11], v[140:143], v[200:203], v[8:11]
	v_mfma_f32_16x16x32_bf16 v[52:55], v[144:147], v[160:163], 0
	v_mfma_f32_16x16x32_bf16 v[48:51], v[152:155], v[160:163], 0
	v_mfma_f32_16x16x32_bf16 v[36:39], v[144:147], v[168:171], 0
	v_mfma_f32_16x16x32_bf16 v[32:35], v[152:155], v[168:171], 0
	v_mfma_f32_16x16x32_bf16 v[20:23], v[144:147], v[176:179], 0
	v_mfma_f32_16x16x32_bf16 v[16:19], v[152:155], v[176:179], 0
	v_mfma_f32_16x16x32_bf16 v[4:7], v[144:147], v[184:187], 0
	v_mfma_f32_16x16x32_bf16 v[0:3], v[152:155], v[184:187], 0
	v_mfma_f32_16x16x32_bf16 v[52:55], v[148:151], v[164:167], v[52:55]
	v_mfma_f32_16x16x32_bf16 v[48:51], v[156:159], v[164:167], v[48:51]
	v_mfma_f32_16x16x32_bf16 v[36:39], v[148:151], v[172:175], v[36:39]
	v_mfma_f32_16x16x32_bf16 v[32:35], v[156:159], v[172:175], v[32:35]
	v_mfma_f32_16x16x32_bf16 v[20:23], v[148:151], v[180:183], v[20:23]
	v_mfma_f32_16x16x32_bf16 v[16:19], v[156:159], v[180:183], v[16:19]
	v_mfma_f32_16x16x32_bf16 v[4:7], v[148:151], v[200:203], v[4:7]
	v_mfma_f32_16x16x32_bf16 v[0:3], v[156:159], v[200:203], v[0:3]
	s_barrier
	s_setprio 0
	s_add_i32 s67, 0, 0x18000
	s_add_i32 s76, 0, 0x1c000
	v_add_u32_e32 v140, s67, v218
	v_add_u32_e32 v156, s76, v218
	ds_read_b128 v[128:131], v140
	ds_read_b128 v[132:135], v140 offset:1024
	ds_read_b128 v[136:139], v140 offset:2048
	ds_read_b128 v[140:143], v140 offset:3072
	ds_read_b128 v[144:147], v156
	ds_read_b128 v[148:151], v156 offset:1024
	ds_read_b128 v[152:155], v156 offset:2048
	ds_read_b128 v[156:159], v156 offset:3072
	s_add_u32 s74, s94, 0x160000
	s_addc_u32 s75, s95, 0
	s_mov_b32 m0, s35
	v_lshl_add_u64 v[212:213], s[74:75], 0, v[188:189]
	ds_read_b128 v[160:163], v223 offset:32768
	ds_read_b128 v[164:167], v223 offset:33792
	ds_read_b128 v[168:171], v223 offset:34816
	ds_read_b128 v[172:175], v223 offset:35840
	ds_read_b128 v[176:179], v223 offset:36864
	ds_read_b128 v[180:183], v223 offset:37888
	ds_read_b128 v[184:187], v223 offset:38912
	ds_read_b128 v[200:203], v223 offset:39936
	global_load_lds_dwordx4 v[212:213], off
	v_lshl_add_u64 v[212:213], s[74:75], 0, v[190:191]
	s_mov_b32 m0, s68
	s_nop 0
	global_load_lds_dwordx4 v[212:213], off
	s_waitcnt vmcnt(8)
	s_waitcnt lgkmcnt(0)
	s_setprio 1
	s_barrier
	v_mfma_f32_16x16x32_bf16 v[124:127], v[128:131], v[160:163], v[124:127]
	v_mfma_f32_16x16x32_bf16 v[120:123], v[136:139], v[160:163], v[120:123]
	v_mfma_f32_16x16x32_bf16 v[108:111], v[128:131], v[168:171], v[108:111]
	v_mfma_f32_16x16x32_bf16 v[104:107], v[136:139], v[168:171], v[104:107]
	v_mfma_f32_16x16x32_bf16 v[92:95], v[128:131], v[176:179], v[92:95]
	v_mfma_f32_16x16x32_bf16 v[88:91], v[136:139], v[176:179], v[88:91]
	v_mfma_f32_16x16x32_bf16 v[76:79], v[128:131], v[184:187], v[76:79]
	v_mfma_f32_16x16x32_bf16 v[72:75], v[136:139], v[184:187], v[72:75]
	v_mfma_f32_16x16x32_bf16 v[124:127], v[132:135], v[164:167], v[124:127]
	v_mfma_f32_16x16x32_bf16 v[120:123], v[140:143], v[164:167], v[120:123]
	v_mfma_f32_16x16x32_bf16 v[108:111], v[132:135], v[172:175], v[108:111]
	v_mfma_f32_16x16x32_bf16 v[104:107], v[140:143], v[172:175], v[104:107]
	v_mfma_f32_16x16x32_bf16 v[92:95], v[132:135], v[180:183], v[92:95]
	v_mfma_f32_16x16x32_bf16 v[88:91], v[140:143], v[180:183], v[88:91]
	v_mfma_f32_16x16x32_bf16 v[76:79], v[132:135], v[200:203], v[76:79]
	v_mfma_f32_16x16x32_bf16 v[72:75], v[140:143], v[200:203], v[72:75]
	v_mfma_f32_16x16x32_bf16 v[116:119], v[144:147], v[160:163], v[116:119]
	v_mfma_f32_16x16x32_bf16 v[112:115], v[152:155], v[160:163], v[112:115]
	v_mfma_f32_16x16x32_bf16 v[100:103], v[144:147], v[168:171], v[100:103]
	v_mfma_f32_16x16x32_bf16 v[96:99], v[152:155], v[168:171], v[96:99]
	v_mfma_f32_16x16x32_bf16 v[84:87], v[144:147], v[176:179], v[84:87]
	v_mfma_f32_16x16x32_bf16 v[80:83], v[152:155], v[176:179], v[80:83]
	v_mfma_f32_16x16x32_bf16 v[68:71], v[144:147], v[184:187], v[68:71]
	v_mfma_f32_16x16x32_bf16 v[64:67], v[152:155], v[184:187], v[64:67]
	v_mfma_f32_16x16x32_bf16 v[116:119], v[148:151], v[164:167], v[116:119]
	v_mfma_f32_16x16x32_bf16 v[112:115], v[156:159], v[164:167], v[112:115]
	v_mfma_f32_16x16x32_bf16 v[100:103], v[148:151], v[172:175], v[100:103]
	v_mfma_f32_16x16x32_bf16 v[96:99], v[156:159], v[172:175], v[96:99]
	v_mfma_f32_16x16x32_bf16 v[84:87], v[148:151], v[180:183], v[84:87]
	v_mfma_f32_16x16x32_bf16 v[80:83], v[156:159], v[180:183], v[80:83]
	v_mfma_f32_16x16x32_bf16 v[68:71], v[148:151], v[200:203], v[68:71]
	v_mfma_f32_16x16x32_bf16 v[64:67], v[156:159], v[200:203], v[64:67]
	s_barrier
; #define PG8_STAGE(bufoff, gbase, voff) do { _Pragma("unroll") for (int _i = 0; _i < 2; ++_i) \
;         __builtin_amdgcn_global_load_lds((const unsigned*)((const char*)(gbase) + (voff)[_i]), (PG8_LAS unsigned*)(lds + (bufoff) + ldsw + _i * 8192), 16, 0, 0); } while (0)
; #define PG8_LDA(dst, b, h) do { _Pragma("unroll") for (int m = 0; m < 4; ++m) _Pragma("unroll") for (int k = 0; k < 2; ++k) dst[m][k] = *(const PG8_LAS bf16x8*)(lds + PG8_SA(b, h) + aoff + m * 2048 + k * 1024); } while (0)
; #define PG8_MMA(ai, bj, At, Bt) do { __builtin_amdgcn_s_setprio(1); _Pragma("unroll") for (int m = 0; m < 4; ++m) _Pragma("unroll") for (int n = 0; n < 2; ++n) _Pragma("unroll") for (int k = 0; k < 2; ++k) \
;         acc[ai][bj][m][n] = __builtin_amdgcn_mfma_f32_16x16x32_bf16(Bt[n][k], At[m][k], acc[ai][bj][m][n], 0, 0, 0); __builtin_amdgcn_s_setprio(0); } while (0)
; #define PG8_WAIT_V(n) asm volatile("s_waitcnt vmcnt(" #n ")" ::: "memory")
; #define PG8_WAIT_L(n) asm volatile("s_waitcnt lgkmcnt(" #n ")" ::: "memory")
; #define PG8_BAR __builtin_amdgcn_s_barrier()
; #define PG8_SCHED __builtin_amdgcn_sched_barrier(0)
; template <class Epi, class Sched, bool ALIGN_EPI = false, bool SP2 = false>
; __device__ __forceinline__ void gemm_phase(PG8_LAS unsigned char* lds, const Gemm g, const Sched& S, const Epi& E) {
;     ...
;         for (int t = 0; t < nt; t += 2) {
;             const bool last = (t == nt - 2);
;             const char* a1 = cA + (size_t)(t + 1) * kstep;
;             const char* a2 = last ? nA : cA + (size_t)(t + 2) * kstep; const char* b2 = last ? nB : cB + (size_t)(t + 2) * kstep;
;     ...
;             PG8_LDA(At, 1, 1); PG8_STAGE(PG8_SB(1, 0), b3, voffB); PG8_STAGE(PG8_SB(1, 1), b3 + hstep, voffB); PG8_STAGE(PG8_SA(1, 0), a3, voffA);
;             PG8_WAIT_V(8); PG8_WAIT_L(0); PG8_BAR; PG8_MMA(1, 0, At, B0); PG8_MMA(1, 1, At, B1); PG8_BAR; PG8_SCHED;
	s_setprio 0
	s_add_i32 s67, s67, s14
	v_lshl_add_u64 v[204:205], v[204:205], 0, s[46:47]
	s_mov_b32 m0, s67
	ds_read_b128 v[160:163], v223 offset:49152
	ds_read_b128 v[164:167], v223 offset:50176
	ds_read_b128 v[168:171], v223 offset:51200
	ds_read_b128 v[172:175], v223 offset:52224
	ds_read_b128 v[176:179], v223 offset:53248
	ds_read_b128 v[180:183], v223 offset:54272
	ds_read_b128 v[184:187], v223 offset:55296
	ds_read_b128 v[200:203], v223 offset:56320
	global_load_lds_dwordx4 v[204:205], off
	s_add_i32 m0, s67, 0x2000
	s_add_u32 s74, s82, 0x160080
	v_lshl_add_u64 v[204:205], v[206:207], 0, s[46:47]
	s_addc_u32 s75, s83, 0
	s_add_i32 s67, s76, s14
	global_load_lds_dwordx4 v[204:205], off
	v_lshl_add_u64 v[204:205], s[74:75], 0, v[188:189]
	s_mov_b32 m0, s67
	s_nop 0
	global_load_lds_dwordx4 v[204:205], off
	v_lshl_add_u64 v[204:205], s[74:75], 0, v[190:191]
	s_add_i32 m0, s67, 0x2000
	s_nop 0
	global_load_lds_dwordx4 v[204:205], off
	v_lshl_add_u64 v[204:205], v[208:209], 0, s[46:47]
	s_mov_b32 m0, s70
	s_nop 0
	global_load_lds_dwordx4 v[204:205], off
	v_lshl_add_u64 v[204:205], v[210:211], 0, s[46:47]
	s_mov_b32 m0, s71
	s_nop 0
	global_load_lds_dwordx4 v[204:205], off
	s_waitcnt vmcnt(8)
	s_waitcnt lgkmcnt(0)
	s_setprio 1
	s_barrier
	v_mfma_f32_16x16x32_bf16 v[60:63], v[128:131], v[160:163], v[60:63]
	v_mfma_f32_16x16x32_bf16 v[56:59], v[136:139], v[160:163], v[56:59]
	v_mfma_f32_16x16x32_bf16 v[44:47], v[128:131], v[168:171], v[44:47]
	v_mfma_f32_16x16x32_bf16 v[40:43], v[136:139], v[168:171], v[40:43]
	v_mfma_f32_16x16x32_bf16 v[28:31], v[128:131], v[176:179], v[28:31]
	v_mfma_f32_16x16x32_bf16 v[24:27], v[136:139], v[176:179], v[24:27]
	v_mfma_f32_16x16x32_bf16 v[12:15], v[128:131], v[184:187], v[12:15]
	v_mfma_f32_16x16x32_bf16 v[8:11], v[136:139], v[184:187], v[8:11]
	v_mfma_f32_16x16x32_bf16 v[60:63], v[132:135], v[164:167], v[60:63]
	v_mfma_f32_16x16x32_bf16 v[56:59], v[140:143], v[164:167], v[56:59]
	v_mfma_f32_16x16x32_bf16 v[44:47], v[132:135], v[172:175], v[44:47]
	v_mfma_f32_16x16x32_bf16 v[40:43], v[140:143], v[172:175], v[40:43]
	v_mfma_f32_16x16x32_bf16 v[28:31], v[132:135], v[180:183], v[28:31]
	v_mfma_f32_16x16x32_bf16 v[24:27], v[140:143], v[180:183], v[24:27]
	v_mfma_f32_16x16x32_bf16 v[12:15], v[132:135], v[200:203], v[12:15]
	v_mfma_f32_16x16x32_bf16 v[8:11], v[140:143], v[200:203], v[8:11]
	v_mfma_f32_16x16x32_bf16 v[52:55], v[144:147], v[160:163], v[52:55]
	v_mfma_f32_16x16x32_bf16 v[48:51], v[152:155], v[160:163], v[48:51]
	v_mfma_f32_16x16x32_bf16 v[36:39], v[144:147], v[168:171], v[36:39]
	v_mfma_f32_16x16x32_bf16 v[32:35], v[152:155], v[168:171], v[32:35]
	v_mfma_f32_16x16x32_bf16 v[20:23], v[144:147], v[176:179], v[20:23]
	v_mfma_f32_16x16x32_bf16 v[16:19], v[152:155], v[176:179], v[16:19]
	v_mfma_f32_16x16x32_bf16 v[4:7], v[144:147], v[184:187], v[4:7]
	v_mfma_f32_16x16x32_bf16 v[0:3], v[152:155], v[184:187], v[0:3]
	v_mfma_f32_16x16x32_bf16 v[52:55], v[148:151], v[164:167], v[52:55]
	v_mfma_f32_16x16x32_bf16 v[48:51], v[156:159], v[164:167], v[48:51]
	v_mfma_f32_16x16x32_bf16 v[36:39], v[148:151], v[172:175], v[36:39]
	v_mfma_f32_16x16x32_bf16 v[32:35], v[156:159], v[172:175], v[32:35]
	v_mfma_f32_16x16x32_bf16 v[20:23], v[148:151], v[180:183], v[20:23]
	v_mfma_f32_16x16x32_bf16 v[16:19], v[156:159], v[180:183], v[16:19]
	v_mfma_f32_16x16x32_bf16 v[4:7], v[148:151], v[200:203], v[4:7]
	v_mfma_f32_16x16x32_bf16 v[0:3], v[156:159], v[200:203], v[0:3]
	s_barrier
	s_setprio 0
	s_add_i32 s66, s66, 2
	s_add_u32 s22, s22, 0x100
	s_addc_u32 vcc_lo, vcc_lo, 0
	s_cmpk_gt_u32 s66, 0x55
	s_mov_b64 s[92:93], s[10:11]

; #define PG8_STAGE(bufoff, gbase, voff) do { _Pragma("unroll") for (int _i = 0; _i < 2; ++_i) \
;         __builtin_amdgcn_global_load_lds((const unsigned*)((const char*)(gbase) + (voff)[_i]), (PG8_LAS unsigned*)(lds + (bufoff) + ldsw + _i * 8192), 16, 0, 0); } while (0)
; #define PG8_LDA(dst, b, h) do { _Pragma("unroll") for (int m = 0; m < 4; ++m) _Pragma("unroll") for (int k = 0; k < 2; ++k) dst[m][k] = *(const PG8_LAS bf16x8*)(lds + PG8_SA(b, h) + aoff + m * 2048 + k * 1024); } while (0)
; #define PG8_LDB(dst, b, h) do { _Pragma("unroll") for (int n = 0; n < 2; ++n) _Pragma("unroll") for (int k = 0; k < 2; ++k) dst[n][k] = *(const PG8_LAS bf16x8*)(lds + PG8_SB(b, h) + boff + n * 2048 + k * 1024); } while (0)
; #define PG8_MMA(ai, bj, At, Bt) do { __builtin_amdgcn_s_setprio(1); _Pragma("unroll") for (int m = 0; m < 4; ++m) _Pragma("unroll") for (int n = 0; n < 2; ++n) _Pragma("unroll") for (int k = 0; k < 2; ++k) \
;         acc[ai][bj][m][n] = __builtin_amdgcn_mfma_f32_16x16x32_bf16(Bt[n][k], At[m][k], acc[ai][bj][m][n], 0, 0, 0); __builtin_amdgcn_s_setprio(0); } while (0)
; #define PG8_WAIT_V(n) asm volatile("s_waitcnt vmcnt(" #n ")" ::: "memory")
; template <class Epi, class Sched, bool ALIGN_EPI = false, bool SP2 = false>
; __device__ __forceinline__ void gemm_phase(PG8_LAS unsigned char* lds, const Gemm g, const Sched& S, const Epi& E) {
;     ...
;         const char* nA = has_next ? (const char*)g.A + (size_t)nxt.pm * tstep : cA; const char* nB = has_next ? (const char*)g.Bt + (size_t)nxt.pn * tstep : cB;
;         for (int t = 0; t < nt; t += 2) {
;             const bool last = (t == nt - 2);
;             const char* a1 = cA + (size_t)(t + 1) * kstep;
;             const char* a2 = last ? nA : cA + (size_t)(t + 2) * kstep; const char* b2 = last ? nB : cB + (size_t)(t + 2) * kstep;
;             const char* a3 = a2 + kstep; const char* b3 = b2 + kstep;
;             if (last && has_next) S.a_ready(nxt);
;             if constexpr (SP2) {
;             PG8_LDB(B0, 0, 0); PG8_LDB(B1, 0, 1); PG8_SCHED; PG8_LDA(At, 0, 0); PG8_STAGE(PG8_SA(1, 1), a1 + hstep, voffA);
;             PG8_WAIT_V(8); PG8_WAIT_L(0); PG8_BAR; PG8_MMA(0, 0, At, B0); PG8_MMA(0, 1, At, B1); PG8_BAR; PG8_SCHED;
;             PG8_LDA(At, 0, 1); PG8_STAGE(PG8_SB(0, 0), b2, voffB); PG8_STAGE(PG8_SB(0, 1), b2 + hstep, voffB); PG8_STAGE(PG8_SA(0, 0), a2, voffA);
.LBB0_402:
	s_ashr_i32 s91, s90, 31
	s_lshl_b64 s[12:13], s[90:91], 20
	s_add_u32 s92, s40, s12
	s_addc_u32 s93, s41, s13
	s_and_b64 s[12:13], s[8:9], exec
	s_cselect_b32 s12, s93, s11
	s_cselect_b32 s13, s92, s10
	s_ashr_i32 s89, s88, 31
	s_lshl_b64 s[66:67], s[88:89], 20
	s_add_u32 s82, s84, s66
	s_addc_u32 s83, s85, s67
	s_and_b64 s[66:67], s[8:9], exec
	s_cselect_b32 s47, s83, s97
	s_cselect_b32 s89, s82, s96
	s_add_u32 s10, s10, 0x80080
	s_addc_u32 s11, s11, 0
	s_add_u32 s91, s96, 0x100
	s_addc_u32 s95, s97, 0
	s_mov_b32 s66, -2
	s_waitcnt lgkmcnt(0)
	ds_read_b128 v[128:131], v179
	ds_read_b128 v[132:135], v179 offset:1024
	ds_read_b128 v[154:157], v179 offset:2048
	ds_read_b128 v[158:161], v179 offset:3072
	ds_read_b128 v[162:165], v180
	ds_read_b128 v[166:169], v180 offset:1024
	ds_read_b128 v[170:173], v180 offset:2048
	ds_read_b128 v[186:189], v180 offset:3072
	s_add_u32 s67, s10, 0xfff80080
	s_addc_u32 s74, s11, -1
	s_cmp_eq_u32 s66, 28
	s_cselect_b32 vcc_hi, s12, s74
	s_cselect_b32 vcc_lo, s13, s67
	s_cselect_b32 s97, s47, s95
	s_cselect_b32 s96, s89, s91
	v_lshl_add_u64 v[174:175], s[10:11], 0, v[146:147]
	s_add_i32 m0, s14, 0xc000
	ds_read_b128 v[190:193], v181
	ds_read_b128 v[194:197], v181 offset:1024
	ds_read_b128 v[198:201], v181 offset:2048
	ds_read_b128 v[202:205], v181 offset:3072
	ds_read_b128 v[206:209], v181 offset:4096
	ds_read_b128 v[210:213], v181 offset:5120
	ds_read_b128 v[218:221], v181 offset:6144
	ds_read_b128 v[224:227], v181 offset:7168
	global_load_lds_dwordx4 v[174:175], off
	v_lshl_add_u64 v[174:175], s[10:11], 0, v[148:149]
	s_add_i32 m0, s14, 0xe000
	s_nop 0
	global_load_lds_dwordx4 v[174:175], off
	s_waitcnt vmcnt(8)
	s_waitcnt lgkmcnt(0)
	s_setprio 1
	s_barrier
	v_mfma_f32_16x16x32_bf16 v[72:75], v[128:131], v[190:193], 0
	v_mfma_f32_16x16x32_bf16 v[80:83], v[154:157], v[190:193], 0
	v_mfma_f32_16x16x32_bf16 v[104:107], v[128:131], v[198:201], 0
	v_mfma_f32_16x16x32_bf16 v[108:111], v[154:157], v[198:201], 0
	v_mfma_f32_16x16x32_bf16 v[124:127], v[128:131], v[206:209], 0
	v_mfma_f32_16x16x32_bf16 v[120:123], v[154:157], v[206:209], 0
	v_mfma_f32_16x16x32_bf16 v[100:103], v[128:131], v[218:221], 0
	v_mfma_f32_16x16x32_bf16 v[96:99], v[154:157], v[218:221], 0
	v_mfma_f32_16x16x32_bf16 v[72:75], v[132:135], v[194:197], v[72:75]
	v_mfma_f32_16x16x32_bf16 v[80:83], v[158:161], v[194:197], v[80:83]
	v_mfma_f32_16x16x32_bf16 v[104:107], v[132:135], v[202:205], v[104:107]
	v_mfma_f32_16x16x32_bf16 v[108:111], v[158:161], v[202:205], v[108:111]
	v_mfma_f32_16x16x32_bf16 v[124:127], v[132:135], v[210:213], v[124:127]
	v_mfma_f32_16x16x32_bf16 v[120:123], v[158:161], v[210:213], v[120:123]
	v_mfma_f32_16x16x32_bf16 v[100:103], v[132:135], v[224:227], v[100:103]
	v_mfma_f32_16x16x32_bf16 v[96:99], v[158:161], v[224:227], v[96:99]
	v_mfma_f32_16x16x32_bf16 v[64:67], v[162:165], v[190:193], 0
	v_mfma_f32_16x16x32_bf16 v[68:71], v[170:173], v[190:193], 0
	v_mfma_f32_16x16x32_bf16 v[88:91], v[162:165], v[198:201], 0
	v_mfma_f32_16x16x32_bf16 v[92:95], v[170:173], v[198:201], 0
	v_mfma_f32_16x16x32_bf16 v[116:119], v[162:165], v[206:209], 0
	v_mfma_f32_16x16x32_bf16 v[112:115], v[170:173], v[206:209], 0
	v_mfma_f32_16x16x32_bf16 v[84:87], v[162:165], v[218:221], 0
	v_mfma_f32_16x16x32_bf16 v[76:79], v[170:173], v[218:221], 0
	v_mfma_f32_16x16x32_bf16 v[64:67], v[166:169], v[194:197], v[64:67]
	v_mfma_f32_16x16x32_bf16 v[68:71], v[186:189], v[194:197], v[68:71]
	v_mfma_f32_16x16x32_bf16 v[88:91], v[166:169], v[202:205], v[88:91]
	v_mfma_f32_16x16x32_bf16 v[92:95], v[186:189], v[202:205], v[92:95]
	v_mfma_f32_16x16x32_bf16 v[116:119], v[166:169], v[210:213], v[116:119]
	v_mfma_f32_16x16x32_bf16 v[112:115], v[186:189], v[210:213], v[112:115]
	v_mfma_f32_16x16x32_bf16 v[84:87], v[166:169], v[224:227], v[84:87]
	v_mfma_f32_16x16x32_bf16 v[76:79], v[186:189], v[224:227], v[76:79]
	s_barrier
	s_setprio 0
	s_add_i32 s67, s80, s3
	v_lshl_add_u64 v[174:175], s[96:97], 0, v[138:139]
	s_mov_b32 m0, s67
	ds_read_b128 v[190:193], v181 offset:16384
	ds_read_b128 v[194:197], v181 offset:17408
	ds_read_b128 v[198:201], v181 offset:18432
	ds_read_b128 v[202:205], v181 offset:19456
	ds_read_b128 v[206:209], v181 offset:20480
	ds_read_b128 v[210:213], v181 offset:21504
	ds_read_b128 v[218:221], v181 offset:22528
	ds_read_b128 v[224:227], v181 offset:23552
	global_load_lds_dwordx4 v[174:175], off
	s_add_i32 m0, s67, 0x2000
	s_add_u32 s74, s96, 0x80000
	v_lshl_add_u64 v[214:215], s[96:97], 0, v[142:143]
	s_addc_u32 s75, s97, 0
	s_add_i32 s67, s81, s3
	global_load_lds_dwordx4 v[214:215], off
	v_lshl_add_u64 v[228:229], s[74:75], 0, v[138:139]
	s_mov_b32 m0, s67
	v_lshl_add_u64 v[230:231], vcc, 0, v[140:141]
	global_load_lds_dwordx4 v[228:229], off
	v_lshl_add_u64 v[228:229], s[74:75], 0, v[142:143]
	s_add_i32 m0, s67, 0x2000
	s_nop 0
	global_load_lds_dwordx4 v[228:229], off
	v_lshl_add_u64 v[228:229], vcc, 0, v[136:137]
	s_mov_b32 m0, s14
	s_nop 0
	global_load_lds_dwordx4 v[228:229], off
	s_mov_b32 m0, s15
	s_nop 0
	global_load_lds_dwordx4 v[230:231], off
	s_waitcnt vmcnt(8)
	s_waitcnt lgkmcnt(0)
	s_setprio 1
	s_barrier
; #define PG8_STAGE(bufoff, gbase, voff) do { _Pragma("unroll") for (int _i = 0; _i < 2; ++_i) \
;         __builtin_amdgcn_global_load_lds((const unsigned*)((const char*)(gbase) + (voff)[_i]), (PG8_LAS unsigned*)(lds + (bufoff) + ldsw + _i * 8192), 16, 0, 0); } while (0)
; #define PG8_LDA(dst, b, h) do { _Pragma("unroll") for (int m = 0; m < 4; ++m) _Pragma("unroll") for (int k = 0; k < 2; ++k) dst[m][k] = *(const PG8_LAS bf16x8*)(lds + PG8_SA(b, h) + aoff + m * 2048 + k * 1024); } while (0)
; #define PG8_LDB(dst, b, h) do { _Pragma("unroll") for (int n = 0; n < 2; ++n) _Pragma("unroll") for (int k = 0; k < 2; ++k) dst[n][k] = *(const PG8_LAS bf16x8*)(lds + PG8_SB(b, h) + boff + n * 2048 + k * 1024); } while (0)
; #define PG8_MMA(ai, bj, At, Bt) do { __builtin_amdgcn_s_setprio(1); _Pragma("unroll") for (int m = 0; m < 4; ++m) _Pragma("unroll") for (int n = 0; n < 2; ++n) _Pragma("unroll") for (int k = 0; k < 2; ++k) \
;         acc[ai][bj][m][n] = __builtin_amdgcn_mfma_f32_16x16x32_bf16(Bt[n][k], At[m][k], acc[ai][bj][m][n], 0, 0, 0); __builtin_amdgcn_s_setprio(0); } while (0)
; #define PG8_WAIT_V(n) asm volatile("s_waitcnt vmcnt(" #n ")" ::: "memory")
; #define PG8_WAIT_L(n) asm volatile("s_waitcnt lgkmcnt(" #n ")" ::: "memory")
; #define PG8_BAR __builtin_amdgcn_s_barrier()
; #define PG8_SCHED __builtin_amdgcn_sched_barrier(0)
; template <class Epi, class Sched, bool ALIGN_EPI = false, bool SP2 = false>
; __device__ __forceinline__ void gemm_phase(PG8_LAS unsigned char* lds, const Gemm g, const Sched& S, const Epi& E) {
;     ...
;             PG8_WAIT_V(8); PG8_WAIT_L(0); PG8_BAR; PG8_MMA(1, 0, At, B0); PG8_MMA(1, 1, At, B1); PG8_BAR; PG8_SCHED;
;             PG8_LDB(B0, 1, 0); PG8_LDB(B1, 1, 1); PG8_SCHED; PG8_LDA(At, 1, 0); PG8_STAGE(PG8_SA(0, 1), a2 + hstep, voffA);
;             PG8_WAIT_V(8); PG8_WAIT_L(0); PG8_BAR; PG8_MMA(0, 0, At, B0); PG8_MMA(0, 1, At, B1); PG8_BAR; PG8_SCHED;
	v_mfma_f32_16x16x32_bf16 v[60:63], v[128:131], v[190:193], 0
	v_mfma_f32_16x16x32_bf16 v[56:59], v[154:157], v[190:193], 0
	v_mfma_f32_16x16x32_bf16 v[44:47], v[128:131], v[198:201], 0
	v_mfma_f32_16x16x32_bf16 v[40:43], v[154:157], v[198:201], 0
	v_mfma_f32_16x16x32_bf16 v[28:31], v[128:131], v[206:209], 0
	v_mfma_f32_16x16x32_bf16 v[24:27], v[154:157], v[206:209], 0
	v_mfma_f32_16x16x32_bf16 v[12:15], v[128:131], v[218:221], 0
	v_mfma_f32_16x16x32_bf16 v[8:11], v[154:157], v[218:221], 0
	v_mfma_f32_16x16x32_bf16 v[60:63], v[132:135], v[194:197], v[60:63]
	v_mfma_f32_16x16x32_bf16 v[56:59], v[158:161], v[194:197], v[56:59]
	v_mfma_f32_16x16x32_bf16 v[44:47], v[132:135], v[202:205], v[44:47]
	v_mfma_f32_16x16x32_bf16 v[40:43], v[158:161], v[202:205], v[40:43]
	v_mfma_f32_16x16x32_bf16 v[28:31], v[132:135], v[210:213], v[28:31]
	v_mfma_f32_16x16x32_bf16 v[24:27], v[158:161], v[210:213], v[24:27]
	v_mfma_f32_16x16x32_bf16 v[12:15], v[132:135], v[224:227], v[12:15]
	v_mfma_f32_16x16x32_bf16 v[8:11], v[158:161], v[224:227], v[8:11]
	v_mfma_f32_16x16x32_bf16 v[52:55], v[162:165], v[190:193], 0
	v_mfma_f32_16x16x32_bf16 v[48:51], v[170:173], v[190:193], 0
	v_mfma_f32_16x16x32_bf16 v[36:39], v[162:165], v[198:201], 0
	v_mfma_f32_16x16x32_bf16 v[32:35], v[170:173], v[198:201], 0
	v_mfma_f32_16x16x32_bf16 v[20:23], v[162:165], v[206:209], 0
	v_mfma_f32_16x16x32_bf16 v[16:19], v[170:173], v[206:209], 0
	v_mfma_f32_16x16x32_bf16 v[4:7], v[162:165], v[218:221], 0
	v_mfma_f32_16x16x32_bf16 v[0:3], v[170:173], v[218:221], 0
	v_mfma_f32_16x16x32_bf16 v[52:55], v[166:169], v[194:197], v[52:55]
	v_mfma_f32_16x16x32_bf16 v[48:51], v[186:189], v[194:197], v[48:51]
	v_mfma_f32_16x16x32_bf16 v[36:39], v[166:169], v[202:205], v[36:39]
	v_mfma_f32_16x16x32_bf16 v[32:35], v[186:189], v[202:205], v[32:35]
	v_mfma_f32_16x16x32_bf16 v[20:23], v[166:169], v[210:213], v[20:23]
	v_mfma_f32_16x16x32_bf16 v[16:19], v[186:189], v[210:213], v[16:19]
	v_mfma_f32_16x16x32_bf16 v[4:7], v[166:169], v[224:227], v[4:7]
	v_mfma_f32_16x16x32_bf16 v[0:3], v[186:189], v[224:227], v[0:3]
	s_barrier
	s_setprio 0
	s_add_i32 s67, 0, 0x18000
	s_add_i32 s76, 0, 0x1c000
	v_add_u32_e32 v158, s67, v177
	v_add_u32_e32 v186, s76, v177
	ds_read_b128 v[128:131], v158
	ds_read_b128 v[132:135], v158 offset:1024
	ds_read_b128 v[154:157], v158 offset:2048
	ds_read_b128 v[158:161], v158 offset:3072
	ds_read_b128 v[162:165], v186
	ds_read_b128 v[166:169], v186 offset:1024
	ds_read_b128 v[170:173], v186 offset:2048
	ds_read_b128 v[186:189], v186 offset:3072
	s_add_u32 s74, vcc_lo, 0x80000
	s_addc_u32 s75, vcc_hi, 0
	s_mov_b32 m0, s23
	v_lshl_add_u64 v[232:233], s[74:75], 0, v[136:137]
	ds_read_b128 v[190:193], v181 offset:32768
	ds_read_b128 v[194:197], v181 offset:33792
	ds_read_b128 v[198:201], v181 offset:34816
	ds_read_b128 v[202:205], v181 offset:35840
	ds_read_b128 v[206:209], v181 offset:36864
	ds_read_b128 v[210:213], v181 offset:37888
	ds_read_b128 v[218:221], v181 offset:38912
	ds_read_b128 v[224:227], v181 offset:39936
	global_load_lds_dwordx4 v[232:233], off
	v_lshl_add_u64 v[232:233], s[74:75], 0, v[140:141]
	s_mov_b32 m0, s34
	s_nop 0
	global_load_lds_dwordx4 v[232:233], off
	s_waitcnt vmcnt(8)
	s_waitcnt lgkmcnt(0)
	s_setprio 1
	s_barrier
	v_mfma_f32_16x16x32_bf16 v[72:75], v[128:131], v[190:193], v[72:75]
	v_mfma_f32_16x16x32_bf16 v[80:83], v[154:157], v[190:193], v[80:83]
	v_mfma_f32_16x16x32_bf16 v[104:107], v[128:131], v[198:201], v[104:107]
	v_mfma_f32_16x16x32_bf16 v[108:111], v[154:157], v[198:201], v[108:111]
	v_mfma_f32_16x16x32_bf16 v[124:127], v[128:131], v[206:209], v[124:127]
	v_mfma_f32_16x16x32_bf16 v[120:123], v[154:157], v[206:209], v[120:123]
	v_mfma_f32_16x16x32_bf16 v[100:103], v[128:131], v[218:221], v[100:103]
	v_mfma_f32_16x16x32_bf16 v[96:99], v[154:157], v[218:221], v[96:99]
	v_mfma_f32_16x16x32_bf16 v[72:75], v[132:135], v[194:197], v[72:75]
	v_mfma_f32_16x16x32_bf16 v[80:83], v[158:161], v[194:197], v[80:83]
	v_mfma_f32_16x16x32_bf16 v[104:107], v[132:135], v[202:205], v[104:107]
	v_mfma_f32_16x16x32_bf16 v[108:111], v[158:161], v[202:205], v[108:111]
	v_mfma_f32_16x16x32_bf16 v[124:127], v[132:135], v[210:213], v[124:127]
	v_mfma_f32_16x16x32_bf16 v[120:123], v[158:161], v[210:213], v[120:123]
	v_mfma_f32_16x16x32_bf16 v[100:103], v[132:135], v[224:227], v[100:103]
	v_mfma_f32_16x16x32_bf16 v[96:99], v[158:161], v[224:227], v[96:99]
	v_mfma_f32_16x16x32_bf16 v[64:67], v[162:165], v[190:193], v[64:67]
	v_mfma_f32_16x16x32_bf16 v[68:71], v[170:173], v[190:193], v[68:71]
	v_mfma_f32_16x16x32_bf16 v[88:91], v[162:165], v[198:201], v[88:91]
	v_mfma_f32_16x16x32_bf16 v[92:95], v[170:173], v[198:201], v[92:95]
	v_mfma_f32_16x16x32_bf16 v[116:119], v[162:165], v[206:209], v[116:119]
	v_mfma_f32_16x16x32_bf16 v[112:115], v[170:173], v[206:209], v[112:115]
	v_mfma_f32_16x16x32_bf16 v[84:87], v[162:165], v[218:221], v[84:87]
	v_mfma_f32_16x16x32_bf16 v[76:79], v[170:173], v[218:221], v[76:79]
	v_mfma_f32_16x16x32_bf16 v[64:67], v[166:169], v[194:197], v[64:67]
	v_mfma_f32_16x16x32_bf16 v[68:71], v[186:189], v[194:197], v[68:71]
	v_mfma_f32_16x16x32_bf16 v[88:91], v[166:169], v[202:205], v[88:91]
	v_mfma_f32_16x16x32_bf16 v[92:95], v[186:189], v[202:205], v[92:95]
	v_mfma_f32_16x16x32_bf16 v[116:119], v[166:169], v[210:213], v[116:119]
	v_mfma_f32_16x16x32_bf16 v[112:115], v[186:189], v[210:213], v[112:115]
	v_mfma_f32_16x16x32_bf16 v[84:87], v[166:169], v[224:227], v[84:87]
	v_mfma_f32_16x16x32_bf16 v[76:79], v[186:189], v[224:227], v[76:79]
	s_barrier
; #define PG8_STAGE(bufoff, gbase, voff) do { _Pragma("unroll") for (int _i = 0; _i < 2; ++_i) \
;         __builtin_amdgcn_global_load_lds((const unsigned*)((const char*)(gbase) + (voff)[_i]), (PG8_LAS unsigned*)(lds + (bufoff) + ldsw + _i * 8192), 16, 0, 0); } while (0)
; #define PG8_LDA(dst, b, h) do { _Pragma("unroll") for (int m = 0; m < 4; ++m) _Pragma("unroll") for (int k = 0; k < 2; ++k) dst[m][k] = *(const PG8_LAS bf16x8*)(lds + PG8_SA(b, h) + aoff + m * 2048 + k * 1024); } while (0)
; #define PG8_MMA(ai, bj, At, Bt) do { __builtin_amdgcn_s_setprio(1); _Pragma("unroll") for (int m = 0; m < 4; ++m) _Pragma("unroll") for (int n = 0; n < 2; ++n) _Pragma("unroll") for (int k = 0; k < 2; ++k) \
;         acc[ai][bj][m][n] = __builtin_amdgcn_mfma_f32_16x16x32_bf16(Bt[n][k], At[m][k], acc[ai][bj][m][n], 0, 0, 0); __builtin_amdgcn_s_setprio(0); } while (0)
; #define PG8_WAIT_V(n) asm volatile("s_waitcnt vmcnt(" #n ")" ::: "memory")
; #define PG8_WAIT_L(n) asm volatile("s_waitcnt lgkmcnt(" #n ")" ::: "memory")
; #define PG8_BAR __builtin_amdgcn_s_barrier()
; #define PG8_SCHED __builtin_amdgcn_sched_barrier(0)
; template <class Epi, class Sched, bool ALIGN_EPI = false, bool SP2 = false>
; __device__ __forceinline__ void gemm_phase(PG8_LAS unsigned char* lds, const Gemm g, const Sched& S, const Epi& E) {
;     ...
;         for (int t = 0; t < nt; t += 2) {
;             const bool last = (t == nt - 2);
;             const char* a1 = cA + (size_t)(t + 1) * kstep;
;             const char* a2 = last ? nA : cA + (size_t)(t + 2) * kstep; const char* b2 = last ? nB : cB + (size_t)(t + 2) * kstep;
;     ...
;             PG8_LDA(At, 1, 1); PG8_STAGE(PG8_SB(1, 0), b3, voffB); PG8_STAGE(PG8_SB(1, 1), b3 + hstep, voffB); PG8_STAGE(PG8_SA(1, 0), a3, voffA);
;             PG8_WAIT_V(8); PG8_WAIT_L(0); PG8_BAR; PG8_MMA(1, 0, At, B0); PG8_MMA(1, 1, At, B1); PG8_BAR; PG8_SCHED;
	s_setprio 0
	s_add_i32 s67, s67, s3
	v_lshl_add_u64 v[174:175], v[174:175], 0, s[44:45]
	s_mov_b32 m0, s67
	ds_read_b128 v[190:193], v181 offset:49152
	ds_read_b128 v[194:197], v181 offset:50176
	ds_read_b128 v[198:201], v181 offset:51200
	ds_read_b128 v[202:205], v181 offset:52224
	ds_read_b128 v[206:209], v181 offset:53248
	ds_read_b128 v[210:213], v181 offset:54272
	ds_read_b128 v[218:221], v181 offset:55296
	ds_read_b128 v[224:227], v181 offset:56320
	global_load_lds_dwordx4 v[174:175], off
	s_add_i32 m0, s67, 0x2000
	s_add_u32 s74, s96, 0x80080
	v_lshl_add_u64 v[174:175], v[214:215], 0, s[44:45]
	s_addc_u32 s75, s97, 0
	s_add_i32 s67, s76, s3
	global_load_lds_dwordx4 v[174:175], off
	v_lshl_add_u64 v[174:175], s[74:75], 0, v[138:139]
	s_mov_b32 m0, s67
	s_nop 0
	global_load_lds_dwordx4 v[174:175], off
	v_lshl_add_u64 v[174:175], s[74:75], 0, v[142:143]
	s_add_i32 m0, s67, 0x2000
	s_nop 0
	global_load_lds_dwordx4 v[174:175], off
	v_lshl_add_u64 v[174:175], v[228:229], 0, s[44:45]
	s_mov_b32 m0, s68
	s_nop 0
	global_load_lds_dwordx4 v[174:175], off
	v_lshl_add_u64 v[174:175], v[230:231], 0, s[44:45]
	s_mov_b32 m0, s69
	s_nop 0
	global_load_lds_dwordx4 v[174:175], off
	s_waitcnt vmcnt(8)
	s_waitcnt lgkmcnt(0)
	s_setprio 1
	s_barrier
	v_mfma_f32_16x16x32_bf16 v[60:63], v[128:131], v[190:193], v[60:63]
	v_mfma_f32_16x16x32_bf16 v[56:59], v[154:157], v[190:193], v[56:59]
	v_mfma_f32_16x16x32_bf16 v[44:47], v[128:131], v[198:201], v[44:47]
	v_mfma_f32_16x16x32_bf16 v[40:43], v[154:157], v[198:201], v[40:43]
	v_mfma_f32_16x16x32_bf16 v[28:31], v[128:131], v[206:209], v[28:31]
	v_mfma_f32_16x16x32_bf16 v[24:27], v[154:157], v[206:209], v[24:27]
	v_mfma_f32_16x16x32_bf16 v[12:15], v[128:131], v[218:221], v[12:15]
	v_mfma_f32_16x16x32_bf16 v[8:11], v[154:157], v[218:221], v[8:11]
	v_mfma_f32_16x16x32_bf16 v[60:63], v[132:135], v[194:197], v[60:63]
	v_mfma_f32_16x16x32_bf16 v[56:59], v[158:161], v[194:197], v[56:59]
	v_mfma_f32_16x16x32_bf16 v[44:47], v[132:135], v[202:205], v[44:47]
	v_mfma_f32_16x16x32_bf16 v[40:43], v[158:161], v[202:205], v[40:43]
	v_mfma_f32_16x16x32_bf16 v[28:31], v[132:135], v[210:213], v[28:31]
	v_mfma_f32_16x16x32_bf16 v[24:27], v[158:161], v[210:213], v[24:27]
	v_mfma_f32_16x16x32_bf16 v[12:15], v[132:135], v[224:227], v[12:15]
	v_mfma_f32_16x16x32_bf16 v[8:11], v[158:161], v[224:227], v[8:11]
	v_mfma_f32_16x16x32_bf16 v[52:55], v[162:165], v[190:193], v[52:55]
	v_mfma_f32_16x16x32_bf16 v[48:51], v[170:173], v[190:193], v[48:51]
	v_mfma_f32_16x16x32_bf16 v[36:39], v[162:165], v[198:201], v[36:39]
	v_mfma_f32_16x16x32_bf16 v[32:35], v[170:173], v[198:201], v[32:35]
	v_mfma_f32_16x16x32_bf16 v[20:23], v[162:165], v[206:209], v[20:23]
	v_mfma_f32_16x16x32_bf16 v[16:19], v[170:173], v[206:209], v[16:19]
	v_mfma_f32_16x16x32_bf16 v[4:7], v[162:165], v[218:221], v[4:7]
	v_mfma_f32_16x16x32_bf16 v[0:3], v[170:173], v[218:221], v[0:3]
	v_mfma_f32_16x16x32_bf16 v[52:55], v[166:169], v[194:197], v[52:55]
	v_mfma_f32_16x16x32_bf16 v[48:51], v[186:189], v[194:197], v[48:51]
	v_mfma_f32_16x16x32_bf16 v[36:39], v[166:169], v[202:205], v[36:39]
	v_mfma_f32_16x16x32_bf16 v[32:35], v[186:189], v[202:205], v[32:35]
	v_mfma_f32_16x16x32_bf16 v[20:23], v[166:169], v[210:213], v[20:23]
	v_mfma_f32_16x16x32_bf16 v[16:19], v[186:189], v[210:213], v[16:19]
	v_mfma_f32_16x16x32_bf16 v[4:7], v[166:169], v[224:227], v[4:7]
	v_mfma_f32_16x16x32_bf16 v[0:3], v[186:189], v[224:227], v[0:3]
	s_barrier
	s_setprio 0
	s_add_i32 s66, s66, 2
	s_add_u32 s10, s10, 0x100
	s_addc_u32 s11, s11, 0
	s_add_u32 s91, s91, 0x100
	s_addc_u32 s95, s95, 0
	s_cmp_gt_u32 s66, 29

; #define PG8_STAGE(bufoff, gbase, voff) do { _Pragma("unroll") for (int _i = 0; _i < 2; ++_i) \
;         __builtin_amdgcn_global_load_lds((const unsigned*)((const char*)(gbase) + (voff)[_i]), (PG8_LAS unsigned*)(lds + (bufoff) + ldsw + _i * 8192), 16, 0, 0); } while (0)
; #define PG8_LDA(dst, b, h) do { _Pragma("unroll") for (int m = 0; m < 4; ++m) _Pragma("unroll") for (int k = 0; k < 2; ++k) dst[m][k] = *(const PG8_LAS bf16x8*)(lds + PG8_SA(b, h) + aoff + m * 2048 + k * 1024); } while (0)
; #define PG8_LDB(dst, b, h) do { _Pragma("unroll") for (int n = 0; n < 2; ++n) _Pragma("unroll") for (int k = 0; k < 2; ++k) dst[n][k] = *(const PG8_LAS bf16x8*)(lds + PG8_SB(b, h) + boff + n * 2048 + k * 1024); } while (0)
; #define PG8_MMA(ai, bj, At, Bt) do { __builtin_amdgcn_s_setprio(1); _Pragma("unroll") for (int m = 0; m < 4; ++m) _Pragma("unroll") for (int n = 0; n < 2; ++n) _Pragma("unroll") for (int k = 0; k < 2; ++k) \
;         acc[ai][bj][m][n] = __builtin_amdgcn_mfma_f32_16x16x32_bf16(Bt[n][k], At[m][k], acc[ai][bj][m][n], 0, 0, 0); __builtin_amdgcn_s_setprio(0); } while (0)
; #define PG8_WAIT_V(n) asm volatile("s_waitcnt vmcnt(" #n ")" ::: "memory")
; template <class Epi, class Sched, bool ALIGN_EPI = false, bool SP2 = false>
; __device__ __forceinline__ void gemm_phase(PG8_LAS unsigned char* lds, const Gemm g, const Sched& S, const Epi& E) {
;     ...
;         const char* nA = has_next ? (const char*)g.A + (size_t)nxt.pm * tstep : cA; const char* nB = has_next ? (const char*)g.Bt + (size_t)nxt.pn * tstep : cB;
;         for (int t = 0; t < nt; t += 2) {
;             const bool last = (t == nt - 2);
;             const char* a1 = cA + (size_t)(t + 1) * kstep;
;             const char* a2 = last ? nA : cA + (size_t)(t + 2) * kstep; const char* b2 = last ? nB : cB + (size_t)(t + 2) * kstep;
;             const char* a3 = a2 + kstep; const char* b3 = b2 + kstep;
;             if (last && has_next) S.a_ready(nxt);
;             if constexpr (SP2) {
;             PG8_LDB(B0, 0, 0); PG8_LDB(B1, 0, 1); PG8_SCHED; PG8_LDA(At, 0, 0); PG8_STAGE(PG8_SA(1, 1), a1 + hstep, voffA);
;             PG8_WAIT_V(8); PG8_WAIT_L(0); PG8_BAR; PG8_MMA(0, 0, At, B0); PG8_MMA(0, 1, At, B1); PG8_BAR; PG8_SCHED;
;             PG8_LDA(At, 0, 1); PG8_STAGE(PG8_SB(0, 0), b2, voffB); PG8_STAGE(PG8_SB(0, 1), b2 + hstep, voffB); PG8_STAGE(PG8_SA(0, 0), a2, voffA);
.LBB0_492:
	s_ashr_i32 s85, s84, 31
	s_lshl_b64 s[12:13], s[84:85], 20
	s_add_u32 s86, s0, s12
	s_addc_u32 s87, s1, s13
	s_and_b64 s[12:13], s[6:7], exec
	s_cselect_b32 s12, s87, s83
	s_cselect_b32 s13, s86, s82
	s_ashr_i32 s47, s46, 31
	s_lshl_b64 s[66:67], s[46:47], 20
	s_add_u32 s88, s40, s66
	s_addc_u32 s89, s41, s67
	s_and_b64 s[66:67], s[6:7], exec
	s_cselect_b32 s47, s89, s95
	s_cselect_b32 s81, s88, s94
	s_add_u32 s92, s82, 0x80080
	s_addc_u32 s93, s83, 0
	s_add_u32 s85, s94, 0x100
	s_addc_u32 s91, s95, 0
	s_mov_b32 s66, -2
	ds_read_b128 v[144:147], v166
	ds_read_b128 v[148:151], v166 offset:1024
	ds_read_b128 v[152:155], v166 offset:2048
	ds_read_b128 v[156:159], v166 offset:3072
	ds_read_b128 v[172:175], v167
	ds_read_b128 v[176:179], v167 offset:1024
	ds_read_b128 v[180:183], v167 offset:2048
	ds_read_b128 v[184:187], v167 offset:3072
	s_add_u32 s67, s92, 0xfff80080
	s_addc_u32 s74, s93, -1
	s_cmp_eq_u32 s66, 28
	s_cselect_b32 s95, s12, s74
	s_cselect_b32 s94, s13, s67
	s_cselect_b32 s83, s47, s91
	s_cselect_b32 s82, s81, s85
	v_lshl_add_u64 v[160:161], s[92:93], 0, v[136:137]
	s_add_i32 m0, s14, 0xc000
	ds_read_b128 v[188:191], v168
	ds_read_b128 v[192:195], v168 offset:1024
	ds_read_b128 v[196:199], v168 offset:2048
	ds_read_b128 v[200:203], v168 offset:3072
	ds_read_b128 v[204:207], v168 offset:4096
	ds_read_b128 v[208:211], v168 offset:5120
	ds_read_b128 v[212:215], v168 offset:6144
	ds_read_b128 v[218:221], v168 offset:7168
	global_load_lds_dwordx4 v[160:161], off
	v_lshl_add_u64 v[160:161], s[92:93], 0, v[138:139]
	s_add_i32 m0, s14, 0xe000
	s_nop 0
	global_load_lds_dwordx4 v[160:161], off
	s_waitcnt vmcnt(8)
	s_waitcnt lgkmcnt(0)
	s_setprio 1
	s_barrier
	v_mfma_f32_16x16x32_bf16 v[124:127], v[144:147], v[188:191], 0
	v_mfma_f32_16x16x32_bf16 v[120:123], v[152:155], v[188:191], 0
	v_mfma_f32_16x16x32_bf16 v[108:111], v[144:147], v[196:199], 0
	v_mfma_f32_16x16x32_bf16 v[104:107], v[152:155], v[196:199], 0
	v_mfma_f32_16x16x32_bf16 v[100:103], v[144:147], v[204:207], 0
	v_mfma_f32_16x16x32_bf16 v[92:95], v[152:155], v[204:207], 0
	v_mfma_f32_16x16x32_bf16 v[84:87], v[144:147], v[212:215], 0
	v_mfma_f32_16x16x32_bf16 v[76:79], v[152:155], v[212:215], 0
	v_mfma_f32_16x16x32_bf16 v[124:127], v[148:151], v[192:195], v[124:127]
	v_mfma_f32_16x16x32_bf16 v[120:123], v[156:159], v[192:195], v[120:123]
	v_mfma_f32_16x16x32_bf16 v[108:111], v[148:151], v[200:203], v[108:111]
	v_mfma_f32_16x16x32_bf16 v[104:107], v[156:159], v[200:203], v[104:107]
	v_mfma_f32_16x16x32_bf16 v[100:103], v[148:151], v[208:211], v[100:103]
	v_mfma_f32_16x16x32_bf16 v[92:95], v[156:159], v[208:211], v[92:95]
	v_mfma_f32_16x16x32_bf16 v[84:87], v[148:151], v[218:221], v[84:87]
	v_mfma_f32_16x16x32_bf16 v[76:79], v[156:159], v[218:221], v[76:79]
	v_mfma_f32_16x16x32_bf16 v[116:119], v[172:175], v[188:191], 0
	v_mfma_f32_16x16x32_bf16 v[112:115], v[180:183], v[188:191], 0
	v_mfma_f32_16x16x32_bf16 v[96:99], v[172:175], v[196:199], 0
	v_mfma_f32_16x16x32_bf16 v[88:91], v[180:183], v[196:199], 0
	v_mfma_f32_16x16x32_bf16 v[80:83], v[172:175], v[204:207], 0
	v_mfma_f32_16x16x32_bf16 v[72:75], v[180:183], v[204:207], 0
	v_mfma_f32_16x16x32_bf16 v[68:71], v[172:175], v[212:215], 0
	v_mfma_f32_16x16x32_bf16 v[64:67], v[180:183], v[212:215], 0
	v_mfma_f32_16x16x32_bf16 v[116:119], v[176:179], v[192:195], v[116:119]
	v_mfma_f32_16x16x32_bf16 v[112:115], v[184:187], v[192:195], v[112:115]
	v_mfma_f32_16x16x32_bf16 v[96:99], v[176:179], v[200:203], v[96:99]
	v_mfma_f32_16x16x32_bf16 v[88:91], v[184:187], v[200:203], v[88:91]
	v_mfma_f32_16x16x32_bf16 v[80:83], v[176:179], v[208:211], v[80:83]
	v_mfma_f32_16x16x32_bf16 v[72:75], v[184:187], v[208:211], v[72:75]
	v_mfma_f32_16x16x32_bf16 v[68:71], v[176:179], v[218:221], v[68:71]
	v_mfma_f32_16x16x32_bf16 v[64:67], v[184:187], v[218:221], v[64:67]
	s_barrier
	s_setprio 0
	s_add_i32 s67, s70, s3
	v_lshl_add_u64 v[160:161], s[82:83], 0, v[132:133]
	s_mov_b32 m0, s67
	ds_read_b128 v[188:191], v168 offset:16384
	ds_read_b128 v[192:195], v168 offset:17408
	ds_read_b128 v[196:199], v168 offset:18432
	ds_read_b128 v[200:203], v168 offset:19456
	ds_read_b128 v[204:207], v168 offset:20480
	ds_read_b128 v[208:211], v168 offset:21504
	ds_read_b128 v[212:215], v168 offset:22528
	ds_read_b128 v[218:221], v168 offset:23552
	global_load_lds_dwordx4 v[160:161], off
	s_add_i32 m0, s67, 0x2000
	s_add_u32 s74, s82, 0x80000
	v_lshl_add_u64 v[224:225], s[82:83], 0, v[128:129]
	s_addc_u32 s75, s83, 0
	s_add_i32 s67, s71, s3
	global_load_lds_dwordx4 v[224:225], off
	v_lshl_add_u64 v[226:227], s[74:75], 0, v[132:133]
	s_mov_b32 m0, s67
	v_lshl_add_u64 v[228:229], s[94:95], 0, v[130:131]
	global_load_lds_dwordx4 v[226:227], off
	v_lshl_add_u64 v[226:227], s[74:75], 0, v[128:129]
	s_add_i32 m0, s67, 0x2000
	s_nop 0
	global_load_lds_dwordx4 v[226:227], off
	v_lshl_add_u64 v[226:227], s[94:95], 0, v[134:135]
	s_mov_b32 m0, s14
	s_nop 0
	global_load_lds_dwordx4 v[226:227], off
	s_mov_b32 m0, s15
	s_nop 0
	global_load_lds_dwordx4 v[228:229], off
	s_waitcnt vmcnt(8)
	s_waitcnt lgkmcnt(0)
	s_setprio 1
	s_barrier
; #define PG8_STAGE(bufoff, gbase, voff) do { _Pragma("unroll") for (int _i = 0; _i < 2; ++_i) \
;         __builtin_amdgcn_global_load_lds((const unsigned*)((const char*)(gbase) + (voff)[_i]), (PG8_LAS unsigned*)(lds + (bufoff) + ldsw + _i * 8192), 16, 0, 0); } while (0)
; #define PG8_LDA(dst, b, h) do { _Pragma("unroll") for (int m = 0; m < 4; ++m) _Pragma("unroll") for (int k = 0; k < 2; ++k) dst[m][k] = *(const PG8_LAS bf16x8*)(lds + PG8_SA(b, h) + aoff + m * 2048 + k * 1024); } while (0)
; #define PG8_LDB(dst, b, h) do { _Pragma("unroll") for (int n = 0; n < 2; ++n) _Pragma("unroll") for (int k = 0; k < 2; ++k) dst[n][k] = *(const PG8_LAS bf16x8*)(lds + PG8_SB(b, h) + boff + n * 2048 + k * 1024); } while (0)
; #define PG8_MMA(ai, bj, At, Bt) do { __builtin_amdgcn_s_setprio(1); _Pragma("unroll") for (int m = 0; m < 4; ++m) _Pragma("unroll") for (int n = 0; n < 2; ++n) _Pragma("unroll") for (int k = 0; k < 2; ++k) \
;         acc[ai][bj][m][n] = __builtin_amdgcn_mfma_f32_16x16x32_bf16(Bt[n][k], At[m][k], acc[ai][bj][m][n], 0, 0, 0); __builtin_amdgcn_s_setprio(0); } while (0)
; #define PG8_WAIT_V(n) asm volatile("s_waitcnt vmcnt(" #n ")" ::: "memory")
; #define PG8_WAIT_L(n) asm volatile("s_waitcnt lgkmcnt(" #n ")" ::: "memory")
; #define PG8_BAR __builtin_amdgcn_s_barrier()
; #define PG8_SCHED __builtin_amdgcn_sched_barrier(0)
; template <class Epi, class Sched, bool ALIGN_EPI = false, bool SP2 = false>
; __device__ __forceinline__ void gemm_phase(PG8_LAS unsigned char* lds, const Gemm g, const Sched& S, const Epi& E) {
;     ...
;             PG8_WAIT_V(8); PG8_WAIT_L(0); PG8_BAR; PG8_MMA(1, 0, At, B0); PG8_MMA(1, 1, At, B1); PG8_BAR; PG8_SCHED;
;             PG8_LDB(B0, 1, 0); PG8_LDB(B1, 1, 1); PG8_SCHED; PG8_LDA(At, 1, 0); PG8_STAGE(PG8_SA(0, 1), a2 + hstep, voffA);
;             PG8_WAIT_V(8); PG8_WAIT_L(0); PG8_BAR; PG8_MMA(0, 0, At, B0); PG8_MMA(0, 1, At, B1); PG8_BAR; PG8_SCHED;
	v_mfma_f32_16x16x32_bf16 v[60:63], v[144:147], v[188:191], 0
	v_mfma_f32_16x16x32_bf16 v[56:59], v[152:155], v[188:191], 0
	v_mfma_f32_16x16x32_bf16 v[52:55], v[144:147], v[196:199], 0
	v_mfma_f32_16x16x32_bf16 v[44:47], v[152:155], v[196:199], 0
	v_mfma_f32_16x16x32_bf16 v[36:39], v[144:147], v[204:207], 0
	v_mfma_f32_16x16x32_bf16 v[28:31], v[152:155], v[204:207], 0
	v_mfma_f32_16x16x32_bf16 v[20:23], v[144:147], v[212:215], 0
	v_mfma_f32_16x16x32_bf16 v[12:15], v[152:155], v[212:215], 0
	v_mfma_f32_16x16x32_bf16 v[60:63], v[148:151], v[192:195], v[60:63]
	v_mfma_f32_16x16x32_bf16 v[56:59], v[156:159], v[192:195], v[56:59]
	v_mfma_f32_16x16x32_bf16 v[52:55], v[148:151], v[200:203], v[52:55]
	v_mfma_f32_16x16x32_bf16 v[44:47], v[156:159], v[200:203], v[44:47]
	v_mfma_f32_16x16x32_bf16 v[36:39], v[148:151], v[208:211], v[36:39]
	v_mfma_f32_16x16x32_bf16 v[28:31], v[156:159], v[208:211], v[28:31]
	v_mfma_f32_16x16x32_bf16 v[20:23], v[148:151], v[218:221], v[20:23]
	v_mfma_f32_16x16x32_bf16 v[12:15], v[156:159], v[218:221], v[12:15]
	v_mfma_f32_16x16x32_bf16 v[48:51], v[172:175], v[188:191], 0
	v_mfma_f32_16x16x32_bf16 v[40:43], v[180:183], v[188:191], 0
	v_mfma_f32_16x16x32_bf16 v[32:35], v[172:175], v[196:199], 0
	v_mfma_f32_16x16x32_bf16 v[24:27], v[180:183], v[196:199], 0
	v_mfma_f32_16x16x32_bf16 v[16:19], v[172:175], v[204:207], 0
	v_mfma_f32_16x16x32_bf16 v[8:11], v[180:183], v[204:207], 0
	v_mfma_f32_16x16x32_bf16 v[4:7], v[172:175], v[212:215], 0
	v_mfma_f32_16x16x32_bf16 v[0:3], v[180:183], v[212:215], 0
	v_mfma_f32_16x16x32_bf16 v[48:51], v[176:179], v[192:195], v[48:51]
	v_mfma_f32_16x16x32_bf16 v[40:43], v[184:187], v[192:195], v[40:43]
	v_mfma_f32_16x16x32_bf16 v[32:35], v[176:179], v[200:203], v[32:35]
	v_mfma_f32_16x16x32_bf16 v[24:27], v[184:187], v[200:203], v[24:27]
	v_mfma_f32_16x16x32_bf16 v[16:19], v[176:179], v[208:211], v[16:19]
	v_mfma_f32_16x16x32_bf16 v[8:11], v[184:187], v[208:211], v[8:11]
	v_mfma_f32_16x16x32_bf16 v[4:7], v[176:179], v[218:221], v[4:7]
	v_mfma_f32_16x16x32_bf16 v[0:3], v[184:187], v[218:221], v[0:3]
	s_barrier
	s_setprio 0
	s_add_i32 s67, 0, 0x18000
	s_add_i32 s76, 0, 0x1c000
	v_add_u32_e32 v156, s67, v163
	v_add_u32_e32 v171, s76, v163
	ds_read_b128 v[144:147], v156
	ds_read_b128 v[148:151], v156 offset:1024
	ds_read_b128 v[152:155], v156 offset:2048
	ds_read_b128 v[156:159], v156 offset:3072
	ds_read_b128 v[172:175], v171
	ds_read_b128 v[176:179], v171 offset:1024
	ds_read_b128 v[180:183], v171 offset:2048
	ds_read_b128 v[184:187], v171 offset:3072
	s_add_u32 s74, s94, 0x80000
	s_addc_u32 s75, s95, 0
	s_mov_b32 m0, s23
	v_lshl_add_u64 v[230:231], s[74:75], 0, v[134:135]
	ds_read_b128 v[188:191], v168 offset:32768
	ds_read_b128 v[192:195], v168 offset:33792
	ds_read_b128 v[196:199], v168 offset:34816
	ds_read_b128 v[200:203], v168 offset:35840
	ds_read_b128 v[204:207], v168 offset:36864
	ds_read_b128 v[208:211], v168 offset:37888
	ds_read_b128 v[212:215], v168 offset:38912
	ds_read_b128 v[218:221], v168 offset:39936
	global_load_lds_dwordx4 v[230:231], off
	v_lshl_add_u64 v[230:231], s[74:75], 0, v[130:131]
	s_mov_b32 m0, s34
	s_nop 0
	global_load_lds_dwordx4 v[230:231], off
	s_waitcnt vmcnt(8)
	s_waitcnt lgkmcnt(0)
	s_setprio 1
	s_barrier
	v_mfma_f32_16x16x32_bf16 v[124:127], v[144:147], v[188:191], v[124:127]
	v_mfma_f32_16x16x32_bf16 v[120:123], v[152:155], v[188:191], v[120:123]
	v_mfma_f32_16x16x32_bf16 v[108:111], v[144:147], v[196:199], v[108:111]
	v_mfma_f32_16x16x32_bf16 v[104:107], v[152:155], v[196:199], v[104:107]
	v_mfma_f32_16x16x32_bf16 v[100:103], v[144:147], v[204:207], v[100:103]
	v_mfma_f32_16x16x32_bf16 v[92:95], v[152:155], v[204:207], v[92:95]
	v_mfma_f32_16x16x32_bf16 v[84:87], v[144:147], v[212:215], v[84:87]
	v_mfma_f32_16x16x32_bf16 v[76:79], v[152:155], v[212:215], v[76:79]
	v_mfma_f32_16x16x32_bf16 v[124:127], v[148:151], v[192:195], v[124:127]
	v_mfma_f32_16x16x32_bf16 v[120:123], v[156:159], v[192:195], v[120:123]
	v_mfma_f32_16x16x32_bf16 v[108:111], v[148:151], v[200:203], v[108:111]
	v_mfma_f32_16x16x32_bf16 v[104:107], v[156:159], v[200:203], v[104:107]
	v_mfma_f32_16x16x32_bf16 v[100:103], v[148:151], v[208:211], v[100:103]
	v_mfma_f32_16x16x32_bf16 v[92:95], v[156:159], v[208:211], v[92:95]
	v_mfma_f32_16x16x32_bf16 v[84:87], v[148:151], v[218:221], v[84:87]
	v_mfma_f32_16x16x32_bf16 v[76:79], v[156:159], v[218:221], v[76:79]
	v_mfma_f32_16x16x32_bf16 v[116:119], v[172:175], v[188:191], v[116:119]
	v_mfma_f32_16x16x32_bf16 v[112:115], v[180:183], v[188:191], v[112:115]
	v_mfma_f32_16x16x32_bf16 v[96:99], v[172:175], v[196:199], v[96:99]
	v_mfma_f32_16x16x32_bf16 v[88:91], v[180:183], v[196:199], v[88:91]
	v_mfma_f32_16x16x32_bf16 v[80:83], v[172:175], v[204:207], v[80:83]
	v_mfma_f32_16x16x32_bf16 v[72:75], v[180:183], v[204:207], v[72:75]
	v_mfma_f32_16x16x32_bf16 v[68:71], v[172:175], v[212:215], v[68:71]
	v_mfma_f32_16x16x32_bf16 v[64:67], v[180:183], v[212:215], v[64:67]
	v_mfma_f32_16x16x32_bf16 v[116:119], v[176:179], v[192:195], v[116:119]
	v_mfma_f32_16x16x32_bf16 v[112:115], v[184:187], v[192:195], v[112:115]
	v_mfma_f32_16x16x32_bf16 v[96:99], v[176:179], v[200:203], v[96:99]
	v_mfma_f32_16x16x32_bf16 v[88:91], v[184:187], v[200:203], v[88:91]
	v_mfma_f32_16x16x32_bf16 v[80:83], v[176:179], v[208:211], v[80:83]
	v_mfma_f32_16x16x32_bf16 v[72:75], v[184:187], v[208:211], v[72:75]
	v_mfma_f32_16x16x32_bf16 v[68:71], v[176:179], v[218:221], v[68:71]
	v_mfma_f32_16x16x32_bf16 v[64:67], v[184:187], v[218:221], v[64:67]
	s_barrier
; #define PG8_STAGE(bufoff, gbase, voff) do { _Pragma("unroll") for (int _i = 0; _i < 2; ++_i) \
;         __builtin_amdgcn_global_load_lds((const unsigned*)((const char*)(gbase) + (voff)[_i]), (PG8_LAS unsigned*)(lds + (bufoff) + ldsw + _i * 8192), 16, 0, 0); } while (0)
; #define PG8_LDA(dst, b, h) do { _Pragma("unroll") for (int m = 0; m < 4; ++m) _Pragma("unroll") for (int k = 0; k < 2; ++k) dst[m][k] = *(const PG8_LAS bf16x8*)(lds + PG8_SA(b, h) + aoff + m * 2048 + k * 1024); } while (0)
; #define PG8_MMA(ai, bj, At, Bt) do { __builtin_amdgcn_s_setprio(1); _Pragma("unroll") for (int m = 0; m < 4; ++m) _Pragma("unroll") for (int n = 0; n < 2; ++n) _Pragma("unroll") for (int k = 0; k < 2; ++k) \
;         acc[ai][bj][m][n] = __builtin_amdgcn_mfma_f32_16x16x32_bf16(Bt[n][k], At[m][k], acc[ai][bj][m][n], 0, 0, 0); __builtin_amdgcn_s_setprio(0); } while (0)
; #define PG8_WAIT_V(n) asm volatile("s_waitcnt vmcnt(" #n ")" ::: "memory")
; #define PG8_WAIT_L(n) asm volatile("s_waitcnt lgkmcnt(" #n ")" ::: "memory")
; #define PG8_BAR __builtin_amdgcn_s_barrier()
; #define PG8_SCHED __builtin_amdgcn_sched_barrier(0)
; template <class Epi, class Sched, bool ALIGN_EPI = false, bool SP2 = false>
; __device__ __forceinline__ void gemm_phase(PG8_LAS unsigned char* lds, const Gemm g, const Sched& S, const Epi& E) {
;     ...
;         for (int t = 0; t < nt; t += 2) {
;             const bool last = (t == nt - 2);
;             const char* a1 = cA + (size_t)(t + 1) * kstep;
;             const char* a2 = last ? nA : cA + (size_t)(t + 2) * kstep; const char* b2 = last ? nB : cB + (size_t)(t + 2) * kstep;
;     ...
;             PG8_LDA(At, 1, 1); PG8_STAGE(PG8_SB(1, 0), b3, voffB); PG8_STAGE(PG8_SB(1, 1), b3 + hstep, voffB); PG8_STAGE(PG8_SA(1, 0), a3, voffA);
;             PG8_WAIT_V(8); PG8_WAIT_L(0); PG8_BAR; PG8_MMA(1, 0, At, B0); PG8_MMA(1, 1, At, B1); PG8_BAR; PG8_SCHED;
	s_setprio 0
	s_add_i32 s67, s67, s3
	v_lshl_add_u64 v[160:161], v[160:161], 0, s[10:11]
	s_mov_b32 m0, s67
	ds_read_b128 v[188:191], v168 offset:49152
	ds_read_b128 v[192:195], v168 offset:50176
	ds_read_b128 v[196:199], v168 offset:51200
	ds_read_b128 v[200:203], v168 offset:52224
	ds_read_b128 v[204:207], v168 offset:53248
	ds_read_b128 v[208:211], v168 offset:54272
	ds_read_b128 v[212:215], v168 offset:55296
	ds_read_b128 v[218:221], v168 offset:56320
	global_load_lds_dwordx4 v[160:161], off
	s_add_i32 m0, s67, 0x2000
	s_add_u32 s74, s82, 0x80080
	v_lshl_add_u64 v[160:161], v[224:225], 0, s[10:11]
	s_addc_u32 s75, s83, 0
	s_add_i32 s67, s76, s3
	global_load_lds_dwordx4 v[160:161], off
	v_lshl_add_u64 v[160:161], s[74:75], 0, v[132:133]
	s_mov_b32 m0, s67
	s_nop 0
	global_load_lds_dwordx4 v[160:161], off
	v_lshl_add_u64 v[160:161], s[74:75], 0, v[128:129]
	s_add_i32 m0, s67, 0x2000
	s_nop 0
	global_load_lds_dwordx4 v[160:161], off
	v_lshl_add_u64 v[160:161], v[226:227], 0, s[10:11]
	s_mov_b32 m0, s68
	s_nop 0
	global_load_lds_dwordx4 v[160:161], off
	v_lshl_add_u64 v[160:161], v[228:229], 0, s[10:11]
	s_mov_b32 m0, s69
	s_nop 0
	global_load_lds_dwordx4 v[160:161], off
	s_waitcnt vmcnt(8)
	s_waitcnt lgkmcnt(0)
	s_setprio 1
	s_barrier
	v_mfma_f32_16x16x32_bf16 v[60:63], v[144:147], v[188:191], v[60:63]
	v_mfma_f32_16x16x32_bf16 v[56:59], v[152:155], v[188:191], v[56:59]
	v_mfma_f32_16x16x32_bf16 v[52:55], v[144:147], v[196:199], v[52:55]
	v_mfma_f32_16x16x32_bf16 v[44:47], v[152:155], v[196:199], v[44:47]
	v_mfma_f32_16x16x32_bf16 v[36:39], v[144:147], v[204:207], v[36:39]
	v_mfma_f32_16x16x32_bf16 v[28:31], v[152:155], v[204:207], v[28:31]
	v_mfma_f32_16x16x32_bf16 v[20:23], v[144:147], v[212:215], v[20:23]
	v_mfma_f32_16x16x32_bf16 v[12:15], v[152:155], v[212:215], v[12:15]
	v_mfma_f32_16x16x32_bf16 v[60:63], v[148:151], v[192:195], v[60:63]
	v_mfma_f32_16x16x32_bf16 v[56:59], v[156:159], v[192:195], v[56:59]
	v_mfma_f32_16x16x32_bf16 v[52:55], v[148:151], v[200:203], v[52:55]
	v_mfma_f32_16x16x32_bf16 v[44:47], v[156:159], v[200:203], v[44:47]
	v_mfma_f32_16x16x32_bf16 v[36:39], v[148:151], v[208:211], v[36:39]
	v_mfma_f32_16x16x32_bf16 v[28:31], v[156:159], v[208:211], v[28:31]
	v_mfma_f32_16x16x32_bf16 v[20:23], v[148:151], v[218:221], v[20:23]
	v_mfma_f32_16x16x32_bf16 v[12:15], v[156:159], v[218:221], v[12:15]
	v_mfma_f32_16x16x32_bf16 v[48:51], v[172:175], v[188:191], v[48:51]
	v_mfma_f32_16x16x32_bf16 v[40:43], v[180:183], v[188:191], v[40:43]
	v_mfma_f32_16x16x32_bf16 v[32:35], v[172:175], v[196:199], v[32:35]
	v_mfma_f32_16x16x32_bf16 v[24:27], v[180:183], v[196:199], v[24:27]
	v_mfma_f32_16x16x32_bf16 v[16:19], v[172:175], v[204:207], v[16:19]
	v_mfma_f32_16x16x32_bf16 v[8:11], v[180:183], v[204:207], v[8:11]
	v_mfma_f32_16x16x32_bf16 v[4:7], v[172:175], v[212:215], v[4:7]
	v_mfma_f32_16x16x32_bf16 v[0:3], v[180:183], v[212:215], v[0:3]
	v_mfma_f32_16x16x32_bf16 v[48:51], v[176:179], v[192:195], v[48:51]
	v_mfma_f32_16x16x32_bf16 v[40:43], v[184:187], v[192:195], v[40:43]
	v_mfma_f32_16x16x32_bf16 v[32:35], v[176:179], v[200:203], v[32:35]
	v_mfma_f32_16x16x32_bf16 v[24:27], v[184:187], v[200:203], v[24:27]
	v_mfma_f32_16x16x32_bf16 v[16:19], v[176:179], v[208:211], v[16:19]
	v_mfma_f32_16x16x32_bf16 v[8:11], v[184:187], v[208:211], v[8:11]
	v_mfma_f32_16x16x32_bf16 v[4:7], v[176:179], v[218:221], v[4:7]
	v_mfma_f32_16x16x32_bf16 v[0:3], v[184:187], v[218:221], v[0:3]
	s_barrier
	s_setprio 0
	s_add_i32 s66, s66, 2
	s_add_u32 s92, s92, 0x100
	s_addc_u32 s93, s93, 0
	s_add_u32 s85, s85, 0x100
	s_addc_u32 s91, s91, 0
	s_cmp_gt_u32 s66, 29

; #define PG8_STAGE(bufoff, gbase, voff) do { _Pragma("unroll") for (int _i = 0; _i < 2; ++_i) \
;         __builtin_amdgcn_global_load_lds((const unsigned*)((const char*)(gbase) + (voff)[_i]), (PG8_LAS unsigned*)(lds + (bufoff) + ldsw + _i * 8192), 16, 0, 0); } while (0)
; #define PG8_LDA(dst, b, h) do { _Pragma("unroll") for (int m = 0; m < 4; ++m) _Pragma("unroll") for (int k = 0; k < 2; ++k) dst[m][k] = *(const PG8_LAS bf16x8*)(lds + PG8_SA(b, h) + aoff + m * 2048 + k * 1024); } while (0)
; #define PG8_LDB(dst, b, h) do { _Pragma("unroll") for (int n = 0; n < 2; ++n) _Pragma("unroll") for (int k = 0; k < 2; ++k) dst[n][k] = *(const PG8_LAS bf16x8*)(lds + PG8_SB(b, h) + boff + n * 2048 + k * 1024); } while (0)
; #define PG8_MMA(ai, bj, At, Bt) do { __builtin_amdgcn_s_setprio(1); _Pragma("unroll") for (int m = 0; m < 4; ++m) _Pragma("unroll") for (int n = 0; n < 2; ++n) _Pragma("unroll") for (int k = 0; k < 2; ++k) \
;         acc[ai][bj][m][n] = __builtin_amdgcn_mfma_f32_16x16x32_bf16(Bt[n][k], At[m][k], acc[ai][bj][m][n], 0, 0, 0); __builtin_amdgcn_s_setprio(0); } while (0)
; #define PG8_WAIT_V(n) asm volatile("s_waitcnt vmcnt(" #n ")" ::: "memory")
; template <class Epi, class Sched, bool ALIGN_EPI = false, bool SP2 = false>
; __device__ __forceinline__ void gemm_phase(PG8_LAS unsigned char* lds, const Gemm g, const Sched& S, const Epi& E) {
;     ...
;         const char* nA = has_next ? (const char*)g.A + (size_t)nxt.pm * tstep : cA; const char* nB = has_next ? (const char*)g.Bt + (size_t)nxt.pn * tstep : cB;
;         for (int t = 0; t < nt; t += 2) {
;             const bool last = (t == nt - 2);
;             const char* a1 = cA + (size_t)(t + 1) * kstep;
;             const char* a2 = last ? nA : cA + (size_t)(t + 2) * kstep; const char* b2 = last ? nB : cB + (size_t)(t + 2) * kstep;
;             const char* a3 = a2 + kstep; const char* b3 = b2 + kstep;
;             if (last && has_next) S.a_ready(nxt);
;             if constexpr (SP2) {
;             PG8_LDB(B0, 0, 0); PG8_LDB(B1, 0, 1); PG8_SCHED; PG8_LDA(At, 0, 0); PG8_STAGE(PG8_SA(1, 1), a1 + hstep, voffA);
;             PG8_WAIT_V(8); PG8_WAIT_L(0); PG8_BAR; PG8_MMA(0, 0, At, B0); PG8_MMA(0, 1, At, B1); PG8_BAR; PG8_SCHED;
;             PG8_LDA(At, 0, 1); PG8_STAGE(PG8_SB(0, 0), b2, voffB); PG8_STAGE(PG8_SB(0, 1), b2 + hstep, voffB); PG8_STAGE(PG8_SA(0, 0), a2, voffA);
.LBB0_780:
	s_ashr_i32 s29, s28, 31
	s_lshl_b64 s[12:13], s[28:29], 19
	s_add_u32 s30, s38, s12
	s_addc_u32 s31, s39, s13
	s_and_b64 s[12:13], s[6:7], exec
	s_cselect_b32 s12, s31, s47
	s_cselect_b32 s13, s30, s46
	s_ashr_i32 s21, s20, 31
	s_lshl_b64 s[42:43], s[20:21], 19
	v_readlane_b32 s50, v252, 4
	v_readlane_b32 s51, v252, 5
	s_add_u32 s42, s50, s42
	s_addc_u32 s43, s51, s43
	s_and_b64 s[50:51], s[6:7], exec
	s_cselect_b32 s21, s43, s49
	s_cselect_b32 s29, s42, s48
	s_add_u32 s46, s46, 0x40080
	s_addc_u32 s47, s47, 0
	s_add_u32 s71, s48, 0x100
	s_addc_u32 s72, s49, 0
	s_mov_b32 s66, -2
	ds_read_b128 v[144:147], v153
	ds_read_b128 v[156:159], v153 offset:1024
	ds_read_b128 v[160:163], v153 offset:2048
	ds_read_b128 v[164:167], v153 offset:3072
	ds_read_b128 v[168:171], v154
	ds_read_b128 v[172:175], v154 offset:1024
	ds_read_b128 v[176:179], v154 offset:2048
	ds_read_b128 v[180:183], v154 offset:3072
	s_add_u32 s48, s46, 0xfffc0080
	s_addc_u32 s49, s47, -1
	s_cmp_eq_u32 s66, 12
	s_cselect_b32 s51, s12, s49
	s_cselect_b32 s50, s13, s48
	s_cselect_b32 s49, s21, s72
	s_cselect_b32 s48, s29, s71
	v_lshl_add_u64 v[148:149], s[46:47], 0, v[136:137]
	s_add_i32 m0, s14, 0xc000
	ds_read_b128 v[184:187], v155
	ds_read_b128 v[188:191], v155 offset:1024
	ds_read_b128 v[192:195], v155 offset:2048
	ds_read_b128 v[196:199], v155 offset:3072
	ds_read_b128 v[200:203], v155 offset:4096
	ds_read_b128 v[204:207], v155 offset:5120
	ds_read_b128 v[208:211], v155 offset:6144
	ds_read_b128 v[212:215], v155 offset:7168
	global_load_lds_dwordx4 v[148:149], off
	v_lshl_add_u64 v[148:149], s[46:47], 0, v[138:139]
	s_add_i32 m0, s14, 0xe000
	s_nop 0
	global_load_lds_dwordx4 v[148:149], off
	s_waitcnt vmcnt(8)
	s_waitcnt lgkmcnt(0)
	s_setprio 1
	s_barrier
	v_mfma_f32_16x16x32_bf16 v[124:127], v[144:147], v[184:187], 0
	v_mfma_f32_16x16x32_bf16 v[120:123], v[160:163], v[184:187], 0
	v_mfma_f32_16x16x32_bf16 v[108:111], v[144:147], v[192:195], 0
	v_mfma_f32_16x16x32_bf16 v[104:107], v[160:163], v[192:195], 0
	v_mfma_f32_16x16x32_bf16 v[96:99], v[144:147], v[200:203], 0
	v_mfma_f32_16x16x32_bf16 v[88:91], v[160:163], v[200:203], 0
	v_mfma_f32_16x16x32_bf16 v[80:83], v[144:147], v[208:211], 0
	v_mfma_f32_16x16x32_bf16 v[72:75], v[160:163], v[208:211], 0
	v_mfma_f32_16x16x32_bf16 v[124:127], v[156:159], v[188:191], v[124:127]
	v_mfma_f32_16x16x32_bf16 v[120:123], v[164:167], v[188:191], v[120:123]
	v_mfma_f32_16x16x32_bf16 v[108:111], v[156:159], v[196:199], v[108:111]
	v_mfma_f32_16x16x32_bf16 v[104:107], v[164:167], v[196:199], v[104:107]
	v_mfma_f32_16x16x32_bf16 v[96:99], v[156:159], v[204:207], v[96:99]
	v_mfma_f32_16x16x32_bf16 v[88:91], v[164:167], v[204:207], v[88:91]
	v_mfma_f32_16x16x32_bf16 v[80:83], v[156:159], v[212:215], v[80:83]
	v_mfma_f32_16x16x32_bf16 v[72:75], v[164:167], v[212:215], v[72:75]
	v_mfma_f32_16x16x32_bf16 v[116:119], v[168:171], v[184:187], 0
	v_mfma_f32_16x16x32_bf16 v[112:115], v[176:179], v[184:187], 0
	v_mfma_f32_16x16x32_bf16 v[100:103], v[168:171], v[192:195], 0
	v_mfma_f32_16x16x32_bf16 v[92:95], v[176:179], v[192:195], 0
	v_mfma_f32_16x16x32_bf16 v[84:87], v[168:171], v[200:203], 0
	v_mfma_f32_16x16x32_bf16 v[76:79], v[176:179], v[200:203], 0
	v_mfma_f32_16x16x32_bf16 v[68:71], v[168:171], v[208:211], 0
	v_mfma_f32_16x16x32_bf16 v[64:67], v[176:179], v[208:211], 0
	v_mfma_f32_16x16x32_bf16 v[116:119], v[172:175], v[188:191], v[116:119]
	v_mfma_f32_16x16x32_bf16 v[112:115], v[180:183], v[188:191], v[112:115]
	v_mfma_f32_16x16x32_bf16 v[100:103], v[172:175], v[196:199], v[100:103]
	v_mfma_f32_16x16x32_bf16 v[92:95], v[180:183], v[196:199], v[92:95]
	v_mfma_f32_16x16x32_bf16 v[84:87], v[172:175], v[204:207], v[84:87]
	v_mfma_f32_16x16x32_bf16 v[76:79], v[180:183], v[204:207], v[76:79]
	v_mfma_f32_16x16x32_bf16 v[68:71], v[172:175], v[212:215], v[68:71]
	v_mfma_f32_16x16x32_bf16 v[64:67], v[180:183], v[212:215], v[64:67]
	s_barrier
	s_setprio 0
	s_add_i32 s67, s68, s3
	v_lshl_add_u64 v[148:149], s[48:49], 0, v[132:133]
	s_mov_b32 m0, s67
	ds_read_b128 v[184:187], v155 offset:16384
	ds_read_b128 v[188:191], v155 offset:17408
	ds_read_b128 v[192:195], v155 offset:18432
	ds_read_b128 v[196:199], v155 offset:19456
	ds_read_b128 v[200:203], v155 offset:20480
	ds_read_b128 v[204:207], v155 offset:21504
	ds_read_b128 v[208:211], v155 offset:22528
	ds_read_b128 v[212:215], v155 offset:23552
	global_load_lds_dwordx4 v[148:149], off
	s_add_i32 m0, s67, 0x2000
	s_add_u32 s74, s48, 0x40000
	v_lshl_add_u64 v[216:217], s[48:49], 0, v[128:129]
	s_addc_u32 s75, s49, 0
	s_add_i32 s67, s69, s3
	global_load_lds_dwordx4 v[216:217], off
	v_lshl_add_u64 v[218:219], s[74:75], 0, v[132:133]
	s_mov_b32 m0, s67
	v_lshl_add_u64 v[220:221], s[50:51], 0, v[130:131]
	global_load_lds_dwordx4 v[218:219], off
	v_lshl_add_u64 v[218:219], s[74:75], 0, v[128:129]
	s_add_i32 m0, s67, 0x2000
	s_nop 0
	global_load_lds_dwordx4 v[218:219], off
	v_lshl_add_u64 v[218:219], s[50:51], 0, v[134:135]
	s_mov_b32 m0, s14
	s_nop 0
	global_load_lds_dwordx4 v[218:219], off
	s_mov_b32 m0, s15
	s_nop 0
	global_load_lds_dwordx4 v[220:221], off
	s_waitcnt vmcnt(8)
	s_waitcnt lgkmcnt(0)
	s_setprio 1
	s_barrier
; #define PG8_STAGE(bufoff, gbase, voff) do { _Pragma("unroll") for (int _i = 0; _i < 2; ++_i) \
;         __builtin_amdgcn_global_load_lds((const unsigned*)((const char*)(gbase) + (voff)[_i]), (PG8_LAS unsigned*)(lds + (bufoff) + ldsw + _i * 8192), 16, 0, 0); } while (0)
; #define PG8_LDA(dst, b, h) do { _Pragma("unroll") for (int m = 0; m < 4; ++m) _Pragma("unroll") for (int k = 0; k < 2; ++k) dst[m][k] = *(const PG8_LAS bf16x8*)(lds + PG8_SA(b, h) + aoff + m * 2048 + k * 1024); } while (0)
; #define PG8_LDB(dst, b, h) do { _Pragma("unroll") for (int n = 0; n < 2; ++n) _Pragma("unroll") for (int k = 0; k < 2; ++k) dst[n][k] = *(const PG8_LAS bf16x8*)(lds + PG8_SB(b, h) + boff + n * 2048 + k * 1024); } while (0)
; #define PG8_MMA(ai, bj, At, Bt) do { __builtin_amdgcn_s_setprio(1); _Pragma("unroll") for (int m = 0; m < 4; ++m) _Pragma("unroll") for (int n = 0; n < 2; ++n) _Pragma("unroll") for (int k = 0; k < 2; ++k) \
;         acc[ai][bj][m][n] = __builtin_amdgcn_mfma_f32_16x16x32_bf16(Bt[n][k], At[m][k], acc[ai][bj][m][n], 0, 0, 0); __builtin_amdgcn_s_setprio(0); } while (0)
; #define PG8_WAIT_V(n) asm volatile("s_waitcnt vmcnt(" #n ")" ::: "memory")
; #define PG8_WAIT_L(n) asm volatile("s_waitcnt lgkmcnt(" #n ")" ::: "memory")
; #define PG8_BAR __builtin_amdgcn_s_barrier()
; #define PG8_SCHED __builtin_amdgcn_sched_barrier(0)
; template <class Epi, class Sched, bool ALIGN_EPI = false, bool SP2 = false>
; __device__ __forceinline__ void gemm_phase(PG8_LAS unsigned char* lds, const Gemm g, const Sched& S, const Epi& E) {
;     ...
;             PG8_WAIT_V(8); PG8_WAIT_L(0); PG8_BAR; PG8_MMA(1, 0, At, B0); PG8_MMA(1, 1, At, B1); PG8_BAR; PG8_SCHED;
;             PG8_LDB(B0, 1, 0); PG8_LDB(B1, 1, 1); PG8_SCHED; PG8_LDA(At, 1, 0); PG8_STAGE(PG8_SA(0, 1), a2 + hstep, voffA);
;             PG8_WAIT_V(8); PG8_WAIT_L(0); PG8_BAR; PG8_MMA(0, 0, At, B0); PG8_MMA(0, 1, At, B1); PG8_BAR; PG8_SCHED;
	v_mfma_f32_16x16x32_bf16 v[60:63], v[144:147], v[184:187], 0
	v_mfma_f32_16x16x32_bf16 v[56:59], v[160:163], v[184:187], 0
	v_mfma_f32_16x16x32_bf16 v[48:51], v[144:147], v[192:195], 0
	v_mfma_f32_16x16x32_bf16 v[40:43], v[160:163], v[192:195], 0
	v_mfma_f32_16x16x32_bf16 v[32:35], v[144:147], v[200:203], 0
	v_mfma_f32_16x16x32_bf16 v[24:27], v[160:163], v[200:203], 0
	v_mfma_f32_16x16x32_bf16 v[16:19], v[144:147], v[208:211], 0
	v_mfma_f32_16x16x32_bf16 v[8:11], v[160:163], v[208:211], 0
	v_mfma_f32_16x16x32_bf16 v[60:63], v[156:159], v[188:191], v[60:63]
	v_mfma_f32_16x16x32_bf16 v[56:59], v[164:167], v[188:191], v[56:59]
	v_mfma_f32_16x16x32_bf16 v[48:51], v[156:159], v[196:199], v[48:51]
	v_mfma_f32_16x16x32_bf16 v[40:43], v[164:167], v[196:199], v[40:43]
	v_mfma_f32_16x16x32_bf16 v[32:35], v[156:159], v[204:207], v[32:35]
	v_mfma_f32_16x16x32_bf16 v[24:27], v[164:167], v[204:207], v[24:27]
	v_mfma_f32_16x16x32_bf16 v[16:19], v[156:159], v[212:215], v[16:19]
	v_mfma_f32_16x16x32_bf16 v[8:11], v[164:167], v[212:215], v[8:11]
	v_mfma_f32_16x16x32_bf16 v[52:55], v[168:171], v[184:187], 0
	v_mfma_f32_16x16x32_bf16 v[44:47], v[176:179], v[184:187], 0
	v_mfma_f32_16x16x32_bf16 v[36:39], v[168:171], v[192:195], 0
	v_mfma_f32_16x16x32_bf16 v[28:31], v[176:179], v[192:195], 0
	v_mfma_f32_16x16x32_bf16 v[20:23], v[168:171], v[200:203], 0
	v_mfma_f32_16x16x32_bf16 v[12:15], v[176:179], v[200:203], 0
	v_mfma_f32_16x16x32_bf16 v[4:7], v[168:171], v[208:211], 0
	v_mfma_f32_16x16x32_bf16 v[0:3], v[176:179], v[208:211], 0
	v_mfma_f32_16x16x32_bf16 v[52:55], v[172:175], v[188:191], v[52:55]
	v_mfma_f32_16x16x32_bf16 v[44:47], v[180:183], v[188:191], v[44:47]
	v_mfma_f32_16x16x32_bf16 v[36:39], v[172:175], v[196:199], v[36:39]
	v_mfma_f32_16x16x32_bf16 v[28:31], v[180:183], v[196:199], v[28:31]
	v_mfma_f32_16x16x32_bf16 v[20:23], v[172:175], v[204:207], v[20:23]
	v_mfma_f32_16x16x32_bf16 v[12:15], v[180:183], v[204:207], v[12:15]
	v_mfma_f32_16x16x32_bf16 v[4:7], v[172:175], v[212:215], v[4:7]
	v_mfma_f32_16x16x32_bf16 v[0:3], v[180:183], v[212:215], v[0:3]
	s_barrier
	s_setprio 0
	s_add_i32 s67, 0, 0x18000
	s_add_i32 s74, 0, 0x1c000
	v_add_u32_e32 v164, s67, v151
	v_add_u32_e32 v180, s74, v151
	ds_read_b128 v[144:147], v164
	ds_read_b128 v[156:159], v164 offset:1024
	ds_read_b128 v[160:163], v164 offset:2048
	ds_read_b128 v[164:167], v164 offset:3072
	ds_read_b128 v[168:171], v180
	ds_read_b128 v[172:175], v180 offset:1024
	ds_read_b128 v[176:179], v180 offset:2048
	ds_read_b128 v[180:183], v180 offset:3072
	s_add_u32 s50, s50, 0x40000
	s_addc_u32 s51, s51, 0
	s_mov_b32 m0, s22
	v_lshl_add_u64 v[226:227], s[50:51], 0, v[134:135]
	ds_read_b128 v[184:187], v155 offset:32768
	ds_read_b128 v[188:191], v155 offset:33792
	ds_read_b128 v[192:195], v155 offset:34816
	ds_read_b128 v[196:199], v155 offset:35840
	ds_read_b128 v[200:203], v155 offset:36864
	ds_read_b128 v[204:207], v155 offset:37888
	ds_read_b128 v[208:211], v155 offset:38912
	ds_read_b128 v[212:215], v155 offset:39936
	global_load_lds_dwordx4 v[226:227], off
	v_lshl_add_u64 v[226:227], s[50:51], 0, v[130:131]
	s_mov_b32 m0, s23
	s_nop 0
	global_load_lds_dwordx4 v[226:227], off
	s_waitcnt vmcnt(8)
	s_waitcnt lgkmcnt(0)
	s_setprio 1
	s_barrier
	v_mfma_f32_16x16x32_bf16 v[124:127], v[144:147], v[184:187], v[124:127]
	v_mfma_f32_16x16x32_bf16 v[120:123], v[160:163], v[184:187], v[120:123]
	v_mfma_f32_16x16x32_bf16 v[108:111], v[144:147], v[192:195], v[108:111]
	v_mfma_f32_16x16x32_bf16 v[104:107], v[160:163], v[192:195], v[104:107]
	v_mfma_f32_16x16x32_bf16 v[96:99], v[144:147], v[200:203], v[96:99]
	v_mfma_f32_16x16x32_bf16 v[88:91], v[160:163], v[200:203], v[88:91]
	v_mfma_f32_16x16x32_bf16 v[80:83], v[144:147], v[208:211], v[80:83]
	v_mfma_f32_16x16x32_bf16 v[72:75], v[160:163], v[208:211], v[72:75]
	v_mfma_f32_16x16x32_bf16 v[124:127], v[156:159], v[188:191], v[124:127]
	v_mfma_f32_16x16x32_bf16 v[120:123], v[164:167], v[188:191], v[120:123]
	v_mfma_f32_16x16x32_bf16 v[108:111], v[156:159], v[196:199], v[108:111]
	v_mfma_f32_16x16x32_bf16 v[104:107], v[164:167], v[196:199], v[104:107]
	v_mfma_f32_16x16x32_bf16 v[96:99], v[156:159], v[204:207], v[96:99]
	v_mfma_f32_16x16x32_bf16 v[88:91], v[164:167], v[204:207], v[88:91]
	v_mfma_f32_16x16x32_bf16 v[80:83], v[156:159], v[212:215], v[80:83]
	v_mfma_f32_16x16x32_bf16 v[72:75], v[164:167], v[212:215], v[72:75]
	v_mfma_f32_16x16x32_bf16 v[116:119], v[168:171], v[184:187], v[116:119]
	v_mfma_f32_16x16x32_bf16 v[112:115], v[176:179], v[184:187], v[112:115]
	v_mfma_f32_16x16x32_bf16 v[100:103], v[168:171], v[192:195], v[100:103]
	v_mfma_f32_16x16x32_bf16 v[92:95], v[176:179], v[192:195], v[92:95]
	v_mfma_f32_16x16x32_bf16 v[84:87], v[168:171], v[200:203], v[84:87]
	v_mfma_f32_16x16x32_bf16 v[76:79], v[176:179], v[200:203], v[76:79]
	v_mfma_f32_16x16x32_bf16 v[68:71], v[168:171], v[208:211], v[68:71]
	v_mfma_f32_16x16x32_bf16 v[64:67], v[176:179], v[208:211], v[64:67]
	v_mfma_f32_16x16x32_bf16 v[116:119], v[172:175], v[188:191], v[116:119]
	v_mfma_f32_16x16x32_bf16 v[112:115], v[180:183], v[188:191], v[112:115]
	v_mfma_f32_16x16x32_bf16 v[100:103], v[172:175], v[196:199], v[100:103]
	v_mfma_f32_16x16x32_bf16 v[92:95], v[180:183], v[196:199], v[92:95]
	v_mfma_f32_16x16x32_bf16 v[84:87], v[172:175], v[204:207], v[84:87]
	v_mfma_f32_16x16x32_bf16 v[76:79], v[180:183], v[204:207], v[76:79]
	v_mfma_f32_16x16x32_bf16 v[68:71], v[172:175], v[212:215], v[68:71]
	v_mfma_f32_16x16x32_bf16 v[64:67], v[180:183], v[212:215], v[64:67]
	s_barrier
; #define PG8_STAGE(bufoff, gbase, voff) do { _Pragma("unroll") for (int _i = 0; _i < 2; ++_i) \
;         __builtin_amdgcn_global_load_lds((const unsigned*)((const char*)(gbase) + (voff)[_i]), (PG8_LAS unsigned*)(lds + (bufoff) + ldsw + _i * 8192), 16, 0, 0); } while (0)
; #define PG8_LDA(dst, b, h) do { _Pragma("unroll") for (int m = 0; m < 4; ++m) _Pragma("unroll") for (int k = 0; k < 2; ++k) dst[m][k] = *(const PG8_LAS bf16x8*)(lds + PG8_SA(b, h) + aoff + m * 2048 + k * 1024); } while (0)
; #define PG8_MMA(ai, bj, At, Bt) do { __builtin_amdgcn_s_setprio(1); _Pragma("unroll") for (int m = 0; m < 4; ++m) _Pragma("unroll") for (int n = 0; n < 2; ++n) _Pragma("unroll") for (int k = 0; k < 2; ++k) \
;         acc[ai][bj][m][n] = __builtin_amdgcn_mfma_f32_16x16x32_bf16(Bt[n][k], At[m][k], acc[ai][bj][m][n], 0, 0, 0); __builtin_amdgcn_s_setprio(0); } while (0)
; #define PG8_WAIT_V(n) asm volatile("s_waitcnt vmcnt(" #n ")" ::: "memory")
; #define PG8_WAIT_L(n) asm volatile("s_waitcnt lgkmcnt(" #n ")" ::: "memory")
; #define PG8_BAR __builtin_amdgcn_s_barrier()
; #define PG8_SCHED __builtin_amdgcn_sched_barrier(0)
; template <class Epi, class Sched, bool ALIGN_EPI = false, bool SP2 = false>
; __device__ __forceinline__ void gemm_phase(PG8_LAS unsigned char* lds, const Gemm g, const Sched& S, const Epi& E) {
;     ...
;         for (int t = 0; t < nt; t += 2) {
;             const bool last = (t == nt - 2);
;             const char* a1 = cA + (size_t)(t + 1) * kstep;
;             const char* a2 = last ? nA : cA + (size_t)(t + 2) * kstep; const char* b2 = last ? nB : cB + (size_t)(t + 2) * kstep;
;     ...
;             PG8_LDA(At, 1, 1); PG8_STAGE(PG8_SB(1, 0), b3, voffB); PG8_STAGE(PG8_SB(1, 1), b3 + hstep, voffB); PG8_STAGE(PG8_SA(1, 0), a3, voffA);
;             PG8_WAIT_V(8); PG8_WAIT_L(0); PG8_BAR; PG8_MMA(1, 0, At, B0); PG8_MMA(1, 1, At, B1); PG8_BAR; PG8_SCHED;
	s_setprio 0
	s_add_i32 s50, s67, s3
	v_lshl_add_u64 v[148:149], v[148:149], 0, s[16:17]
	s_mov_b32 m0, s50
	ds_read_b128 v[184:187], v155 offset:49152
	ds_read_b128 v[188:191], v155 offset:50176
	ds_read_b128 v[192:195], v155 offset:51200
	ds_read_b128 v[196:199], v155 offset:52224
	ds_read_b128 v[200:203], v155 offset:53248
	ds_read_b128 v[204:207], v155 offset:54272
	ds_read_b128 v[208:211], v155 offset:55296
	ds_read_b128 v[212:215], v155 offset:56320
	global_load_lds_dwordx4 v[148:149], off
	s_add_i32 m0, s50, 0x2000
	s_add_u32 s48, s48, 0x40080
	v_lshl_add_u64 v[148:149], v[216:217], 0, s[16:17]
	s_addc_u32 s49, s49, 0
	s_add_i32 s50, s74, s3
	global_load_lds_dwordx4 v[148:149], off
	v_lshl_add_u64 v[148:149], s[48:49], 0, v[132:133]
	s_mov_b32 m0, s50
	s_nop 0
	global_load_lds_dwordx4 v[148:149], off
	v_lshl_add_u64 v[148:149], s[48:49], 0, v[128:129]
	s_add_i32 m0, s50, 0x2000
	s_nop 0
	global_load_lds_dwordx4 v[148:149], off
	v_lshl_add_u64 v[148:149], v[218:219], 0, s[16:17]
	s_mov_b32 m0, s35
	s_nop 0
	global_load_lds_dwordx4 v[148:149], off
	v_lshl_add_u64 v[148:149], v[220:221], 0, s[16:17]
	s_mov_b32 m0, s45
	s_nop 0
	global_load_lds_dwordx4 v[148:149], off
	s_waitcnt vmcnt(8)
	s_waitcnt lgkmcnt(0)
	s_setprio 1
	s_barrier
	v_mfma_f32_16x16x32_bf16 v[60:63], v[144:147], v[184:187], v[60:63]
	v_mfma_f32_16x16x32_bf16 v[56:59], v[160:163], v[184:187], v[56:59]
	v_mfma_f32_16x16x32_bf16 v[48:51], v[144:147], v[192:195], v[48:51]
	v_mfma_f32_16x16x32_bf16 v[40:43], v[160:163], v[192:195], v[40:43]
	v_mfma_f32_16x16x32_bf16 v[32:35], v[144:147], v[200:203], v[32:35]
	v_mfma_f32_16x16x32_bf16 v[24:27], v[160:163], v[200:203], v[24:27]
	v_mfma_f32_16x16x32_bf16 v[16:19], v[144:147], v[208:211], v[16:19]
	v_mfma_f32_16x16x32_bf16 v[8:11], v[160:163], v[208:211], v[8:11]
	v_mfma_f32_16x16x32_bf16 v[60:63], v[156:159], v[188:191], v[60:63]
	v_mfma_f32_16x16x32_bf16 v[56:59], v[164:167], v[188:191], v[56:59]
	v_mfma_f32_16x16x32_bf16 v[48:51], v[156:159], v[196:199], v[48:51]
	v_mfma_f32_16x16x32_bf16 v[40:43], v[164:167], v[196:199], v[40:43]
	v_mfma_f32_16x16x32_bf16 v[32:35], v[156:159], v[204:207], v[32:35]
	v_mfma_f32_16x16x32_bf16 v[24:27], v[164:167], v[204:207], v[24:27]
	v_mfma_f32_16x16x32_bf16 v[16:19], v[156:159], v[212:215], v[16:19]
	v_mfma_f32_16x16x32_bf16 v[8:11], v[164:167], v[212:215], v[8:11]
	v_mfma_f32_16x16x32_bf16 v[52:55], v[168:171], v[184:187], v[52:55]
	v_mfma_f32_16x16x32_bf16 v[44:47], v[176:179], v[184:187], v[44:47]
	v_mfma_f32_16x16x32_bf16 v[36:39], v[168:171], v[192:195], v[36:39]
	v_mfma_f32_16x16x32_bf16 v[28:31], v[176:179], v[192:195], v[28:31]
	v_mfma_f32_16x16x32_bf16 v[20:23], v[168:171], v[200:203], v[20:23]
	v_mfma_f32_16x16x32_bf16 v[12:15], v[176:179], v[200:203], v[12:15]
	v_mfma_f32_16x16x32_bf16 v[4:7], v[168:171], v[208:211], v[4:7]
	v_mfma_f32_16x16x32_bf16 v[0:3], v[176:179], v[208:211], v[0:3]
	v_mfma_f32_16x16x32_bf16 v[52:55], v[172:175], v[188:191], v[52:55]
	v_mfma_f32_16x16x32_bf16 v[44:47], v[180:183], v[188:191], v[44:47]
	v_mfma_f32_16x16x32_bf16 v[36:39], v[172:175], v[196:199], v[36:39]
	v_mfma_f32_16x16x32_bf16 v[28:31], v[180:183], v[196:199], v[28:31]
	v_mfma_f32_16x16x32_bf16 v[20:23], v[172:175], v[204:207], v[20:23]
	v_mfma_f32_16x16x32_bf16 v[12:15], v[180:183], v[204:207], v[12:15]
	v_mfma_f32_16x16x32_bf16 v[4:7], v[172:175], v[212:215], v[4:7]
	v_mfma_f32_16x16x32_bf16 v[0:3], v[180:183], v[212:215], v[0:3]
	s_barrier
	s_setprio 0
	s_add_i32 s66, s66, 2
	s_add_u32 s46, s46, 0x100
	s_addc_u32 s47, s47, 0
	s_add_u32 s71, s71, 0x100
	s_addc_u32 s72, s72, 0
	s_cmp_gt_u32 s66, 13

; #define PG8_STAGE(bufoff, gbase, voff) do { _Pragma("unroll") for (int _i = 0; _i < 2; ++_i) \
;         __builtin_amdgcn_global_load_lds((const unsigned*)((const char*)(gbase) + (voff)[_i]), (PG8_LAS unsigned*)(lds + (bufoff) + ldsw + _i * 8192), 16, 0, 0); } while (0)
; #define PG8_LDA(dst, b, h) do { _Pragma("unroll") for (int m = 0; m < 4; ++m) _Pragma("unroll") for (int k = 0; k < 2; ++k) dst[m][k] = *(const PG8_LAS bf16x8*)(lds + PG8_SA(b, h) + aoff + m * 2048 + k * 1024); } while (0)
; #define PG8_LDB(dst, b, h) do { _Pragma("unroll") for (int n = 0; n < 2; ++n) _Pragma("unroll") for (int k = 0; k < 2; ++k) dst[n][k] = *(const PG8_LAS bf16x8*)(lds + PG8_SB(b, h) + boff + n * 2048 + k * 1024); } while (0)
; #define PG8_MMA(ai, bj, At, Bt) do { __builtin_amdgcn_s_setprio(1); _Pragma("unroll") for (int m = 0; m < 4; ++m) _Pragma("unroll") for (int n = 0; n < 2; ++n) _Pragma("unroll") for (int k = 0; k < 2; ++k) \
;         acc[ai][bj][m][n] = __builtin_amdgcn_mfma_f32_16x16x32_bf16(Bt[n][k], At[m][k], acc[ai][bj][m][n], 0, 0, 0); __builtin_amdgcn_s_setprio(0); } while (0)
; #define PG8_WAIT_V(n) asm volatile("s_waitcnt vmcnt(" #n ")" ::: "memory")
; template <class Epi, class Sched, bool ALIGN_EPI = false, bool SP2 = false>
; __device__ __forceinline__ void gemm_phase(PG8_LAS unsigned char* lds, const Gemm g, const Sched& S, const Epi& E) {
;     ...
;         const char* nA = has_next ? (const char*)g.A + (size_t)nxt.pm * tstep : cA; const char* nB = has_next ? (const char*)g.Bt + (size_t)nxt.pn * tstep : cB;
;         for (int t = 0; t < nt; t += 2) {
;             const bool last = (t == nt - 2);
;             const char* a1 = cA + (size_t)(t + 1) * kstep;
;             const char* a2 = last ? nA : cA + (size_t)(t + 2) * kstep; const char* b2 = last ? nB : cB + (size_t)(t + 2) * kstep;
;             const char* a3 = a2 + kstep; const char* b3 = b2 + kstep;
;             if (last && has_next) S.a_ready(nxt);
;             if constexpr (SP2) {
;             PG8_LDB(B0, 0, 0); PG8_LDB(B1, 0, 1); PG8_SCHED; PG8_LDA(At, 0, 0); PG8_STAGE(PG8_SA(1, 1), a1 + hstep, voffA);
;             PG8_WAIT_V(8); PG8_WAIT_L(0); PG8_BAR; PG8_MMA(0, 0, At, B0); PG8_MMA(0, 1, At, B1); PG8_BAR; PG8_SCHED;
;             PG8_LDA(At, 0, 1); PG8_STAGE(PG8_SB(0, 0), b2, voffB); PG8_STAGE(PG8_SB(0, 1), b2 + hstep, voffB); PG8_STAGE(PG8_SA(0, 0), a2, voffA);
.LBB0_800:
	s_ashr_i32 s29, s28, 31
	s_lshl_b64 s[12:13], s[28:29], 19
	s_add_u32 s30, s8, s12
	s_addc_u32 s31, s9, s13
	s_and_b64 s[12:13], s[6:7], exec
	s_cselect_b32 s12, s31, s47
	s_cselect_b32 s13, s30, s46
	s_ashr_i32 s21, s20, 31
	s_lshl_b64 s[42:43], s[20:21], 19
	v_readlane_b32 s50, v252, 6
	v_readlane_b32 s51, v252, 7
	s_add_u32 s42, s50, s42
	s_addc_u32 s43, s51, s43
	s_and_b64 s[50:51], s[6:7], exec
	s_cselect_b32 s21, s43, s49
	s_cselect_b32 s29, s42, s48
	s_add_u32 s46, s46, 0x40080
	s_addc_u32 s47, s47, 0
	s_add_u32 s71, s48, 0x100
	s_addc_u32 s72, s49, 0
	s_mov_b32 s66, -2
	ds_read_b128 v[128:131], v179
	ds_read_b128 v[132:135], v179 offset:1024
	ds_read_b128 v[136:139], v179 offset:2048
	ds_read_b128 v[140:143], v179 offset:3072
	ds_read_b128 v[144:147], v180
	ds_read_b128 v[148:151], v180 offset:1024
	ds_read_b128 v[168:171], v180 offset:2048
	ds_read_b128 v[172:175], v180 offset:3072
	s_add_u32 s48, s46, 0xfffc0080
	s_addc_u32 s49, s47, -1
	s_cmp_eq_u32 s66, 12
	s_cselect_b32 s51, s12, s49
	s_cselect_b32 s50, s13, s48
	s_cselect_b32 s49, s21, s72
	s_cselect_b32 s48, s29, s71
	v_lshl_add_u64 v[214:215], s[46:47], 0, v[160:161]
	s_add_i32 m0, s14, 0xc000
	ds_read_b128 v[182:185], v181
	ds_read_b128 v[186:189], v181 offset:1024
	ds_read_b128 v[190:193], v181 offset:2048
	ds_read_b128 v[194:197], v181 offset:3072
	ds_read_b128 v[198:201], v181 offset:4096
	ds_read_b128 v[202:205], v181 offset:5120
	ds_read_b128 v[206:209], v181 offset:6144
	ds_read_b128 v[210:213], v181 offset:7168
	global_load_lds_dwordx4 v[214:215], off
	v_lshl_add_u64 v[214:215], s[46:47], 0, v[162:163]
	s_add_i32 m0, s14, 0xe000
	s_nop 0
	global_load_lds_dwordx4 v[214:215], off
	s_waitcnt vmcnt(8)
	s_waitcnt lgkmcnt(0)
	s_setprio 1
	s_barrier
	v_mfma_f32_16x16x32_bf16 v[124:127], v[128:131], v[182:185], 0
	v_mfma_f32_16x16x32_bf16 v[120:123], v[136:139], v[182:185], 0
	v_mfma_f32_16x16x32_bf16 v[108:111], v[128:131], v[190:193], 0
	v_mfma_f32_16x16x32_bf16 v[104:107], v[136:139], v[190:193], 0
	v_mfma_f32_16x16x32_bf16 v[92:95], v[128:131], v[198:201], 0
	v_mfma_f32_16x16x32_bf16 v[88:91], v[136:139], v[198:201], 0
	v_mfma_f32_16x16x32_bf16 v[76:79], v[128:131], v[206:209], 0
	v_mfma_f32_16x16x32_bf16 v[72:75], v[136:139], v[206:209], 0
	v_mfma_f32_16x16x32_bf16 v[124:127], v[132:135], v[186:189], v[124:127]
	v_mfma_f32_16x16x32_bf16 v[120:123], v[140:143], v[186:189], v[120:123]
	v_mfma_f32_16x16x32_bf16 v[108:111], v[132:135], v[194:197], v[108:111]
	v_mfma_f32_16x16x32_bf16 v[104:107], v[140:143], v[194:197], v[104:107]
	v_mfma_f32_16x16x32_bf16 v[92:95], v[132:135], v[202:205], v[92:95]
	v_mfma_f32_16x16x32_bf16 v[88:91], v[140:143], v[202:205], v[88:91]
	v_mfma_f32_16x16x32_bf16 v[76:79], v[132:135], v[210:213], v[76:79]
	v_mfma_f32_16x16x32_bf16 v[72:75], v[140:143], v[210:213], v[72:75]
	v_mfma_f32_16x16x32_bf16 v[116:119], v[144:147], v[182:185], 0
	v_mfma_f32_16x16x32_bf16 v[112:115], v[168:171], v[182:185], 0
	v_mfma_f32_16x16x32_bf16 v[100:103], v[144:147], v[190:193], 0
	v_mfma_f32_16x16x32_bf16 v[96:99], v[168:171], v[190:193], 0
	v_mfma_f32_16x16x32_bf16 v[84:87], v[144:147], v[198:201], 0
	v_mfma_f32_16x16x32_bf16 v[80:83], v[168:171], v[198:201], 0
	v_mfma_f32_16x16x32_bf16 v[68:71], v[144:147], v[206:209], 0
	v_mfma_f32_16x16x32_bf16 v[64:67], v[168:171], v[206:209], 0
	v_mfma_f32_16x16x32_bf16 v[116:119], v[148:151], v[186:189], v[116:119]
	v_mfma_f32_16x16x32_bf16 v[112:115], v[172:175], v[186:189], v[112:115]
	v_mfma_f32_16x16x32_bf16 v[100:103], v[148:151], v[194:197], v[100:103]
	v_mfma_f32_16x16x32_bf16 v[96:99], v[172:175], v[194:197], v[96:99]
	v_mfma_f32_16x16x32_bf16 v[84:87], v[148:151], v[202:205], v[84:87]
	v_mfma_f32_16x16x32_bf16 v[80:83], v[172:175], v[202:205], v[80:83]
	v_mfma_f32_16x16x32_bf16 v[68:71], v[148:151], v[210:213], v[68:71]
	v_mfma_f32_16x16x32_bf16 v[64:67], v[172:175], v[210:213], v[64:67]
	s_barrier
	s_setprio 0
	s_add_i32 s67, s68, s3
	v_lshl_add_u64 v[214:215], s[48:49], 0, v[156:157]
	s_mov_b32 m0, s67
	ds_read_b128 v[182:185], v181 offset:16384
	ds_read_b128 v[186:189], v181 offset:17408
	ds_read_b128 v[190:193], v181 offset:18432
	ds_read_b128 v[194:197], v181 offset:19456
	ds_read_b128 v[198:201], v181 offset:20480
	ds_read_b128 v[202:205], v181 offset:21504
	ds_read_b128 v[206:209], v181 offset:22528
	ds_read_b128 v[210:213], v181 offset:23552
	global_load_lds_dwordx4 v[214:215], off
	s_add_i32 m0, s67, 0x2000
	s_add_u32 s74, s48, 0x40000
	v_lshl_add_u64 v[216:217], s[48:49], 0, v[152:153]
	s_addc_u32 s75, s49, 0
	s_add_i32 s67, s69, s3
	global_load_lds_dwordx4 v[216:217], off
	v_lshl_add_u64 v[218:219], s[74:75], 0, v[156:157]
	s_mov_b32 m0, s67
	v_lshl_add_u64 v[220:221], s[50:51], 0, v[154:155]
	global_load_lds_dwordx4 v[218:219], off
	v_lshl_add_u64 v[218:219], s[74:75], 0, v[152:153]
	s_add_i32 m0, s67, 0x2000
	s_nop 0
	global_load_lds_dwordx4 v[218:219], off
	v_lshl_add_u64 v[218:219], s[50:51], 0, v[158:159]
	s_mov_b32 m0, s14
	s_nop 0
	global_load_lds_dwordx4 v[218:219], off
	s_mov_b32 m0, s15
	s_nop 0
	global_load_lds_dwordx4 v[220:221], off
	s_waitcnt vmcnt(8)
	s_waitcnt lgkmcnt(0)
	s_setprio 1
	s_barrier
; #define PG8_STAGE(bufoff, gbase, voff) do { _Pragma("unroll") for (int _i = 0; _i < 2; ++_i) \
;         __builtin_amdgcn_global_load_lds((const unsigned*)((const char*)(gbase) + (voff)[_i]), (PG8_LAS unsigned*)(lds + (bufoff) + ldsw + _i * 8192), 16, 0, 0); } while (0)
; #define PG8_LDA(dst, b, h) do { _Pragma("unroll") for (int m = 0; m < 4; ++m) _Pragma("unroll") for (int k = 0; k < 2; ++k) dst[m][k] = *(const PG8_LAS bf16x8*)(lds + PG8_SA(b, h) + aoff + m * 2048 + k * 1024); } while (0)
; #define PG8_LDB(dst, b, h) do { _Pragma("unroll") for (int n = 0; n < 2; ++n) _Pragma("unroll") for (int k = 0; k < 2; ++k) dst[n][k] = *(const PG8_LAS bf16x8*)(lds + PG8_SB(b, h) + boff + n * 2048 + k * 1024); } while (0)
; #define PG8_MMA(ai, bj, At, Bt) do { __builtin_amdgcn_s_setprio(1); _Pragma("unroll") for (int m = 0; m < 4; ++m) _Pragma("unroll") for (int n = 0; n < 2; ++n) _Pragma("unroll") for (int k = 0; k < 2; ++k) \
;         acc[ai][bj][m][n] = __builtin_amdgcn_mfma_f32_16x16x32_bf16(Bt[n][k], At[m][k], acc[ai][bj][m][n], 0, 0, 0); __builtin_amdgcn_s_setprio(0); } while (0)
; #define PG8_WAIT_V(n) asm volatile("s_waitcnt vmcnt(" #n ")" ::: "memory")
; #define PG8_WAIT_L(n) asm volatile("s_waitcnt lgkmcnt(" #n ")" ::: "memory")
; #define PG8_BAR __builtin_amdgcn_s_barrier()
; #define PG8_SCHED __builtin_amdgcn_sched_barrier(0)
; template <class Epi, class Sched, bool ALIGN_EPI = false, bool SP2 = false>
; __device__ __forceinline__ void gemm_phase(PG8_LAS unsigned char* lds, const Gemm g, const Sched& S, const Epi& E) {
;     ...
;             PG8_WAIT_V(8); PG8_WAIT_L(0); PG8_BAR; PG8_MMA(1, 0, At, B0); PG8_MMA(1, 1, At, B1); PG8_BAR; PG8_SCHED;
;             PG8_LDB(B0, 1, 0); PG8_LDB(B1, 1, 1); PG8_SCHED; PG8_LDA(At, 1, 0); PG8_STAGE(PG8_SA(0, 1), a2 + hstep, voffA);
;             PG8_WAIT_V(8); PG8_WAIT_L(0); PG8_BAR; PG8_MMA(0, 0, At, B0); PG8_MMA(0, 1, At, B1); PG8_BAR; PG8_SCHED;
	v_mfma_f32_16x16x32_bf16 v[60:63], v[128:131], v[182:185], 0
	v_mfma_f32_16x16x32_bf16 v[56:59], v[136:139], v[182:185], 0
	v_mfma_f32_16x16x32_bf16 v[44:47], v[128:131], v[190:193], 0
	v_mfma_f32_16x16x32_bf16 v[40:43], v[136:139], v[190:193], 0
	v_mfma_f32_16x16x32_bf16 v[28:31], v[128:131], v[198:201], 0
	v_mfma_f32_16x16x32_bf16 v[24:27], v[136:139], v[198:201], 0
	v_mfma_f32_16x16x32_bf16 v[12:15], v[128:131], v[206:209], 0
	v_mfma_f32_16x16x32_bf16 v[8:11], v[136:139], v[206:209], 0
	v_mfma_f32_16x16x32_bf16 v[60:63], v[132:135], v[186:189], v[60:63]
	v_mfma_f32_16x16x32_bf16 v[56:59], v[140:143], v[186:189], v[56:59]
	v_mfma_f32_16x16x32_bf16 v[44:47], v[132:135], v[194:197], v[44:47]
	v_mfma_f32_16x16x32_bf16 v[40:43], v[140:143], v[194:197], v[40:43]
	v_mfma_f32_16x16x32_bf16 v[28:31], v[132:135], v[202:205], v[28:31]
	v_mfma_f32_16x16x32_bf16 v[24:27], v[140:143], v[202:205], v[24:27]
	v_mfma_f32_16x16x32_bf16 v[12:15], v[132:135], v[210:213], v[12:15]
	v_mfma_f32_16x16x32_bf16 v[8:11], v[140:143], v[210:213], v[8:11]
	v_mfma_f32_16x16x32_bf16 v[52:55], v[144:147], v[182:185], 0
	v_mfma_f32_16x16x32_bf16 v[48:51], v[168:171], v[182:185], 0
	v_mfma_f32_16x16x32_bf16 v[36:39], v[144:147], v[190:193], 0
	v_mfma_f32_16x16x32_bf16 v[32:35], v[168:171], v[190:193], 0
	v_mfma_f32_16x16x32_bf16 v[20:23], v[144:147], v[198:201], 0
	v_mfma_f32_16x16x32_bf16 v[16:19], v[168:171], v[198:201], 0
	v_mfma_f32_16x16x32_bf16 v[4:7], v[144:147], v[206:209], 0
	v_mfma_f32_16x16x32_bf16 v[0:3], v[168:171], v[206:209], 0
	v_mfma_f32_16x16x32_bf16 v[52:55], v[148:151], v[186:189], v[52:55]
	v_mfma_f32_16x16x32_bf16 v[48:51], v[172:175], v[186:189], v[48:51]
	v_mfma_f32_16x16x32_bf16 v[36:39], v[148:151], v[194:197], v[36:39]
	v_mfma_f32_16x16x32_bf16 v[32:35], v[172:175], v[194:197], v[32:35]
	v_mfma_f32_16x16x32_bf16 v[20:23], v[148:151], v[202:205], v[20:23]
	v_mfma_f32_16x16x32_bf16 v[16:19], v[172:175], v[202:205], v[16:19]
	v_mfma_f32_16x16x32_bf16 v[4:7], v[148:151], v[210:213], v[4:7]
	v_mfma_f32_16x16x32_bf16 v[0:3], v[172:175], v[210:213], v[0:3]
	s_barrier
	s_setprio 0
	s_add_i32 s67, 0, 0x18000
	s_add_i32 s74, 0, 0x1c000
	v_add_u32_e32 v140, s67, v177
	v_add_u32_e32 v172, s74, v177
	ds_read_b128 v[128:131], v140
	ds_read_b128 v[132:135], v140 offset:1024
	ds_read_b128 v[136:139], v140 offset:2048
	ds_read_b128 v[140:143], v140 offset:3072
	ds_read_b128 v[144:147], v172
	ds_read_b128 v[148:151], v172 offset:1024
	ds_read_b128 v[168:171], v172 offset:2048
	ds_read_b128 v[172:175], v172 offset:3072
	s_add_u32 s50, s50, 0x40000
	s_addc_u32 s51, s51, 0
	s_mov_b32 m0, s22
	v_lshl_add_u64 v[226:227], s[50:51], 0, v[158:159]
	ds_read_b128 v[182:185], v181 offset:32768
	ds_read_b128 v[186:189], v181 offset:33792
	ds_read_b128 v[190:193], v181 offset:34816
	ds_read_b128 v[194:197], v181 offset:35840
	ds_read_b128 v[198:201], v181 offset:36864
	ds_read_b128 v[202:205], v181 offset:37888
	ds_read_b128 v[206:209], v181 offset:38912
	ds_read_b128 v[210:213], v181 offset:39936
	global_load_lds_dwordx4 v[226:227], off
	v_lshl_add_u64 v[226:227], s[50:51], 0, v[154:155]
	s_mov_b32 m0, s23
	s_nop 0
	global_load_lds_dwordx4 v[226:227], off
	s_waitcnt vmcnt(8)
	s_waitcnt lgkmcnt(0)
	s_setprio 1
	s_barrier
	v_mfma_f32_16x16x32_bf16 v[124:127], v[128:131], v[182:185], v[124:127]
	v_mfma_f32_16x16x32_bf16 v[120:123], v[136:139], v[182:185], v[120:123]
	v_mfma_f32_16x16x32_bf16 v[108:111], v[128:131], v[190:193], v[108:111]
	v_mfma_f32_16x16x32_bf16 v[104:107], v[136:139], v[190:193], v[104:107]
	v_mfma_f32_16x16x32_bf16 v[92:95], v[128:131], v[198:201], v[92:95]
	v_mfma_f32_16x16x32_bf16 v[88:91], v[136:139], v[198:201], v[88:91]
	v_mfma_f32_16x16x32_bf16 v[76:79], v[128:131], v[206:209], v[76:79]
	v_mfma_f32_16x16x32_bf16 v[72:75], v[136:139], v[206:209], v[72:75]
	v_mfma_f32_16x16x32_bf16 v[124:127], v[132:135], v[186:189], v[124:127]
	v_mfma_f32_16x16x32_bf16 v[120:123], v[140:143], v[186:189], v[120:123]
	v_mfma_f32_16x16x32_bf16 v[108:111], v[132:135], v[194:197], v[108:111]
	v_mfma_f32_16x16x32_bf16 v[104:107], v[140:143], v[194:197], v[104:107]
	v_mfma_f32_16x16x32_bf16 v[92:95], v[132:135], v[202:205], v[92:95]
	v_mfma_f32_16x16x32_bf16 v[88:91], v[140:143], v[202:205], v[88:91]
	v_mfma_f32_16x16x32_bf16 v[76:79], v[132:135], v[210:213], v[76:79]
	v_mfma_f32_16x16x32_bf16 v[72:75], v[140:143], v[210:213], v[72:75]
	v_mfma_f32_16x16x32_bf16 v[116:119], v[144:147], v[182:185], v[116:119]
	v_mfma_f32_16x16x32_bf16 v[112:115], v[168:171], v[182:185], v[112:115]
	v_mfma_f32_16x16x32_bf16 v[100:103], v[144:147], v[190:193], v[100:103]
	v_mfma_f32_16x16x32_bf16 v[96:99], v[168:171], v[190:193], v[96:99]
	v_mfma_f32_16x16x32_bf16 v[84:87], v[144:147], v[198:201], v[84:87]
	v_mfma_f32_16x16x32_bf16 v[80:83], v[168:171], v[198:201], v[80:83]
	v_mfma_f32_16x16x32_bf16 v[68:71], v[144:147], v[206:209], v[68:71]
	v_mfma_f32_16x16x32_bf16 v[64:67], v[168:171], v[206:209], v[64:67]
	v_mfma_f32_16x16x32_bf16 v[116:119], v[148:151], v[186:189], v[116:119]
	v_mfma_f32_16x16x32_bf16 v[112:115], v[172:175], v[186:189], v[112:115]
	v_mfma_f32_16x16x32_bf16 v[100:103], v[148:151], v[194:197], v[100:103]
	v_mfma_f32_16x16x32_bf16 v[96:99], v[172:175], v[194:197], v[96:99]
	v_mfma_f32_16x16x32_bf16 v[84:87], v[148:151], v[202:205], v[84:87]
	v_mfma_f32_16x16x32_bf16 v[80:83], v[172:175], v[202:205], v[80:83]
	v_mfma_f32_16x16x32_bf16 v[68:71], v[148:151], v[210:213], v[68:71]
	v_mfma_f32_16x16x32_bf16 v[64:67], v[172:175], v[210:213], v[64:67]
	s_barrier
; #define PG8_STAGE(bufoff, gbase, voff) do { _Pragma("unroll") for (int _i = 0; _i < 2; ++_i) \
;         __builtin_amdgcn_global_load_lds((const unsigned*)((const char*)(gbase) + (voff)[_i]), (PG8_LAS unsigned*)(lds + (bufoff) + ldsw + _i * 8192), 16, 0, 0); } while (0)
; #define PG8_LDA(dst, b, h) do { _Pragma("unroll") for (int m = 0; m < 4; ++m) _Pragma("unroll") for (int k = 0; k < 2; ++k) dst[m][k] = *(const PG8_LAS bf16x8*)(lds + PG8_SA(b, h) + aoff + m * 2048 + k * 1024); } while (0)
; #define PG8_MMA(ai, bj, At, Bt) do { __builtin_amdgcn_s_setprio(1); _Pragma("unroll") for (int m = 0; m < 4; ++m) _Pragma("unroll") for (int n = 0; n < 2; ++n) _Pragma("unroll") for (int k = 0; k < 2; ++k) \
;         acc[ai][bj][m][n] = __builtin_amdgcn_mfma_f32_16x16x32_bf16(Bt[n][k], At[m][k], acc[ai][bj][m][n], 0, 0, 0); __builtin_amdgcn_s_setprio(0); } while (0)
; #define PG8_WAIT_V(n) asm volatile("s_waitcnt vmcnt(" #n ")" ::: "memory")
; #define PG8_WAIT_L(n) asm volatile("s_waitcnt lgkmcnt(" #n ")" ::: "memory")
; #define PG8_BAR __builtin_amdgcn_s_barrier()
; #define PG8_SCHED __builtin_amdgcn_sched_barrier(0)
; template <class Epi, class Sched, bool ALIGN_EPI = false, bool SP2 = false>
; __device__ __forceinline__ void gemm_phase(PG8_LAS unsigned char* lds, const Gemm g, const Sched& S, const Epi& E) {
;     ...
;         for (int t = 0; t < nt; t += 2) {
;             const bool last = (t == nt - 2);
;             const char* a1 = cA + (size_t)(t + 1) * kstep;
;             const char* a2 = last ? nA : cA + (size_t)(t + 2) * kstep; const char* b2 = last ? nB : cB + (size_t)(t + 2) * kstep;
;     ...
;             PG8_LDA(At, 1, 1); PG8_STAGE(PG8_SB(1, 0), b3, voffB); PG8_STAGE(PG8_SB(1, 1), b3 + hstep, voffB); PG8_STAGE(PG8_SA(1, 0), a3, voffA);
;             PG8_WAIT_V(8); PG8_WAIT_L(0); PG8_BAR; PG8_MMA(1, 0, At, B0); PG8_MMA(1, 1, At, B1); PG8_BAR; PG8_SCHED;
	s_setprio 0
	s_add_i32 s50, s67, s3
	v_lshl_add_u64 v[214:215], v[214:215], 0, s[16:17]
	s_mov_b32 m0, s50
	ds_read_b128 v[182:185], v181 offset:49152
	ds_read_b128 v[186:189], v181 offset:50176
	ds_read_b128 v[190:193], v181 offset:51200
	ds_read_b128 v[194:197], v181 offset:52224
	ds_read_b128 v[198:201], v181 offset:53248
	ds_read_b128 v[202:205], v181 offset:54272
	ds_read_b128 v[206:209], v181 offset:55296
	ds_read_b128 v[210:213], v181 offset:56320
	global_load_lds_dwordx4 v[214:215], off
	s_add_i32 m0, s50, 0x2000
	s_add_u32 s48, s48, 0x40080
	v_lshl_add_u64 v[214:215], v[216:217], 0, s[16:17]
	s_addc_u32 s49, s49, 0
	s_add_i32 s50, s74, s3
	global_load_lds_dwordx4 v[214:215], off
	v_lshl_add_u64 v[214:215], s[48:49], 0, v[156:157]
	s_mov_b32 m0, s50
	s_nop 0
	global_load_lds_dwordx4 v[214:215], off
	v_lshl_add_u64 v[214:215], s[48:49], 0, v[152:153]
	s_add_i32 m0, s50, 0x2000
	s_nop 0
	global_load_lds_dwordx4 v[214:215], off
	v_lshl_add_u64 v[214:215], v[218:219], 0, s[16:17]
	s_mov_b32 m0, s35
	s_nop 0
	global_load_lds_dwordx4 v[214:215], off
	v_lshl_add_u64 v[214:215], v[220:221], 0, s[16:17]
	s_mov_b32 m0, s45
	s_nop 0
	global_load_lds_dwordx4 v[214:215], off
	s_waitcnt vmcnt(8)
	s_waitcnt lgkmcnt(0)
	s_setprio 1
	s_barrier
	v_mfma_f32_16x16x32_bf16 v[60:63], v[128:131], v[182:185], v[60:63]
	v_mfma_f32_16x16x32_bf16 v[56:59], v[136:139], v[182:185], v[56:59]
	v_mfma_f32_16x16x32_bf16 v[44:47], v[128:131], v[190:193], v[44:47]
	v_mfma_f32_16x16x32_bf16 v[40:43], v[136:139], v[190:193], v[40:43]
	v_mfma_f32_16x16x32_bf16 v[28:31], v[128:131], v[198:201], v[28:31]
	v_mfma_f32_16x16x32_bf16 v[24:27], v[136:139], v[198:201], v[24:27]
	v_mfma_f32_16x16x32_bf16 v[12:15], v[128:131], v[206:209], v[12:15]
	v_mfma_f32_16x16x32_bf16 v[8:11], v[136:139], v[206:209], v[8:11]
	v_mfma_f32_16x16x32_bf16 v[60:63], v[132:135], v[186:189], v[60:63]
	v_mfma_f32_16x16x32_bf16 v[56:59], v[140:143], v[186:189], v[56:59]
	v_mfma_f32_16x16x32_bf16 v[44:47], v[132:135], v[194:197], v[44:47]
	v_mfma_f32_16x16x32_bf16 v[40:43], v[140:143], v[194:197], v[40:43]
	v_mfma_f32_16x16x32_bf16 v[28:31], v[132:135], v[202:205], v[28:31]
	v_mfma_f32_16x16x32_bf16 v[24:27], v[140:143], v[202:205], v[24:27]
	v_mfma_f32_16x16x32_bf16 v[12:15], v[132:135], v[210:213], v[12:15]
	v_mfma_f32_16x16x32_bf16 v[8:11], v[140:143], v[210:213], v[8:11]
	v_mfma_f32_16x16x32_bf16 v[52:55], v[144:147], v[182:185], v[52:55]
	v_mfma_f32_16x16x32_bf16 v[48:51], v[168:171], v[182:185], v[48:51]
	v_mfma_f32_16x16x32_bf16 v[36:39], v[144:147], v[190:193], v[36:39]
	v_mfma_f32_16x16x32_bf16 v[32:35], v[168:171], v[190:193], v[32:35]
	v_mfma_f32_16x16x32_bf16 v[20:23], v[144:147], v[198:201], v[20:23]
	v_mfma_f32_16x16x32_bf16 v[16:19], v[168:171], v[198:201], v[16:19]
	v_mfma_f32_16x16x32_bf16 v[4:7], v[144:147], v[206:209], v[4:7]
	v_mfma_f32_16x16x32_bf16 v[0:3], v[168:171], v[206:209], v[0:3]
	v_mfma_f32_16x16x32_bf16 v[52:55], v[148:151], v[186:189], v[52:55]
	v_mfma_f32_16x16x32_bf16 v[48:51], v[172:175], v[186:189], v[48:51]
	v_mfma_f32_16x16x32_bf16 v[36:39], v[148:151], v[194:197], v[36:39]
	v_mfma_f32_16x16x32_bf16 v[32:35], v[172:175], v[194:197], v[32:35]
	v_mfma_f32_16x16x32_bf16 v[20:23], v[148:151], v[202:205], v[20:23]
	v_mfma_f32_16x16x32_bf16 v[16:19], v[172:175], v[202:205], v[16:19]
	v_mfma_f32_16x16x32_bf16 v[4:7], v[148:151], v[210:213], v[4:7]
	v_mfma_f32_16x16x32_bf16 v[0:3], v[172:175], v[210:213], v[0:3]
	s_barrier
	s_setprio 0
	s_add_i32 s66, s66, 2
	s_add_u32 s46, s46, 0x100
	s_addc_u32 s47, s47, 0
	s_add_u32 s71, s71, 0x100
	s_addc_u32 s72, s72, 0
	s_cmp_gt_u32 s66, 13

; #define PG8_STAGE(bufoff, gbase, voff) do { _Pragma("unroll") for (int _i = 0; _i < 2; ++_i) \
;         __builtin_amdgcn_global_load_lds((const unsigned*)((const char*)(gbase) + (voff)[_i]), (PG8_LAS unsigned*)(lds + (bufoff) + ldsw + _i * 8192), 16, 0, 0); } while (0)
; #define PG8_LDA(dst, b, h) do { _Pragma("unroll") for (int m = 0; m < 4; ++m) _Pragma("unroll") for (int k = 0; k < 2; ++k) dst[m][k] = *(const PG8_LAS bf16x8*)(lds + PG8_SA(b, h) + aoff + m * 2048 + k * 1024); } while (0)
; #define PG8_LDB(dst, b, h) do { _Pragma("unroll") for (int n = 0; n < 2; ++n) _Pragma("unroll") for (int k = 0; k < 2; ++k) dst[n][k] = *(const PG8_LAS bf16x8*)(lds + PG8_SB(b, h) + boff + n * 2048 + k * 1024); } while (0)
; #define PG8_MMA(ai, bj, At, Bt) do { __builtin_amdgcn_s_setprio(1); _Pragma("unroll") for (int m = 0; m < 4; ++m) _Pragma("unroll") for (int n = 0; n < 2; ++n) _Pragma("unroll") for (int k = 0; k < 2; ++k) \
;         acc[ai][bj][m][n] = __builtin_amdgcn_mfma_f32_16x16x32_bf16(Bt[n][k], At[m][k], acc[ai][bj][m][n], 0, 0, 0); __builtin_amdgcn_s_setprio(0); } while (0)
; #define PG8_WAIT_V(n) asm volatile("s_waitcnt vmcnt(" #n ")" ::: "memory")
; template <class Epi, class Sched, bool ALIGN_EPI = false, bool SP2 = false>
; __device__ __forceinline__ void gemm_phase(PG8_LAS unsigned char* lds, const Gemm g, const Sched& S, const Epi& E) {
;     ...
;         const char* nA = has_next ? (const char*)g.A + (size_t)nxt.pm * tstep : cA; const char* nB = has_next ? (const char*)g.Bt + (size_t)nxt.pn * tstep : cB;
;         for (int t = 0; t < nt; t += 2) {
;             const bool last = (t == nt - 2);
;             const char* a1 = cA + (size_t)(t + 1) * kstep;
;             const char* a2 = last ? nA : cA + (size_t)(t + 2) * kstep; const char* b2 = last ? nB : cB + (size_t)(t + 2) * kstep;
;             const char* a3 = a2 + kstep; const char* b3 = b2 + kstep;
;             if (last && has_next) S.a_ready(nxt);
;             if constexpr (SP2) {
;             PG8_LDB(B0, 0, 0); PG8_LDB(B1, 0, 1); PG8_SCHED; PG8_LDA(At, 0, 0); PG8_STAGE(PG8_SA(1, 1), a1 + hstep, voffA);
;             PG8_WAIT_V(8); PG8_WAIT_L(0); PG8_BAR; PG8_MMA(0, 0, At, B0); PG8_MMA(0, 1, At, B1); PG8_BAR; PG8_SCHED;
;             PG8_LDA(At, 0, 1); PG8_STAGE(PG8_SB(0, 0), b2, voffB); PG8_STAGE(PG8_SB(0, 1), b2 + hstep, voffB); PG8_STAGE(PG8_SA(0, 0), a2, voffA);
.LBB0_875:
	s_ashr_i32 s31, s30, 31
	s_lshl_b64 s[12:13], s[30:31], 20
	s_add_u32 s42, s36, s12
	s_addc_u32 s43, s37, s13
	s_and_b64 s[12:13], s[8:9], exec
	s_cselect_b32 s11, s43, s47
	s_cselect_b32 s12, s42, s46
	s_ashr_i32 s29, s28, 31
	s_lshl_b64 s[44:45], s[28:29], 20
	v_readlane_b32 s50, v252, 8
	v_readlane_b32 s51, v252, 9
	s_add_u32 s44, s50, s44
	s_addc_u32 s45, s51, s45
	s_and_b64 s[50:51], s[8:9], exec
	s_cselect_b32 s13, s45, s49
	s_cselect_b32 s29, s44, s48
	s_add_u32 s31, s48, 0x100
	s_addc_u32 s72, s49, 0
	s_mov_b32 s66, -2
	s_waitcnt lgkmcnt(0)
	ds_read_b128 v[128:131], v228
	ds_read_b128 v[132:135], v228 offset:1024
	ds_read_b128 v[136:139], v228 offset:2048
	ds_read_b128 v[140:143], v228 offset:3072
	ds_read_b128 v[144:147], v229
	ds_read_b128 v[148:151], v229 offset:1024
	ds_read_b128 v[152:155], v229 offset:2048
	ds_read_b128 v[156:159], v229 offset:3072
	s_add_u32 s48, s46, 0x100
	s_addc_u32 s49, s47, 0
	s_cmp_eq_u32 s66, 28
	s_cselect_b32 s75, s11, s49
	s_cselect_b32 s74, s12, s48
	s_cselect_b32 s51, s13, s72
	s_cselect_b32 s50, s29, s31
	v_lshl_add_u64 v[204:205], s[46:47], 0, v[192:193]
	s_add_i32 m0, s14, 0xc000
	ds_read_b128 v[160:163], v230
	ds_read_b128 v[164:167], v230 offset:1024
	ds_read_b128 v[168:171], v230 offset:2048
	ds_read_b128 v[172:175], v230 offset:3072
	ds_read_b128 v[176:179], v230 offset:4096
	ds_read_b128 v[180:183], v230 offset:5120
	ds_read_b128 v[184:187], v230 offset:6144
	ds_read_b128 v[200:203], v230 offset:7168
	global_load_lds_dwordx4 v[204:205], off
	v_lshl_add_u64 v[204:205], s[46:47], 0, v[194:195]
	s_add_i32 m0, s14, 0xe000
	s_nop 0
	global_load_lds_dwordx4 v[204:205], off
	s_waitcnt vmcnt(8)
	s_waitcnt lgkmcnt(0)
	s_setprio 1
	s_barrier
	v_mfma_f32_16x16x32_bf16 v[124:127], v[128:131], v[160:163], 0
	v_mfma_f32_16x16x32_bf16 v[120:123], v[136:139], v[160:163], 0
	v_mfma_f32_16x16x32_bf16 v[108:111], v[128:131], v[168:171], 0
	v_mfma_f32_16x16x32_bf16 v[104:107], v[136:139], v[168:171], 0
	v_mfma_f32_16x16x32_bf16 v[92:95], v[128:131], v[176:179], 0
	v_mfma_f32_16x16x32_bf16 v[88:91], v[136:139], v[176:179], 0
	v_mfma_f32_16x16x32_bf16 v[76:79], v[128:131], v[184:187], 0
	v_mfma_f32_16x16x32_bf16 v[72:75], v[136:139], v[184:187], 0
	v_mfma_f32_16x16x32_bf16 v[124:127], v[132:135], v[164:167], v[124:127]
	v_mfma_f32_16x16x32_bf16 v[120:123], v[140:143], v[164:167], v[120:123]
	v_mfma_f32_16x16x32_bf16 v[108:111], v[132:135], v[172:175], v[108:111]
	v_mfma_f32_16x16x32_bf16 v[104:107], v[140:143], v[172:175], v[104:107]
	v_mfma_f32_16x16x32_bf16 v[92:95], v[132:135], v[180:183], v[92:95]
	v_mfma_f32_16x16x32_bf16 v[88:91], v[140:143], v[180:183], v[88:91]
	v_mfma_f32_16x16x32_bf16 v[76:79], v[132:135], v[200:203], v[76:79]
	v_mfma_f32_16x16x32_bf16 v[72:75], v[140:143], v[200:203], v[72:75]
	v_mfma_f32_16x16x32_bf16 v[116:119], v[144:147], v[160:163], 0
	v_mfma_f32_16x16x32_bf16 v[112:115], v[152:155], v[160:163], 0
	v_mfma_f32_16x16x32_bf16 v[100:103], v[144:147], v[168:171], 0
	v_mfma_f32_16x16x32_bf16 v[96:99], v[152:155], v[168:171], 0
	v_mfma_f32_16x16x32_bf16 v[84:87], v[144:147], v[176:179], 0
	v_mfma_f32_16x16x32_bf16 v[80:83], v[152:155], v[176:179], 0
	v_mfma_f32_16x16x32_bf16 v[68:71], v[144:147], v[184:187], 0
	v_mfma_f32_16x16x32_bf16 v[64:67], v[152:155], v[184:187], 0
	v_mfma_f32_16x16x32_bf16 v[116:119], v[148:151], v[164:167], v[116:119]
	v_mfma_f32_16x16x32_bf16 v[112:115], v[156:159], v[164:167], v[112:115]
	v_mfma_f32_16x16x32_bf16 v[100:103], v[148:151], v[172:175], v[100:103]
	v_mfma_f32_16x16x32_bf16 v[96:99], v[156:159], v[172:175], v[96:99]
	v_mfma_f32_16x16x32_bf16 v[84:87], v[148:151], v[180:183], v[84:87]
	v_mfma_f32_16x16x32_bf16 v[80:83], v[156:159], v[180:183], v[80:83]
	v_mfma_f32_16x16x32_bf16 v[68:71], v[148:151], v[200:203], v[68:71]
	v_mfma_f32_16x16x32_bf16 v[64:67], v[156:159], v[200:203], v[64:67]
	s_barrier
	s_setprio 0
	s_add_i32 s46, s69, s3
	v_lshl_add_u64 v[204:205], s[50:51], 0, v[188:189]
	s_mov_b32 m0, s46
	ds_read_b128 v[160:163], v230 offset:16384
	ds_read_b128 v[164:167], v230 offset:17408
	ds_read_b128 v[168:171], v230 offset:18432
	ds_read_b128 v[172:175], v230 offset:19456
	ds_read_b128 v[176:179], v230 offset:20480
	ds_read_b128 v[180:183], v230 offset:21504
	ds_read_b128 v[184:187], v230 offset:22528
	ds_read_b128 v[200:203], v230 offset:23552
	global_load_lds_dwordx4 v[204:205], off
	s_add_i32 m0, s46, 0x2000
	s_add_u32 s46, s50, 0x80000
	v_lshl_add_u64 v[206:207], s[50:51], 0, v[190:191]
	s_addc_u32 s47, s51, 0
	s_add_i32 s67, s70, s3
	global_load_lds_dwordx4 v[206:207], off
	v_lshl_add_u64 v[208:209], s[46:47], 0, v[188:189]
	s_mov_b32 m0, s67
	v_lshl_add_u64 v[210:211], s[74:75], 0, v[190:191]
	global_load_lds_dwordx4 v[208:209], off
	v_lshl_add_u64 v[208:209], s[46:47], 0, v[190:191]
	s_add_i32 m0, s67, 0x2000
	s_nop 0
	global_load_lds_dwordx4 v[208:209], off
	v_lshl_add_u64 v[208:209], s[74:75], 0, v[188:189]
	s_mov_b32 m0, s14
	s_nop 0
	global_load_lds_dwordx4 v[208:209], off
	s_mov_b32 m0, s15
	s_nop 0
	global_load_lds_dwordx4 v[210:211], off
	s_waitcnt vmcnt(8)
	s_waitcnt lgkmcnt(0)
	s_setprio 1
	s_barrier
; #define PG8_STAGE(bufoff, gbase, voff) do { _Pragma("unroll") for (int _i = 0; _i < 2; ++_i) \
;         __builtin_amdgcn_global_load_lds((const unsigned*)((const char*)(gbase) + (voff)[_i]), (PG8_LAS unsigned*)(lds + (bufoff) + ldsw + _i * 8192), 16, 0, 0); } while (0)
; #define PG8_LDA(dst, b, h) do { _Pragma("unroll") for (int m = 0; m < 4; ++m) _Pragma("unroll") for (int k = 0; k < 2; ++k) dst[m][k] = *(const PG8_LAS bf16x8*)(lds + PG8_SA(b, h) + aoff + m * 2048 + k * 1024); } while (0)
; #define PG8_LDB(dst, b, h) do { _Pragma("unroll") for (int n = 0; n < 2; ++n) _Pragma("unroll") for (int k = 0; k < 2; ++k) dst[n][k] = *(const PG8_LAS bf16x8*)(lds + PG8_SB(b, h) + boff + n * 2048 + k * 1024); } while (0)
; #define PG8_MMA(ai, bj, At, Bt) do { __builtin_amdgcn_s_setprio(1); _Pragma("unroll") for (int m = 0; m < 4; ++m) _Pragma("unroll") for (int n = 0; n < 2; ++n) _Pragma("unroll") for (int k = 0; k < 2; ++k) \
;         acc[ai][bj][m][n] = __builtin_amdgcn_mfma_f32_16x16x32_bf16(Bt[n][k], At[m][k], acc[ai][bj][m][n], 0, 0, 0); __builtin_amdgcn_s_setprio(0); } while (0)
; #define PG8_WAIT_V(n) asm volatile("s_waitcnt vmcnt(" #n ")" ::: "memory")
; #define PG8_WAIT_L(n) asm volatile("s_waitcnt lgkmcnt(" #n ")" ::: "memory")
; #define PG8_BAR __builtin_amdgcn_s_barrier()
; #define PG8_SCHED __builtin_amdgcn_sched_barrier(0)
; template <class Epi, class Sched, bool ALIGN_EPI = false, bool SP2 = false>
; __device__ __forceinline__ void gemm_phase(PG8_LAS unsigned char* lds, const Gemm g, const Sched& S, const Epi& E) {
;     ...
;             PG8_WAIT_V(8); PG8_WAIT_L(0); PG8_BAR; PG8_MMA(1, 0, At, B0); PG8_MMA(1, 1, At, B1); PG8_BAR; PG8_SCHED;
;             PG8_LDB(B0, 1, 0); PG8_LDB(B1, 1, 1); PG8_SCHED; PG8_LDA(At, 1, 0); PG8_STAGE(PG8_SA(0, 1), a2 + hstep, voffA);
;             PG8_WAIT_V(8); PG8_WAIT_L(0); PG8_BAR; PG8_MMA(0, 0, At, B0); PG8_MMA(0, 1, At, B1); PG8_BAR; PG8_SCHED;
	v_mfma_f32_16x16x32_bf16 v[60:63], v[128:131], v[160:163], 0
	v_mfma_f32_16x16x32_bf16 v[56:59], v[136:139], v[160:163], 0
	v_mfma_f32_16x16x32_bf16 v[44:47], v[128:131], v[168:171], 0
	v_mfma_f32_16x16x32_bf16 v[40:43], v[136:139], v[168:171], 0
	v_mfma_f32_16x16x32_bf16 v[28:31], v[128:131], v[176:179], 0
	v_mfma_f32_16x16x32_bf16 v[24:27], v[136:139], v[176:179], 0
	v_mfma_f32_16x16x32_bf16 v[12:15], v[128:131], v[184:187], 0
	v_mfma_f32_16x16x32_bf16 v[8:11], v[136:139], v[184:187], 0
	v_mfma_f32_16x16x32_bf16 v[60:63], v[132:135], v[164:167], v[60:63]
	v_mfma_f32_16x16x32_bf16 v[56:59], v[140:143], v[164:167], v[56:59]
	v_mfma_f32_16x16x32_bf16 v[44:47], v[132:135], v[172:175], v[44:47]
	v_mfma_f32_16x16x32_bf16 v[40:43], v[140:143], v[172:175], v[40:43]
	v_mfma_f32_16x16x32_bf16 v[28:31], v[132:135], v[180:183], v[28:31]
	v_mfma_f32_16x16x32_bf16 v[24:27], v[140:143], v[180:183], v[24:27]
	v_mfma_f32_16x16x32_bf16 v[12:15], v[132:135], v[200:203], v[12:15]
	v_mfma_f32_16x16x32_bf16 v[8:11], v[140:143], v[200:203], v[8:11]
	v_mfma_f32_16x16x32_bf16 v[52:55], v[144:147], v[160:163], 0
	v_mfma_f32_16x16x32_bf16 v[48:51], v[152:155], v[160:163], 0
	v_mfma_f32_16x16x32_bf16 v[36:39], v[144:147], v[168:171], 0
	v_mfma_f32_16x16x32_bf16 v[32:35], v[152:155], v[168:171], 0
	v_mfma_f32_16x16x32_bf16 v[20:23], v[144:147], v[176:179], 0
	v_mfma_f32_16x16x32_bf16 v[16:19], v[152:155], v[176:179], 0
	v_mfma_f32_16x16x32_bf16 v[4:7], v[144:147], v[184:187], 0
	v_mfma_f32_16x16x32_bf16 v[0:3], v[152:155], v[184:187], 0
	v_mfma_f32_16x16x32_bf16 v[52:55], v[148:151], v[164:167], v[52:55]
	v_mfma_f32_16x16x32_bf16 v[48:51], v[156:159], v[164:167], v[48:51]
	v_mfma_f32_16x16x32_bf16 v[36:39], v[148:151], v[172:175], v[36:39]
	v_mfma_f32_16x16x32_bf16 v[32:35], v[156:159], v[172:175], v[32:35]
	v_mfma_f32_16x16x32_bf16 v[20:23], v[148:151], v[180:183], v[20:23]
	v_mfma_f32_16x16x32_bf16 v[16:19], v[156:159], v[180:183], v[16:19]
	v_mfma_f32_16x16x32_bf16 v[4:7], v[148:151], v[200:203], v[4:7]
	v_mfma_f32_16x16x32_bf16 v[0:3], v[156:159], v[200:203], v[0:3]
	s_barrier
	s_setprio 0
	s_add_i32 s67, 0, 0x18000
	s_add_i32 s76, 0, 0x1c000
	v_add_u32_e32 v140, s67, v226
	v_add_u32_e32 v156, s76, v226
	ds_read_b128 v[128:131], v140
	ds_read_b128 v[132:135], v140 offset:1024
	ds_read_b128 v[136:139], v140 offset:2048
	ds_read_b128 v[140:143], v140 offset:3072
	ds_read_b128 v[144:147], v156
	ds_read_b128 v[148:151], v156 offset:1024
	ds_read_b128 v[152:155], v156 offset:2048
	ds_read_b128 v[156:159], v156 offset:3072
	s_add_u32 s46, s74, 0x80000
	s_addc_u32 s47, s75, 0
	s_mov_b32 m0, s22
	v_lshl_add_u64 v[212:213], s[46:47], 0, v[188:189]
	ds_read_b128 v[160:163], v230 offset:32768
	ds_read_b128 v[164:167], v230 offset:33792
	ds_read_b128 v[168:171], v230 offset:34816
	ds_read_b128 v[172:175], v230 offset:35840
	ds_read_b128 v[176:179], v230 offset:36864
	ds_read_b128 v[180:183], v230 offset:37888
	ds_read_b128 v[184:187], v230 offset:38912
	ds_read_b128 v[200:203], v230 offset:39936
	global_load_lds_dwordx4 v[212:213], off
	v_lshl_add_u64 v[212:213], s[46:47], 0, v[190:191]
	s_mov_b32 m0, s23
	s_nop 0
	global_load_lds_dwordx4 v[212:213], off
	s_waitcnt vmcnt(8)
	s_waitcnt lgkmcnt(0)
	s_setprio 1
	s_barrier
	v_mfma_f32_16x16x32_bf16 v[124:127], v[128:131], v[160:163], v[124:127]
	v_mfma_f32_16x16x32_bf16 v[120:123], v[136:139], v[160:163], v[120:123]
	v_mfma_f32_16x16x32_bf16 v[108:111], v[128:131], v[168:171], v[108:111]
	v_mfma_f32_16x16x32_bf16 v[104:107], v[136:139], v[168:171], v[104:107]
	v_mfma_f32_16x16x32_bf16 v[92:95], v[128:131], v[176:179], v[92:95]
	v_mfma_f32_16x16x32_bf16 v[88:91], v[136:139], v[176:179], v[88:91]
	v_mfma_f32_16x16x32_bf16 v[76:79], v[128:131], v[184:187], v[76:79]
	v_mfma_f32_16x16x32_bf16 v[72:75], v[136:139], v[184:187], v[72:75]
	v_mfma_f32_16x16x32_bf16 v[124:127], v[132:135], v[164:167], v[124:127]
	v_mfma_f32_16x16x32_bf16 v[120:123], v[140:143], v[164:167], v[120:123]
	v_mfma_f32_16x16x32_bf16 v[108:111], v[132:135], v[172:175], v[108:111]
	v_mfma_f32_16x16x32_bf16 v[104:107], v[140:143], v[172:175], v[104:107]
	v_mfma_f32_16x16x32_bf16 v[92:95], v[132:135], v[180:183], v[92:95]
	v_mfma_f32_16x16x32_bf16 v[88:91], v[140:143], v[180:183], v[88:91]
	v_mfma_f32_16x16x32_bf16 v[76:79], v[132:135], v[200:203], v[76:79]
	v_mfma_f32_16x16x32_bf16 v[72:75], v[140:143], v[200:203], v[72:75]
	v_mfma_f32_16x16x32_bf16 v[116:119], v[144:147], v[160:163], v[116:119]
	v_mfma_f32_16x16x32_bf16 v[112:115], v[152:155], v[160:163], v[112:115]
	v_mfma_f32_16x16x32_bf16 v[100:103], v[144:147], v[168:171], v[100:103]
	v_mfma_f32_16x16x32_bf16 v[96:99], v[152:155], v[168:171], v[96:99]
	v_mfma_f32_16x16x32_bf16 v[84:87], v[144:147], v[176:179], v[84:87]
	v_mfma_f32_16x16x32_bf16 v[80:83], v[152:155], v[176:179], v[80:83]
	v_mfma_f32_16x16x32_bf16 v[68:71], v[144:147], v[184:187], v[68:71]
	v_mfma_f32_16x16x32_bf16 v[64:67], v[152:155], v[184:187], v[64:67]
	v_mfma_f32_16x16x32_bf16 v[116:119], v[148:151], v[164:167], v[116:119]
	v_mfma_f32_16x16x32_bf16 v[112:115], v[156:159], v[164:167], v[112:115]
	v_mfma_f32_16x16x32_bf16 v[100:103], v[148:151], v[172:175], v[100:103]
	v_mfma_f32_16x16x32_bf16 v[96:99], v[156:159], v[172:175], v[96:99]
	v_mfma_f32_16x16x32_bf16 v[84:87], v[148:151], v[180:183], v[84:87]
	v_mfma_f32_16x16x32_bf16 v[80:83], v[156:159], v[180:183], v[80:83]
	v_mfma_f32_16x16x32_bf16 v[68:71], v[148:151], v[200:203], v[68:71]
	v_mfma_f32_16x16x32_bf16 v[64:67], v[156:159], v[200:203], v[64:67]
	s_barrier
; #define PG8_STAGE(bufoff, gbase, voff) do { _Pragma("unroll") for (int _i = 0; _i < 2; ++_i) \
;         __builtin_amdgcn_global_load_lds((const unsigned*)((const char*)(gbase) + (voff)[_i]), (PG8_LAS unsigned*)(lds + (bufoff) + ldsw + _i * 8192), 16, 0, 0); } while (0)
; #define PG8_LDA(dst, b, h) do { _Pragma("unroll") for (int m = 0; m < 4; ++m) _Pragma("unroll") for (int k = 0; k < 2; ++k) dst[m][k] = *(const PG8_LAS bf16x8*)(lds + PG8_SA(b, h) + aoff + m * 2048 + k * 1024); } while (0)
; #define PG8_MMA(ai, bj, At, Bt) do { __builtin_amdgcn_s_setprio(1); _Pragma("unroll") for (int m = 0; m < 4; ++m) _Pragma("unroll") for (int n = 0; n < 2; ++n) _Pragma("unroll") for (int k = 0; k < 2; ++k) \
;         acc[ai][bj][m][n] = __builtin_amdgcn_mfma_f32_16x16x32_bf16(Bt[n][k], At[m][k], acc[ai][bj][m][n], 0, 0, 0); __builtin_amdgcn_s_setprio(0); } while (0)
; #define PG8_WAIT_V(n) asm volatile("s_waitcnt vmcnt(" #n ")" ::: "memory")
; #define PG8_WAIT_L(n) asm volatile("s_waitcnt lgkmcnt(" #n ")" ::: "memory")
; #define PG8_BAR __builtin_amdgcn_s_barrier()
; #define PG8_SCHED __builtin_amdgcn_sched_barrier(0)
; template <class Epi, class Sched, bool ALIGN_EPI = false, bool SP2 = false>
; __device__ __forceinline__ void gemm_phase(PG8_LAS unsigned char* lds, const Gemm g, const Sched& S, const Epi& E) {
;     ...
;         for (int t = 0; t < nt; t += 2) {
;             const bool last = (t == nt - 2);
;             const char* a1 = cA + (size_t)(t + 1) * kstep;
;             const char* a2 = last ? nA : cA + (size_t)(t + 2) * kstep; const char* b2 = last ? nB : cB + (size_t)(t + 2) * kstep;
;     ...
;             PG8_LDA(At, 1, 1); PG8_STAGE(PG8_SB(1, 0), b3, voffB); PG8_STAGE(PG8_SB(1, 1), b3 + hstep, voffB); PG8_STAGE(PG8_SA(1, 0), a3, voffA);
;             PG8_WAIT_V(8); PG8_WAIT_L(0); PG8_BAR; PG8_MMA(1, 0, At, B0); PG8_MMA(1, 1, At, B1); PG8_BAR; PG8_SCHED;
	s_setprio 0
	s_add_i32 s46, s67, s3
	v_lshl_add_u64 v[204:205], v[204:205], 0, s[20:21]
	s_mov_b32 m0, s46
	ds_read_b128 v[160:163], v230 offset:49152
	ds_read_b128 v[164:167], v230 offset:50176
	ds_read_b128 v[168:171], v230 offset:51200
	ds_read_b128 v[172:175], v230 offset:52224
	ds_read_b128 v[176:179], v230 offset:53248
	ds_read_b128 v[180:183], v230 offset:54272
	ds_read_b128 v[184:187], v230 offset:55296
	ds_read_b128 v[200:203], v230 offset:56320
	global_load_lds_dwordx4 v[204:205], off
	s_add_i32 m0, s46, 0x2000
	s_add_u32 s46, s50, 0x80080
	v_lshl_add_u64 v[204:205], v[206:207], 0, s[20:21]
	s_addc_u32 s47, s51, 0
	s_add_i32 s50, s76, s3
	global_load_lds_dwordx4 v[204:205], off
	v_lshl_add_u64 v[204:205], s[46:47], 0, v[188:189]
	s_mov_b32 m0, s50
	s_nop 0
	global_load_lds_dwordx4 v[204:205], off
	v_lshl_add_u64 v[204:205], s[46:47], 0, v[190:191]
	s_add_i32 m0, s50, 0x2000
	s_nop 0
	global_load_lds_dwordx4 v[204:205], off
	v_lshl_add_u64 v[204:205], v[208:209], 0, s[20:21]
	s_mov_b32 m0, s35
	s_nop 0
	global_load_lds_dwordx4 v[204:205], off
	v_lshl_add_u64 v[204:205], v[210:211], 0, s[20:21]
	s_mov_b32 m0, s68
	s_nop 0
	global_load_lds_dwordx4 v[204:205], off
	s_waitcnt vmcnt(8)
	s_waitcnt lgkmcnt(0)
	s_setprio 1
	s_barrier
	v_mfma_f32_16x16x32_bf16 v[60:63], v[128:131], v[160:163], v[60:63]
	v_mfma_f32_16x16x32_bf16 v[56:59], v[136:139], v[160:163], v[56:59]
	v_mfma_f32_16x16x32_bf16 v[44:47], v[128:131], v[168:171], v[44:47]
	v_mfma_f32_16x16x32_bf16 v[40:43], v[136:139], v[168:171], v[40:43]
	v_mfma_f32_16x16x32_bf16 v[28:31], v[128:131], v[176:179], v[28:31]
	v_mfma_f32_16x16x32_bf16 v[24:27], v[136:139], v[176:179], v[24:27]
	v_mfma_f32_16x16x32_bf16 v[12:15], v[128:131], v[184:187], v[12:15]
	v_mfma_f32_16x16x32_bf16 v[8:11], v[136:139], v[184:187], v[8:11]
	v_mfma_f32_16x16x32_bf16 v[60:63], v[132:135], v[164:167], v[60:63]
	v_mfma_f32_16x16x32_bf16 v[56:59], v[140:143], v[164:167], v[56:59]
	v_mfma_f32_16x16x32_bf16 v[44:47], v[132:135], v[172:175], v[44:47]
	v_mfma_f32_16x16x32_bf16 v[40:43], v[140:143], v[172:175], v[40:43]
	v_mfma_f32_16x16x32_bf16 v[28:31], v[132:135], v[180:183], v[28:31]
	v_mfma_f32_16x16x32_bf16 v[24:27], v[140:143], v[180:183], v[24:27]
	v_mfma_f32_16x16x32_bf16 v[12:15], v[132:135], v[200:203], v[12:15]
	v_mfma_f32_16x16x32_bf16 v[8:11], v[140:143], v[200:203], v[8:11]
	v_mfma_f32_16x16x32_bf16 v[52:55], v[144:147], v[160:163], v[52:55]
	v_mfma_f32_16x16x32_bf16 v[48:51], v[152:155], v[160:163], v[48:51]
	v_mfma_f32_16x16x32_bf16 v[36:39], v[144:147], v[168:171], v[36:39]
	v_mfma_f32_16x16x32_bf16 v[32:35], v[152:155], v[168:171], v[32:35]
	v_mfma_f32_16x16x32_bf16 v[20:23], v[144:147], v[176:179], v[20:23]
	v_mfma_f32_16x16x32_bf16 v[16:19], v[152:155], v[176:179], v[16:19]
	v_mfma_f32_16x16x32_bf16 v[4:7], v[144:147], v[184:187], v[4:7]
	v_mfma_f32_16x16x32_bf16 v[0:3], v[152:155], v[184:187], v[0:3]
	v_mfma_f32_16x16x32_bf16 v[52:55], v[148:151], v[164:167], v[52:55]
	v_mfma_f32_16x16x32_bf16 v[48:51], v[156:159], v[164:167], v[48:51]
	v_mfma_f32_16x16x32_bf16 v[36:39], v[148:151], v[172:175], v[36:39]
	v_mfma_f32_16x16x32_bf16 v[32:35], v[156:159], v[172:175], v[32:35]
	v_mfma_f32_16x16x32_bf16 v[20:23], v[148:151], v[180:183], v[20:23]
	v_mfma_f32_16x16x32_bf16 v[16:19], v[156:159], v[180:183], v[16:19]
	v_mfma_f32_16x16x32_bf16 v[4:7], v[148:151], v[200:203], v[4:7]
	v_mfma_f32_16x16x32_bf16 v[0:3], v[156:159], v[200:203], v[0:3]
	s_barrier
	s_setprio 0
	s_add_i32 s66, s66, 2
	s_add_u32 s31, s31, 0x100
	s_addc_u32 s72, s72, 0
	s_cmp_gt_u32 s66, 29
	s_mov_b64 s[46:47], s[48:49]

; #define PG8_STAGE(bufoff, gbase, voff) do { _Pragma("unroll") for (int _i = 0; _i < 2; ++_i) \
;         __builtin_amdgcn_global_load_lds((const unsigned*)((const char*)(gbase) + (voff)[_i]), (PG8_LAS unsigned*)(lds + (bufoff) + ldsw + _i * 8192), 16, 0, 0); } while (0)
; #define PG8_LDA(dst, b, h) do { _Pragma("unroll") for (int m = 0; m < 4; ++m) _Pragma("unroll") for (int k = 0; k < 2; ++k) dst[m][k] = *(const PG8_LAS bf16x8*)(lds + PG8_SA(b, h) + aoff + m * 2048 + k * 1024); } while (0)
; #define PG8_LDB(dst, b, h) do { _Pragma("unroll") for (int n = 0; n < 2; ++n) _Pragma("unroll") for (int k = 0; k < 2; ++k) dst[n][k] = *(const PG8_LAS bf16x8*)(lds + PG8_SB(b, h) + boff + n * 2048 + k * 1024); } while (0)
; #define PG8_MMA(ai, bj, At, Bt) do { __builtin_amdgcn_s_setprio(1); _Pragma("unroll") for (int m = 0; m < 4; ++m) _Pragma("unroll") for (int n = 0; n < 2; ++n) _Pragma("unroll") for (int k = 0; k < 2; ++k) \
;         acc[ai][bj][m][n] = __builtin_amdgcn_mfma_f32_16x16x32_bf16(Bt[n][k], At[m][k], acc[ai][bj][m][n], 0, 0, 0); __builtin_amdgcn_s_setprio(0); } while (0)
; #define PG8_WAIT_V(n) asm volatile("s_waitcnt vmcnt(" #n ")" ::: "memory")
; template <class Epi, class Sched, bool ALIGN_EPI = false, bool SP2 = false>
; __device__ __forceinline__ void gemm_phase(PG8_LAS unsigned char* lds, const Gemm g, const Sched& S, const Epi& E) {
;     ...
;         const char* nA = has_next ? (const char*)g.A + (size_t)nxt.pm * tstep : cA; const char* nB = has_next ? (const char*)g.Bt + (size_t)nxt.pn * tstep : cB;
;         for (int t = 0; t < nt; t += 2) {
;             const bool last = (t == nt - 2);
;             const char* a1 = cA + (size_t)(t + 1) * kstep;
;             const char* a2 = last ? nA : cA + (size_t)(t + 2) * kstep; const char* b2 = last ? nB : cB + (size_t)(t + 2) * kstep;
;             const char* a3 = a2 + kstep; const char* b3 = b2 + kstep;
;             if (last && has_next) S.a_ready(nxt);
;             if constexpr (SP2) {
;             PG8_LDB(B0, 0, 0); PG8_LDB(B1, 0, 1); PG8_SCHED; PG8_LDA(At, 0, 0); PG8_STAGE(PG8_SA(1, 1), a1 + hstep, voffA);
;             PG8_WAIT_V(8); PG8_WAIT_L(0); PG8_BAR; PG8_MMA(0, 0, At, B0); PG8_MMA(0, 1, At, B1); PG8_BAR; PG8_SCHED;
;             PG8_LDA(At, 0, 1); PG8_STAGE(PG8_SB(0, 0), b2, voffB); PG8_STAGE(PG8_SB(0, 1), b2 + hstep, voffB); PG8_STAGE(PG8_SA(0, 0), a2, voffA);
.LBB0_1024:
	s_ashr_i32 s19, s18, 31
	s_lshl_b64 s[12:13], s[18:19], 20
	s_add_u32 s20, s40, s12
	s_addc_u32 s21, s41, s13
	s_and_b64 s[12:13], s[6:7], exec
	s_cselect_b32 s12, s21, s29
	s_cselect_b32 s13, s20, s28
	s_ashr_i32 s1, s0, 31
	s_lshl_b64 s[24:25], s[0:1], 20
	s_add_u32 s24, s64, s24
	s_addc_u32 s25, s65, s25
	s_and_b64 s[36:37], s[6:7], exec
	s_cselect_b32 s1, s25, s31
	s_cselect_b32 s19, s24, s30
	s_add_u32 s28, s28, 0x80080
	s_addc_u32 s29, s29, 0
	s_add_u32 s47, s30, 0x100
	s_addc_u32 s48, s31, 0
	s_mov_b32 s49, -2
	ds_read_b128 v[146:149], v167
	ds_read_b128 v[150:153], v167 offset:1024
	ds_read_b128 v[178:181], v167 offset:2048
	ds_read_b128 v[182:185], v167 offset:3072
	ds_read_b128 v[186:189], v171
	ds_read_b128 v[190:193], v171 offset:1024
	ds_read_b128 v[194:197], v171 offset:2048
	ds_read_b128 v[198:201], v171 offset:3072
	s_add_u32 s30, s28, 0xfff80080
	s_addc_u32 s31, s29, -1
	s_cmp_eq_u32 s49, 28
	s_cselect_b32 s37, s12, s31
	s_cselect_b32 s36, s13, s30
	s_cselect_b32 s31, s1, s48
	s_cselect_b32 s30, s19, s47
	v_lshl_add_u64 v[156:157], s[28:29], 0, v[138:139]
	s_add_i32 m0, s15, 0xc000
	ds_read_b128 v[202:205], v175
	ds_read_b128 v[206:209], v175 offset:1024
	ds_read_b128 v[210:213], v175 offset:2048
	ds_read_b128 v[214:217], v175 offset:3072
	ds_read_b128 v[218:221], v175 offset:4096
	ds_read_b128 v[226:229], v175 offset:5120
	ds_read_b128 v[230:233], v175 offset:6144
	ds_read_b128 v[234:237], v175 offset:7168
	global_load_lds_dwordx4 v[156:157], off
	v_lshl_add_u64 v[156:157], s[28:29], 0, v[140:141]
	s_add_i32 m0, s15, 0xe000
	s_nop 0
	global_load_lds_dwordx4 v[156:157], off
	s_waitcnt vmcnt(8)
	s_waitcnt lgkmcnt(0)
	s_setprio 1
	s_barrier
	v_mfma_f32_16x16x32_bf16 v[124:127], v[146:149], v[202:205], 0
	v_mfma_f32_16x16x32_bf16 v[120:123], v[178:181], v[202:205], 0
	v_mfma_f32_16x16x32_bf16 v[108:111], v[146:149], v[210:213], 0
	v_mfma_f32_16x16x32_bf16 v[104:107], v[178:181], v[210:213], 0
	v_mfma_f32_16x16x32_bf16 v[92:95], v[146:149], v[218:221], 0
	v_mfma_f32_16x16x32_bf16 v[88:91], v[178:181], v[218:221], 0
	v_mfma_f32_16x16x32_bf16 v[76:79], v[146:149], v[230:233], 0
	v_mfma_f32_16x16x32_bf16 v[72:75], v[178:181], v[230:233], 0
	v_mfma_f32_16x16x32_bf16 v[124:127], v[150:153], v[206:209], v[124:127]
	v_mfma_f32_16x16x32_bf16 v[120:123], v[182:185], v[206:209], v[120:123]
	v_mfma_f32_16x16x32_bf16 v[108:111], v[150:153], v[214:217], v[108:111]
	v_mfma_f32_16x16x32_bf16 v[104:107], v[182:185], v[214:217], v[104:107]
	v_mfma_f32_16x16x32_bf16 v[92:95], v[150:153], v[226:229], v[92:95]
	v_mfma_f32_16x16x32_bf16 v[88:91], v[182:185], v[226:229], v[88:91]
	v_mfma_f32_16x16x32_bf16 v[76:79], v[150:153], v[234:237], v[76:79]
	v_mfma_f32_16x16x32_bf16 v[72:75], v[182:185], v[234:237], v[72:75]
	v_mfma_f32_16x16x32_bf16 v[116:119], v[186:189], v[202:205], 0
	v_mfma_f32_16x16x32_bf16 v[112:115], v[194:197], v[202:205], 0
	v_mfma_f32_16x16x32_bf16 v[100:103], v[186:189], v[210:213], 0
	v_mfma_f32_16x16x32_bf16 v[96:99], v[194:197], v[210:213], 0
	v_mfma_f32_16x16x32_bf16 v[84:87], v[186:189], v[218:221], 0
	v_mfma_f32_16x16x32_bf16 v[80:83], v[194:197], v[218:221], 0
	v_mfma_f32_16x16x32_bf16 v[68:71], v[186:189], v[230:233], 0
	v_mfma_f32_16x16x32_bf16 v[64:67], v[194:197], v[230:233], 0
	v_mfma_f32_16x16x32_bf16 v[116:119], v[190:193], v[206:209], v[116:119]
	v_mfma_f32_16x16x32_bf16 v[112:115], v[198:201], v[206:209], v[112:115]
	v_mfma_f32_16x16x32_bf16 v[100:103], v[190:193], v[214:217], v[100:103]
	v_mfma_f32_16x16x32_bf16 v[96:99], v[198:201], v[214:217], v[96:99]
	v_mfma_f32_16x16x32_bf16 v[84:87], v[190:193], v[226:229], v[84:87]
	v_mfma_f32_16x16x32_bf16 v[80:83], v[198:201], v[226:229], v[80:83]
	v_mfma_f32_16x16x32_bf16 v[68:71], v[190:193], v[234:237], v[68:71]
	v_mfma_f32_16x16x32_bf16 v[64:67], v[198:201], v[234:237], v[64:67]
	s_barrier
	s_setprio 0
	s_add_i32 s50, s43, s3
	v_lshl_add_u64 v[156:157], s[30:31], 0, v[132:133]
	s_mov_b32 m0, s50
	ds_read_b128 v[202:205], v175 offset:16384
	ds_read_b128 v[206:209], v175 offset:17408
	ds_read_b128 v[210:213], v175 offset:18432
	ds_read_b128 v[214:217], v175 offset:19456
	ds_read_b128 v[218:221], v175 offset:20480
	ds_read_b128 v[226:229], v175 offset:21504
	ds_read_b128 v[230:233], v175 offset:22528
	ds_read_b128 v[234:237], v175 offset:23552
	global_load_lds_dwordx4 v[156:157], off
	s_add_i32 m0, s50, 0x2000
	s_add_u32 s50, s30, 0x80000
	v_lshl_add_u64 v[160:161], s[30:31], 0, v[128:129]
	s_addc_u32 s51, s31, 0
	s_add_i32 s66, s44, s3
	global_load_lds_dwordx4 v[160:161], off
	v_lshl_add_u64 v[164:165], s[50:51], 0, v[132:133]
	s_mov_b32 m0, s66
	v_lshl_add_u64 v[168:169], s[36:37], 0, v[130:131]
	global_load_lds_dwordx4 v[164:165], off
	v_lshl_add_u64 v[164:165], s[50:51], 0, v[128:129]
	s_add_i32 m0, s66, 0x2000
	s_nop 0
	global_load_lds_dwordx4 v[164:165], off
	v_lshl_add_u64 v[164:165], s[36:37], 0, v[134:135]
	s_mov_b32 m0, s15
	s_nop 0
	global_load_lds_dwordx4 v[164:165], off
	s_mov_b32 m0, s22
	s_nop 0
	global_load_lds_dwordx4 v[168:169], off
	s_waitcnt vmcnt(8)
	s_waitcnt lgkmcnt(0)
	s_setprio 1
	s_barrier
; #define PG8_STAGE(bufoff, gbase, voff) do { _Pragma("unroll") for (int _i = 0; _i < 2; ++_i) \
;         __builtin_amdgcn_global_load_lds((const unsigned*)((const char*)(gbase) + (voff)[_i]), (PG8_LAS unsigned*)(lds + (bufoff) + ldsw + _i * 8192), 16, 0, 0); } while (0)
; #define PG8_LDA(dst, b, h) do { _Pragma("unroll") for (int m = 0; m < 4; ++m) _Pragma("unroll") for (int k = 0; k < 2; ++k) dst[m][k] = *(const PG8_LAS bf16x8*)(lds + PG8_SA(b, h) + aoff + m * 2048 + k * 1024); } while (0)
; #define PG8_LDB(dst, b, h) do { _Pragma("unroll") for (int n = 0; n < 2; ++n) _Pragma("unroll") for (int k = 0; k < 2; ++k) dst[n][k] = *(const PG8_LAS bf16x8*)(lds + PG8_SB(b, h) + boff + n * 2048 + k * 1024); } while (0)
; #define PG8_MMA(ai, bj, At, Bt) do { __builtin_amdgcn_s_setprio(1); _Pragma("unroll") for (int m = 0; m < 4; ++m) _Pragma("unroll") for (int n = 0; n < 2; ++n) _Pragma("unroll") for (int k = 0; k < 2; ++k) \
;         acc[ai][bj][m][n] = __builtin_amdgcn_mfma_f32_16x16x32_bf16(Bt[n][k], At[m][k], acc[ai][bj][m][n], 0, 0, 0); __builtin_amdgcn_s_setprio(0); } while (0)
; #define PG8_WAIT_V(n) asm volatile("s_waitcnt vmcnt(" #n ")" ::: "memory")
; #define PG8_WAIT_L(n) asm volatile("s_waitcnt lgkmcnt(" #n ")" ::: "memory")
; #define PG8_BAR __builtin_amdgcn_s_barrier()
; #define PG8_SCHED __builtin_amdgcn_sched_barrier(0)
; template <class Epi, class Sched, bool ALIGN_EPI = false, bool SP2 = false>
; __device__ __forceinline__ void gemm_phase(PG8_LAS unsigned char* lds, const Gemm g, const Sched& S, const Epi& E) {
;     ...
;             PG8_WAIT_V(8); PG8_WAIT_L(0); PG8_BAR; PG8_MMA(1, 0, At, B0); PG8_MMA(1, 1, At, B1); PG8_BAR; PG8_SCHED;
;             PG8_LDB(B0, 1, 0); PG8_LDB(B1, 1, 1); PG8_SCHED; PG8_LDA(At, 1, 0); PG8_STAGE(PG8_SA(0, 1), a2 + hstep, voffA);
;             PG8_WAIT_V(8); PG8_WAIT_L(0); PG8_BAR; PG8_MMA(0, 0, At, B0); PG8_MMA(0, 1, At, B1); PG8_BAR; PG8_SCHED;
	v_mfma_f32_16x16x32_bf16 v[60:63], v[146:149], v[202:205], 0
	v_mfma_f32_16x16x32_bf16 v[56:59], v[178:181], v[202:205], 0
	v_mfma_f32_16x16x32_bf16 v[44:47], v[146:149], v[210:213], 0
	v_mfma_f32_16x16x32_bf16 v[40:43], v[178:181], v[210:213], 0
	v_mfma_f32_16x16x32_bf16 v[28:31], v[146:149], v[218:221], 0
	v_mfma_f32_16x16x32_bf16 v[24:27], v[178:181], v[218:221], 0
	v_mfma_f32_16x16x32_bf16 v[12:15], v[146:149], v[230:233], 0
	v_mfma_f32_16x16x32_bf16 v[8:11], v[178:181], v[230:233], 0
	v_mfma_f32_16x16x32_bf16 v[60:63], v[150:153], v[206:209], v[60:63]
	v_mfma_f32_16x16x32_bf16 v[56:59], v[182:185], v[206:209], v[56:59]
	v_mfma_f32_16x16x32_bf16 v[44:47], v[150:153], v[214:217], v[44:47]
	v_mfma_f32_16x16x32_bf16 v[40:43], v[182:185], v[214:217], v[40:43]
	v_mfma_f32_16x16x32_bf16 v[28:31], v[150:153], v[226:229], v[28:31]
	v_mfma_f32_16x16x32_bf16 v[24:27], v[182:185], v[226:229], v[24:27]
	v_mfma_f32_16x16x32_bf16 v[12:15], v[150:153], v[234:237], v[12:15]
	v_mfma_f32_16x16x32_bf16 v[8:11], v[182:185], v[234:237], v[8:11]
	v_mfma_f32_16x16x32_bf16 v[52:55], v[186:189], v[202:205], 0
	v_mfma_f32_16x16x32_bf16 v[48:51], v[194:197], v[202:205], 0
	v_mfma_f32_16x16x32_bf16 v[36:39], v[186:189], v[210:213], 0
	v_mfma_f32_16x16x32_bf16 v[32:35], v[194:197], v[210:213], 0
	v_mfma_f32_16x16x32_bf16 v[20:23], v[186:189], v[218:221], 0
	v_mfma_f32_16x16x32_bf16 v[16:19], v[194:197], v[218:221], 0
	v_mfma_f32_16x16x32_bf16 v[4:7], v[186:189], v[230:233], 0
	v_mfma_f32_16x16x32_bf16 v[0:3], v[194:197], v[230:233], 0
	v_mfma_f32_16x16x32_bf16 v[52:55], v[190:193], v[206:209], v[52:55]
	v_mfma_f32_16x16x32_bf16 v[48:51], v[198:201], v[206:209], v[48:51]
	v_mfma_f32_16x16x32_bf16 v[36:39], v[190:193], v[214:217], v[36:39]
	v_mfma_f32_16x16x32_bf16 v[32:35], v[198:201], v[214:217], v[32:35]
	v_mfma_f32_16x16x32_bf16 v[20:23], v[190:193], v[226:229], v[20:23]
	v_mfma_f32_16x16x32_bf16 v[16:19], v[198:201], v[226:229], v[16:19]
	v_mfma_f32_16x16x32_bf16 v[4:7], v[190:193], v[234:237], v[4:7]
	v_mfma_f32_16x16x32_bf16 v[0:3], v[198:201], v[234:237], v[0:3]
	s_barrier
	s_setprio 0
	s_add_i32 s50, 0, 0x18000
	v_add_u32_e32 v154, s50, v159
	s_add_i32 s51, 0, 0x1c000
	ds_read_b128 v[146:149], v154
	ds_read_b128 v[150:153], v154 offset:1024
	ds_read_b128 v[178:181], v154 offset:2048
	ds_read_b128 v[182:185], v154 offset:3072
	v_add_u32_e32 v154, s51, v159
	ds_read_b128 v[186:189], v154
	ds_read_b128 v[190:193], v154 offset:1024
	ds_read_b128 v[194:197], v154 offset:2048
	ds_read_b128 v[198:201], v154 offset:3072
	s_add_u32 s36, s36, 0x80000
	s_addc_u32 s37, s37, 0
	s_mov_b32 m0, s23
	v_lshl_add_u64 v[172:173], s[36:37], 0, v[134:135]
	ds_read_b128 v[202:205], v175 offset:32768
	ds_read_b128 v[206:209], v175 offset:33792
	ds_read_b128 v[210:213], v175 offset:34816
	ds_read_b128 v[214:217], v175 offset:35840
	ds_read_b128 v[218:221], v175 offset:36864
	ds_read_b128 v[226:229], v175 offset:37888
	ds_read_b128 v[230:233], v175 offset:38912
	ds_read_b128 v[234:237], v175 offset:39936
	global_load_lds_dwordx4 v[172:173], off
	v_lshl_add_u64 v[172:173], s[36:37], 0, v[130:131]
	s_mov_b32 m0, s27
	s_nop 0
	global_load_lds_dwordx4 v[172:173], off
	s_waitcnt vmcnt(8)
	s_waitcnt lgkmcnt(0)
	s_setprio 1
	s_barrier
	v_mfma_f32_16x16x32_bf16 v[124:127], v[146:149], v[202:205], v[124:127]
	v_mfma_f32_16x16x32_bf16 v[120:123], v[178:181], v[202:205], v[120:123]
	v_mfma_f32_16x16x32_bf16 v[108:111], v[146:149], v[210:213], v[108:111]
	v_mfma_f32_16x16x32_bf16 v[104:107], v[178:181], v[210:213], v[104:107]
	v_mfma_f32_16x16x32_bf16 v[92:95], v[146:149], v[218:221], v[92:95]
	v_mfma_f32_16x16x32_bf16 v[88:91], v[178:181], v[218:221], v[88:91]
	v_mfma_f32_16x16x32_bf16 v[76:79], v[146:149], v[230:233], v[76:79]
	v_mfma_f32_16x16x32_bf16 v[72:75], v[178:181], v[230:233], v[72:75]
	v_mfma_f32_16x16x32_bf16 v[124:127], v[150:153], v[206:209], v[124:127]
	v_mfma_f32_16x16x32_bf16 v[120:123], v[182:185], v[206:209], v[120:123]
	v_mfma_f32_16x16x32_bf16 v[108:111], v[150:153], v[214:217], v[108:111]
	v_mfma_f32_16x16x32_bf16 v[104:107], v[182:185], v[214:217], v[104:107]
	v_mfma_f32_16x16x32_bf16 v[92:95], v[150:153], v[226:229], v[92:95]
	v_mfma_f32_16x16x32_bf16 v[88:91], v[182:185], v[226:229], v[88:91]
	v_mfma_f32_16x16x32_bf16 v[76:79], v[150:153], v[234:237], v[76:79]
	v_mfma_f32_16x16x32_bf16 v[72:75], v[182:185], v[234:237], v[72:75]
	v_mfma_f32_16x16x32_bf16 v[116:119], v[186:189], v[202:205], v[116:119]
	v_mfma_f32_16x16x32_bf16 v[112:115], v[194:197], v[202:205], v[112:115]
	v_mfma_f32_16x16x32_bf16 v[100:103], v[186:189], v[210:213], v[100:103]
	v_mfma_f32_16x16x32_bf16 v[96:99], v[194:197], v[210:213], v[96:99]
	v_mfma_f32_16x16x32_bf16 v[84:87], v[186:189], v[218:221], v[84:87]
	v_mfma_f32_16x16x32_bf16 v[80:83], v[194:197], v[218:221], v[80:83]
	v_mfma_f32_16x16x32_bf16 v[68:71], v[186:189], v[230:233], v[68:71]
	v_mfma_f32_16x16x32_bf16 v[64:67], v[194:197], v[230:233], v[64:67]
	v_mfma_f32_16x16x32_bf16 v[116:119], v[190:193], v[206:209], v[116:119]
	v_mfma_f32_16x16x32_bf16 v[112:115], v[198:201], v[206:209], v[112:115]
	v_mfma_f32_16x16x32_bf16 v[100:103], v[190:193], v[214:217], v[100:103]
	v_mfma_f32_16x16x32_bf16 v[96:99], v[198:201], v[214:217], v[96:99]
	v_mfma_f32_16x16x32_bf16 v[84:87], v[190:193], v[226:229], v[84:87]
	v_mfma_f32_16x16x32_bf16 v[80:83], v[198:201], v[226:229], v[80:83]
	v_mfma_f32_16x16x32_bf16 v[68:71], v[190:193], v[234:237], v[68:71]
	v_mfma_f32_16x16x32_bf16 v[64:67], v[198:201], v[234:237], v[64:67]
	s_barrier
; #define PG8_STAGE(bufoff, gbase, voff) do { _Pragma("unroll") for (int _i = 0; _i < 2; ++_i) \
;         __builtin_amdgcn_global_load_lds((const unsigned*)((const char*)(gbase) + (voff)[_i]), (PG8_LAS unsigned*)(lds + (bufoff) + ldsw + _i * 8192), 16, 0, 0); } while (0)
; #define PG8_LDA(dst, b, h) do { _Pragma("unroll") for (int m = 0; m < 4; ++m) _Pragma("unroll") for (int k = 0; k < 2; ++k) dst[m][k] = *(const PG8_LAS bf16x8*)(lds + PG8_SA(b, h) + aoff + m * 2048 + k * 1024); } while (0)
; #define PG8_MMA(ai, bj, At, Bt) do { __builtin_amdgcn_s_setprio(1); _Pragma("unroll") for (int m = 0; m < 4; ++m) _Pragma("unroll") for (int n = 0; n < 2; ++n) _Pragma("unroll") for (int k = 0; k < 2; ++k) \
;         acc[ai][bj][m][n] = __builtin_amdgcn_mfma_f32_16x16x32_bf16(Bt[n][k], At[m][k], acc[ai][bj][m][n], 0, 0, 0); __builtin_amdgcn_s_setprio(0); } while (0)
; #define PG8_WAIT_V(n) asm volatile("s_waitcnt vmcnt(" #n ")" ::: "memory")
; #define PG8_WAIT_L(n) asm volatile("s_waitcnt lgkmcnt(" #n ")" ::: "memory")
; #define PG8_BAR __builtin_amdgcn_s_barrier()
; #define PG8_SCHED __builtin_amdgcn_sched_barrier(0)
; template <class Epi, class Sched, bool ALIGN_EPI = false, bool SP2 = false>
; __device__ __forceinline__ void gemm_phase(PG8_LAS unsigned char* lds, const Gemm g, const Sched& S, const Epi& E) {
;     ...
;         for (int t = 0; t < nt; t += 2) {
;             const bool last = (t == nt - 2);
;             const char* a1 = cA + (size_t)(t + 1) * kstep;
;             const char* a2 = last ? nA : cA + (size_t)(t + 2) * kstep; const char* b2 = last ? nB : cB + (size_t)(t + 2) * kstep;
;     ...
;             PG8_LDA(At, 1, 1); PG8_STAGE(PG8_SB(1, 0), b3, voffB); PG8_STAGE(PG8_SB(1, 1), b3 + hstep, voffB); PG8_STAGE(PG8_SA(1, 0), a3, voffA);
;             PG8_WAIT_V(8); PG8_WAIT_L(0); PG8_BAR; PG8_MMA(1, 0, At, B0); PG8_MMA(1, 1, At, B1); PG8_BAR; PG8_SCHED;
	s_setprio 0
	s_add_i32 s36, s50, s3
	v_lshl_add_u64 v[156:157], v[156:157], 0, s[10:11]
	s_mov_b32 m0, s36
	ds_read_b128 v[202:205], v175 offset:49152
	ds_read_b128 v[206:209], v175 offset:50176
	ds_read_b128 v[210:213], v175 offset:51200
	ds_read_b128 v[214:217], v175 offset:52224
	ds_read_b128 v[218:221], v175 offset:53248
	ds_read_b128 v[226:229], v175 offset:54272
	ds_read_b128 v[230:233], v175 offset:55296
	ds_read_b128 v[234:237], v175 offset:56320
	global_load_lds_dwordx4 v[156:157], off
	s_add_i32 m0, s36, 0x2000
	s_add_u32 s30, s30, 0x80080
	v_lshl_add_u64 v[156:157], v[160:161], 0, s[10:11]
	s_addc_u32 s31, s31, 0
	s_add_i32 s36, s51, s3
	global_load_lds_dwordx4 v[156:157], off
	v_lshl_add_u64 v[156:157], s[30:31], 0, v[132:133]
	s_mov_b32 m0, s36
	s_nop 0
	global_load_lds_dwordx4 v[156:157], off
	v_lshl_add_u64 v[156:157], s[30:31], 0, v[128:129]
	s_add_i32 m0, s36, 0x2000
	s_nop 0
	global_load_lds_dwordx4 v[156:157], off
	v_lshl_add_u64 v[156:157], v[164:165], 0, s[10:11]
	s_mov_b32 m0, s35
	s_nop 0
	global_load_lds_dwordx4 v[156:157], off
	v_lshl_add_u64 v[156:157], v[168:169], 0, s[10:11]
	s_mov_b32 m0, s42
	s_nop 0
	global_load_lds_dwordx4 v[156:157], off
	s_waitcnt vmcnt(8)
	s_waitcnt lgkmcnt(0)
	s_setprio 1
	s_barrier
	v_mfma_f32_16x16x32_bf16 v[60:63], v[146:149], v[202:205], v[60:63]
	v_mfma_f32_16x16x32_bf16 v[56:59], v[178:181], v[202:205], v[56:59]
	v_mfma_f32_16x16x32_bf16 v[44:47], v[146:149], v[210:213], v[44:47]
	v_mfma_f32_16x16x32_bf16 v[40:43], v[178:181], v[210:213], v[40:43]
	v_mfma_f32_16x16x32_bf16 v[28:31], v[146:149], v[218:221], v[28:31]
	v_mfma_f32_16x16x32_bf16 v[24:27], v[178:181], v[218:221], v[24:27]
	v_mfma_f32_16x16x32_bf16 v[12:15], v[146:149], v[230:233], v[12:15]
	v_mfma_f32_16x16x32_bf16 v[8:11], v[178:181], v[230:233], v[8:11]
	v_mfma_f32_16x16x32_bf16 v[60:63], v[150:153], v[206:209], v[60:63]
	v_mfma_f32_16x16x32_bf16 v[56:59], v[182:185], v[206:209], v[56:59]
	v_mfma_f32_16x16x32_bf16 v[44:47], v[150:153], v[214:217], v[44:47]
	v_mfma_f32_16x16x32_bf16 v[40:43], v[182:185], v[214:217], v[40:43]
	v_mfma_f32_16x16x32_bf16 v[28:31], v[150:153], v[226:229], v[28:31]
	v_mfma_f32_16x16x32_bf16 v[24:27], v[182:185], v[226:229], v[24:27]
	v_mfma_f32_16x16x32_bf16 v[12:15], v[150:153], v[234:237], v[12:15]
	v_mfma_f32_16x16x32_bf16 v[8:11], v[182:185], v[234:237], v[8:11]
	v_mfma_f32_16x16x32_bf16 v[52:55], v[186:189], v[202:205], v[52:55]
	v_mfma_f32_16x16x32_bf16 v[48:51], v[194:197], v[202:205], v[48:51]
	v_mfma_f32_16x16x32_bf16 v[36:39], v[186:189], v[210:213], v[36:39]
	v_mfma_f32_16x16x32_bf16 v[32:35], v[194:197], v[210:213], v[32:35]
	v_mfma_f32_16x16x32_bf16 v[20:23], v[186:189], v[218:221], v[20:23]
	v_mfma_f32_16x16x32_bf16 v[16:19], v[194:197], v[218:221], v[16:19]
	v_mfma_f32_16x16x32_bf16 v[4:7], v[186:189], v[230:233], v[4:7]
	v_mfma_f32_16x16x32_bf16 v[0:3], v[194:197], v[230:233], v[0:3]
	v_mfma_f32_16x16x32_bf16 v[52:55], v[190:193], v[206:209], v[52:55]
	v_mfma_f32_16x16x32_bf16 v[48:51], v[198:201], v[206:209], v[48:51]
	v_mfma_f32_16x16x32_bf16 v[36:39], v[190:193], v[214:217], v[36:39]
	v_mfma_f32_16x16x32_bf16 v[32:35], v[198:201], v[214:217], v[32:35]
	v_mfma_f32_16x16x32_bf16 v[20:23], v[190:193], v[226:229], v[20:23]
	v_mfma_f32_16x16x32_bf16 v[16:19], v[198:201], v[226:229], v[16:19]
	v_mfma_f32_16x16x32_bf16 v[4:7], v[190:193], v[234:237], v[4:7]
	v_mfma_f32_16x16x32_bf16 v[0:3], v[198:201], v[234:237], v[0:3]
	s_barrier
	s_setprio 0
	s_add_i32 s49, s49, 2
	s_add_u32 s28, s28, 0x100
	s_addc_u32 s29, s29, 0
	s_add_u32 s47, s47, 0x100
	s_addc_u32 s48, s48, 0
	s_cmp_gt_u32 s49, 29

; #define PG8_STAGE(bufoff, gbase, voff) do { _Pragma("unroll") for (int _i = 0; _i < 2; ++_i) \
;         __builtin_amdgcn_global_load_lds((const unsigned*)((const char*)(gbase) + (voff)[_i]), (PG8_LAS unsigned*)(lds + (bufoff) + ldsw + _i * 8192), 16, 0, 0); } while (0)
; #define PG8_LDA(dst, b, h) do { _Pragma("unroll") for (int m = 0; m < 4; ++m) _Pragma("unroll") for (int k = 0; k < 2; ++k) dst[m][k] = *(const PG8_LAS bf16x8*)(lds + PG8_SA(b, h) + aoff + m * 2048 + k * 1024); } while (0)
; #define PG8_LDB(dst, b, h) do { _Pragma("unroll") for (int n = 0; n < 2; ++n) _Pragma("unroll") for (int k = 0; k < 2; ++k) dst[n][k] = *(const PG8_LAS bf16x8*)(lds + PG8_SB(b, h) + boff + n * 2048 + k * 1024); } while (0)
; #define PG8_MMA(ai, bj, At, Bt) do { __builtin_amdgcn_s_setprio(1); _Pragma("unroll") for (int m = 0; m < 4; ++m) _Pragma("unroll") for (int n = 0; n < 2; ++n) _Pragma("unroll") for (int k = 0; k < 2; ++k) \
;         acc[ai][bj][m][n] = __builtin_amdgcn_mfma_f32_16x16x32_bf16(Bt[n][k], At[m][k], acc[ai][bj][m][n], 0, 0, 0); __builtin_amdgcn_s_setprio(0); } while (0)
; #define PG8_WAIT_V(n) asm volatile("s_waitcnt vmcnt(" #n ")" ::: "memory")
; #define PG8_WAIT_L(n) asm volatile("s_waitcnt lgkmcnt(" #n ")" ::: "memory")
; #define PG8_BAR __builtin_amdgcn_s_barrier()
; #define PG8_SCHED __builtin_amdgcn_sched_barrier(0)
; template <class Epi, class Sched, bool ALIGN_EPI = false, bool SP2 = false>
; __device__ __forceinline__ void gemm_phase(PG8_LAS unsigned char* lds, const Gemm g, const Sched& S, const Epi& E) {
;     ...
;             const char* a1 = cA + (size_t)(t + 1) * kstep;
;             const char* a2 = last ? nA : cA + (size_t)(t + 2) * kstep; const char* b2 = last ? nB : cB + (size_t)(t + 2) * kstep;
;             const char* a3 = a2 + kstep; const char* b3 = b2 + kstep;
;             if (last && has_next) S.a_ready(nxt);
;             if constexpr (SP2) {
;             PG8_LDB(B0, 0, 0); PG8_LDB(B1, 0, 1); PG8_SCHED; PG8_LDA(At, 0, 0); PG8_STAGE(PG8_SA(1, 1), a1 + hstep, voffA);
;             PG8_WAIT_V(8); PG8_WAIT_L(0); PG8_BAR; PG8_MMA(0, 0, At, B0); PG8_MMA(0, 1, At, B1); PG8_BAR; PG8_SCHED;
;             PG8_LDA(At, 0, 1); PG8_STAGE(PG8_SB(0, 0), b2, voffB); PG8_STAGE(PG8_SB(0, 1), b2 + hstep, voffB); PG8_STAGE(PG8_SA(0, 0), a2, voffA);
.LBB0_1107:
	s_add_u32 s13, s30, 0x100
	s_addc_u32 s49, s31, 0
	s_mov_b32 s50, -2
	s_waitcnt lgkmcnt(0)
	ds_read_b128 v[128:131], v209
	ds_read_b128 v[132:135], v209 offset:1024
	ds_read_b128 v[136:139], v209 offset:2048
	ds_read_b128 v[140:143], v209 offset:3072
	ds_read_b128 v[144:147], v210
	ds_read_b128 v[148:151], v210 offset:1024
	ds_read_b128 v[152:155], v210 offset:2048
	ds_read_b128 v[156:159], v210 offset:3072
	s_add_u32 s30, s28, 0x100
	s_addc_u32 s31, s29, 0
	s_cmpk_eq_i32 s50, 0x54
	s_cselect_b32 s41, s11, s31
	s_cselect_b32 s40, s10, s30
	s_cselect_b32 s37, s27, s49
	s_cselect_b32 s36, s26, s13
	v_lshl_add_u64 v[204:205], s[28:29], 0, v[180:181]
	s_add_i32 m0, s15, 0xc000
	ds_read_b128 v[160:163], v211
	ds_read_b128 v[164:167], v211 offset:1024
	ds_read_b128 v[168:171], v211 offset:2048
	ds_read_b128 v[172:175], v211 offset:3072
	ds_read_b128 v[188:191], v211 offset:4096
	ds_read_b128 v[192:195], v211 offset:5120
	ds_read_b128 v[196:199], v211 offset:6144
	ds_read_b128 v[200:203], v211 offset:7168
	global_load_lds_dwordx4 v[204:205], off
	v_lshl_add_u64 v[204:205], s[28:29], 0, v[182:183]
	s_add_i32 m0, s15, 0xe000
	s_nop 0
	global_load_lds_dwordx4 v[204:205], off
	s_waitcnt vmcnt(8)
	s_waitcnt lgkmcnt(0)
	s_setprio 1
	s_barrier
	v_mfma_f32_16x16x32_bf16 v[124:127], v[128:131], v[160:163], 0
	v_mfma_f32_16x16x32_bf16 v[120:123], v[136:139], v[160:163], 0
	v_mfma_f32_16x16x32_bf16 v[108:111], v[128:131], v[168:171], 0
	v_mfma_f32_16x16x32_bf16 v[104:107], v[136:139], v[168:171], 0
	v_mfma_f32_16x16x32_bf16 v[92:95], v[128:131], v[188:191], 0
	v_mfma_f32_16x16x32_bf16 v[88:91], v[136:139], v[188:191], 0
	v_mfma_f32_16x16x32_bf16 v[76:79], v[128:131], v[196:199], 0
	v_mfma_f32_16x16x32_bf16 v[72:75], v[136:139], v[196:199], 0
	v_mfma_f32_16x16x32_bf16 v[124:127], v[132:135], v[164:167], v[124:127]
	v_mfma_f32_16x16x32_bf16 v[120:123], v[140:143], v[164:167], v[120:123]
	v_mfma_f32_16x16x32_bf16 v[108:111], v[132:135], v[172:175], v[108:111]
	v_mfma_f32_16x16x32_bf16 v[104:107], v[140:143], v[172:175], v[104:107]
	v_mfma_f32_16x16x32_bf16 v[92:95], v[132:135], v[192:195], v[92:95]
	v_mfma_f32_16x16x32_bf16 v[88:91], v[140:143], v[192:195], v[88:91]
	v_mfma_f32_16x16x32_bf16 v[76:79], v[132:135], v[200:203], v[76:79]
	v_mfma_f32_16x16x32_bf16 v[72:75], v[140:143], v[200:203], v[72:75]
	v_mfma_f32_16x16x32_bf16 v[116:119], v[144:147], v[160:163], 0
	v_mfma_f32_16x16x32_bf16 v[112:115], v[152:155], v[160:163], 0
	v_mfma_f32_16x16x32_bf16 v[100:103], v[144:147], v[168:171], 0
	v_mfma_f32_16x16x32_bf16 v[96:99], v[152:155], v[168:171], 0
	v_mfma_f32_16x16x32_bf16 v[84:87], v[144:147], v[188:191], 0
	v_mfma_f32_16x16x32_bf16 v[80:83], v[152:155], v[188:191], 0
	v_mfma_f32_16x16x32_bf16 v[68:71], v[144:147], v[196:199], 0
	v_mfma_f32_16x16x32_bf16 v[64:67], v[152:155], v[196:199], 0
	v_mfma_f32_16x16x32_bf16 v[116:119], v[148:151], v[164:167], v[116:119]
	v_mfma_f32_16x16x32_bf16 v[112:115], v[156:159], v[164:167], v[112:115]
	v_mfma_f32_16x16x32_bf16 v[100:103], v[148:151], v[172:175], v[100:103]
	v_mfma_f32_16x16x32_bf16 v[96:99], v[156:159], v[172:175], v[96:99]
	v_mfma_f32_16x16x32_bf16 v[84:87], v[148:151], v[192:195], v[84:87]
	v_mfma_f32_16x16x32_bf16 v[80:83], v[156:159], v[192:195], v[80:83]
	v_mfma_f32_16x16x32_bf16 v[68:71], v[148:151], v[200:203], v[68:71]
	v_mfma_f32_16x16x32_bf16 v[64:67], v[156:159], v[200:203], v[64:67]
	s_barrier
	s_setprio 0
	s_add_i32 s28, s44, s14
	v_lshl_add_u64 v[204:205], s[36:37], 0, v[176:177]
	s_mov_b32 m0, s28
	ds_read_b128 v[160:163], v211 offset:16384
	ds_read_b128 v[164:167], v211 offset:17408
	ds_read_b128 v[168:171], v211 offset:18432
	ds_read_b128 v[172:175], v211 offset:19456
	ds_read_b128 v[188:191], v211 offset:20480
	ds_read_b128 v[192:195], v211 offset:21504
	ds_read_b128 v[196:199], v211 offset:22528
	ds_read_b128 v[200:203], v211 offset:23552
	global_load_lds_dwordx4 v[204:205], off
	s_add_i32 m0, s28, 0x2000
	s_add_u32 s28, s36, 0x160000
	v_lshl_add_u64 v[212:213], s[36:37], 0, v[178:179]
	s_addc_u32 s29, s37, 0
	s_add_i32 s51, s45, s14
	global_load_lds_dwordx4 v[212:213], off
	v_lshl_add_u64 v[214:215], s[28:29], 0, v[176:177]
	s_mov_b32 m0, s51
	v_lshl_add_u64 v[216:217], s[40:41], 0, v[178:179]
	global_load_lds_dwordx4 v[214:215], off
	v_lshl_add_u64 v[214:215], s[28:29], 0, v[178:179]
	s_add_i32 m0, s51, 0x2000
	s_nop 0
	global_load_lds_dwordx4 v[214:215], off
	v_lshl_add_u64 v[214:215], s[40:41], 0, v[176:177]
	s_mov_b32 m0, s15
	s_nop 0
	global_load_lds_dwordx4 v[214:215], off
	s_mov_b32 m0, s22
	s_nop 0
	global_load_lds_dwordx4 v[216:217], off
	s_waitcnt vmcnt(8)
	s_waitcnt lgkmcnt(0)
	s_setprio 1
	s_barrier
; #define PG8_STAGE(bufoff, gbase, voff) do { _Pragma("unroll") for (int _i = 0; _i < 2; ++_i) \
;         __builtin_amdgcn_global_load_lds((const unsigned*)((const char*)(gbase) + (voff)[_i]), (PG8_LAS unsigned*)(lds + (bufoff) + ldsw + _i * 8192), 16, 0, 0); } while (0)
; #define PG8_LDA(dst, b, h) do { _Pragma("unroll") for (int m = 0; m < 4; ++m) _Pragma("unroll") for (int k = 0; k < 2; ++k) dst[m][k] = *(const PG8_LAS bf16x8*)(lds + PG8_SA(b, h) + aoff + m * 2048 + k * 1024); } while (0)
; #define PG8_LDB(dst, b, h) do { _Pragma("unroll") for (int n = 0; n < 2; ++n) _Pragma("unroll") for (int k = 0; k < 2; ++k) dst[n][k] = *(const PG8_LAS bf16x8*)(lds + PG8_SB(b, h) + boff + n * 2048 + k * 1024); } while (0)
; #define PG8_MMA(ai, bj, At, Bt) do { __builtin_amdgcn_s_setprio(1); _Pragma("unroll") for (int m = 0; m < 4; ++m) _Pragma("unroll") for (int n = 0; n < 2; ++n) _Pragma("unroll") for (int k = 0; k < 2; ++k) \
;         acc[ai][bj][m][n] = __builtin_amdgcn_mfma_f32_16x16x32_bf16(Bt[n][k], At[m][k], acc[ai][bj][m][n], 0, 0, 0); __builtin_amdgcn_s_setprio(0); } while (0)
; #define PG8_WAIT_V(n) asm volatile("s_waitcnt vmcnt(" #n ")" ::: "memory")
; template <class Epi, class Sched, bool ALIGN_EPI = false, bool SP2 = false>
; __device__ __forceinline__ void gemm_phase(PG8_LAS unsigned char* lds, const Gemm g, const Sched& S, const Epi& E) {
;     ...
;             PG8_LDB(B0, 0, 0); PG8_LDB(B1, 0, 1); PG8_SCHED; PG8_LDA(At, 0, 0); PG8_STAGE(PG8_SA(1, 1), a1 + hstep, voffA);
;             PG8_WAIT_V(8); PG8_WAIT_L(0); PG8_BAR; PG8_MMA(0, 0, At, B0); PG8_MMA(0, 1, At, B1); PG8_BAR; PG8_SCHED;
;             PG8_LDA(At, 0, 1); PG8_STAGE(PG8_SB(0, 0), b2, voffB); PG8_STAGE(PG8_SB(0, 1), b2 + hstep, voffB); PG8_STAGE(PG8_SA(0, 0), a2, voffA);
;             PG8_WAIT_V(8); PG8_WAIT_L(0); PG8_BAR; PG8_MMA(1, 0, At, B0); PG8_MMA(1, 1, At, B1); PG8_BAR; PG8_SCHED;
;             PG8_LDB(B0, 1, 0); PG8_LDB(B1, 1, 1); PG8_SCHED; PG8_LDA(At, 1, 0); PG8_STAGE(PG8_SA(0, 1), a2 + hstep, voffA);
;             PG8_WAIT_V(8); PG8_WAIT_L(0); PG8_BAR; PG8_MMA(0, 0, At, B0); PG8_MMA(0, 1, At, B1); PG8_BAR; PG8_SCHED;
;             PG8_LDA(At, 1, 1); PG8_STAGE(PG8_SB(1, 0), b3, voffB); PG8_STAGE(PG8_SB(1, 1), b3 + hstep, voffB); PG8_STAGE(PG8_SA(1, 0), a3, voffA);
;             PG8_WAIT_V(8); PG8_WAIT_L(0); PG8_BAR; PG8_MMA(1, 0, At, B0); PG8_MMA(1, 1, At, B1); PG8_BAR; PG8_SCHED;
	v_mfma_f32_16x16x32_bf16 v[60:63], v[128:131], v[160:163], 0
	v_mfma_f32_16x16x32_bf16 v[56:59], v[136:139], v[160:163], 0
	v_mfma_f32_16x16x32_bf16 v[44:47], v[128:131], v[168:171], 0
	v_mfma_f32_16x16x32_bf16 v[40:43], v[136:139], v[168:171], 0
	v_mfma_f32_16x16x32_bf16 v[28:31], v[128:131], v[188:191], 0
	v_mfma_f32_16x16x32_bf16 v[24:27], v[136:139], v[188:191], 0
	v_mfma_f32_16x16x32_bf16 v[12:15], v[128:131], v[196:199], 0
	v_mfma_f32_16x16x32_bf16 v[8:11], v[136:139], v[196:199], 0
	v_mfma_f32_16x16x32_bf16 v[60:63], v[132:135], v[164:167], v[60:63]
	v_mfma_f32_16x16x32_bf16 v[56:59], v[140:143], v[164:167], v[56:59]
	v_mfma_f32_16x16x32_bf16 v[44:47], v[132:135], v[172:175], v[44:47]
	v_mfma_f32_16x16x32_bf16 v[40:43], v[140:143], v[172:175], v[40:43]
	v_mfma_f32_16x16x32_bf16 v[28:31], v[132:135], v[192:195], v[28:31]
	v_mfma_f32_16x16x32_bf16 v[24:27], v[140:143], v[192:195], v[24:27]
	v_mfma_f32_16x16x32_bf16 v[12:15], v[132:135], v[200:203], v[12:15]
	v_mfma_f32_16x16x32_bf16 v[8:11], v[140:143], v[200:203], v[8:11]
	v_mfma_f32_16x16x32_bf16 v[52:55], v[144:147], v[160:163], 0
	v_mfma_f32_16x16x32_bf16 v[48:51], v[152:155], v[160:163], 0
	v_mfma_f32_16x16x32_bf16 v[36:39], v[144:147], v[168:171], 0
	v_mfma_f32_16x16x32_bf16 v[32:35], v[152:155], v[168:171], 0
	v_mfma_f32_16x16x32_bf16 v[20:23], v[144:147], v[188:191], 0
	v_mfma_f32_16x16x32_bf16 v[16:19], v[152:155], v[188:191], 0
	v_mfma_f32_16x16x32_bf16 v[4:7], v[144:147], v[196:199], 0
	v_mfma_f32_16x16x32_bf16 v[0:3], v[152:155], v[196:199], 0
	v_mfma_f32_16x16x32_bf16 v[52:55], v[148:151], v[164:167], v[52:55]
	v_mfma_f32_16x16x32_bf16 v[48:51], v[156:159], v[164:167], v[48:51]
	v_mfma_f32_16x16x32_bf16 v[36:39], v[148:151], v[172:175], v[36:39]
	v_mfma_f32_16x16x32_bf16 v[32:35], v[156:159], v[172:175], v[32:35]
	v_mfma_f32_16x16x32_bf16 v[20:23], v[148:151], v[192:195], v[20:23]
	v_mfma_f32_16x16x32_bf16 v[16:19], v[156:159], v[192:195], v[16:19]
	v_mfma_f32_16x16x32_bf16 v[4:7], v[148:151], v[200:203], v[4:7]
	v_mfma_f32_16x16x32_bf16 v[0:3], v[156:159], v[200:203], v[0:3]
	s_barrier
	s_setprio 0
	s_add_i32 s51, 0, 0x18000
	s_add_i32 s52, 0, 0x1c000
	v_add_u32_e32 v140, s51, v207
	v_add_u32_e32 v156, s52, v207
	ds_read_b128 v[128:131], v140
	ds_read_b128 v[132:135], v140 offset:1024
	ds_read_b128 v[136:139], v140 offset:2048
	ds_read_b128 v[140:143], v140 offset:3072
	ds_read_b128 v[144:147], v156
	ds_read_b128 v[148:151], v156 offset:1024
	ds_read_b128 v[152:155], v156 offset:2048
	ds_read_b128 v[156:159], v156 offset:3072
	s_add_u32 s28, s40, 0x160000
	s_addc_u32 s29, s41, 0
	s_mov_b32 m0, s23
	v_lshl_add_u64 v[218:219], s[28:29], 0, v[176:177]
	ds_read_b128 v[160:163], v211 offset:32768
	ds_read_b128 v[164:167], v211 offset:33792
	ds_read_b128 v[168:171], v211 offset:34816
	ds_read_b128 v[172:175], v211 offset:35840
	ds_read_b128 v[188:191], v211 offset:36864
	ds_read_b128 v[192:195], v211 offset:37888
	ds_read_b128 v[196:199], v211 offset:38912
	ds_read_b128 v[200:203], v211 offset:39936
	global_load_lds_dwordx4 v[218:219], off
	v_lshl_add_u64 v[218:219], s[28:29], 0, v[178:179]
	s_mov_b32 m0, s34
	s_nop 0
	global_load_lds_dwordx4 v[218:219], off
	s_waitcnt vmcnt(8)
	s_waitcnt lgkmcnt(0)
	s_setprio 1
	s_barrier
	v_mfma_f32_16x16x32_bf16 v[124:127], v[128:131], v[160:163], v[124:127]
	v_mfma_f32_16x16x32_bf16 v[120:123], v[136:139], v[160:163], v[120:123]
	v_mfma_f32_16x16x32_bf16 v[108:111], v[128:131], v[168:171], v[108:111]
	v_mfma_f32_16x16x32_bf16 v[104:107], v[136:139], v[168:171], v[104:107]
	v_mfma_f32_16x16x32_bf16 v[92:95], v[128:131], v[188:191], v[92:95]
	v_mfma_f32_16x16x32_bf16 v[88:91], v[136:139], v[188:191], v[88:91]
	v_mfma_f32_16x16x32_bf16 v[76:79], v[128:131], v[196:199], v[76:79]
	v_mfma_f32_16x16x32_bf16 v[72:75], v[136:139], v[196:199], v[72:75]
	v_mfma_f32_16x16x32_bf16 v[124:127], v[132:135], v[164:167], v[124:127]
	v_mfma_f32_16x16x32_bf16 v[120:123], v[140:143], v[164:167], v[120:123]
	v_mfma_f32_16x16x32_bf16 v[108:111], v[132:135], v[172:175], v[108:111]
	v_mfma_f32_16x16x32_bf16 v[104:107], v[140:143], v[172:175], v[104:107]
	v_mfma_f32_16x16x32_bf16 v[92:95], v[132:135], v[192:195], v[92:95]
	v_mfma_f32_16x16x32_bf16 v[88:91], v[140:143], v[192:195], v[88:91]
	v_mfma_f32_16x16x32_bf16 v[76:79], v[132:135], v[200:203], v[76:79]
	v_mfma_f32_16x16x32_bf16 v[72:75], v[140:143], v[200:203], v[72:75]
	v_mfma_f32_16x16x32_bf16 v[116:119], v[144:147], v[160:163], v[116:119]
	v_mfma_f32_16x16x32_bf16 v[112:115], v[152:155], v[160:163], v[112:115]
	v_mfma_f32_16x16x32_bf16 v[100:103], v[144:147], v[168:171], v[100:103]
	v_mfma_f32_16x16x32_bf16 v[96:99], v[152:155], v[168:171], v[96:99]
	v_mfma_f32_16x16x32_bf16 v[84:87], v[144:147], v[188:191], v[84:87]
	v_mfma_f32_16x16x32_bf16 v[80:83], v[152:155], v[188:191], v[80:83]
	v_mfma_f32_16x16x32_bf16 v[68:71], v[144:147], v[196:199], v[68:71]
	v_mfma_f32_16x16x32_bf16 v[64:67], v[152:155], v[196:199], v[64:67]
	v_mfma_f32_16x16x32_bf16 v[116:119], v[148:151], v[164:167], v[116:119]
	v_mfma_f32_16x16x32_bf16 v[112:115], v[156:159], v[164:167], v[112:115]
	v_mfma_f32_16x16x32_bf16 v[100:103], v[148:151], v[172:175], v[100:103]
	v_mfma_f32_16x16x32_bf16 v[96:99], v[156:159], v[172:175], v[96:99]
	v_mfma_f32_16x16x32_bf16 v[84:87], v[148:151], v[192:195], v[84:87]
	v_mfma_f32_16x16x32_bf16 v[80:83], v[156:159], v[192:195], v[80:83]
	v_mfma_f32_16x16x32_bf16 v[68:71], v[148:151], v[200:203], v[68:71]
	v_mfma_f32_16x16x32_bf16 v[64:67], v[156:159], v[200:203], v[64:67]
	s_barrier
; #define PG8_STAGE(bufoff, gbase, voff) do { _Pragma("unroll") for (int _i = 0; _i < 2; ++_i) \
;         __builtin_amdgcn_global_load_lds((const unsigned*)((const char*)(gbase) + (voff)[_i]), (PG8_LAS unsigned*)(lds + (bufoff) + ldsw + _i * 8192), 16, 0, 0); } while (0)
; #define PG8_LDA(dst, b, h) do { _Pragma("unroll") for (int m = 0; m < 4; ++m) _Pragma("unroll") for (int k = 0; k < 2; ++k) dst[m][k] = *(const PG8_LAS bf16x8*)(lds + PG8_SA(b, h) + aoff + m * 2048 + k * 1024); } while (0)
; #define PG8_MMA(ai, bj, At, Bt) do { __builtin_amdgcn_s_setprio(1); _Pragma("unroll") for (int m = 0; m < 4; ++m) _Pragma("unroll") for (int n = 0; n < 2; ++n) _Pragma("unroll") for (int k = 0; k < 2; ++k) \
;         acc[ai][bj][m][n] = __builtin_amdgcn_mfma_f32_16x16x32_bf16(Bt[n][k], At[m][k], acc[ai][bj][m][n], 0, 0, 0); __builtin_amdgcn_s_setprio(0); } while (0)
; #define PG8_WAIT_V(n) asm volatile("s_waitcnt vmcnt(" #n ")" ::: "memory")
; #define PG8_WAIT_L(n) asm volatile("s_waitcnt lgkmcnt(" #n ")" ::: "memory")
; #define PG8_BAR __builtin_amdgcn_s_barrier()
; #define PG8_SCHED __builtin_amdgcn_sched_barrier(0)
; template <class Epi, class Sched, bool ALIGN_EPI = false, bool SP2 = false>
; __device__ __forceinline__ void gemm_phase(PG8_LAS unsigned char* lds, const Gemm g, const Sched& S, const Epi& E) {
;     ...
;         for (int t = 0; t < nt; t += 2) {
;             const bool last = (t == nt - 2);
;             const char* a1 = cA + (size_t)(t + 1) * kstep;
;             const char* a2 = last ? nA : cA + (size_t)(t + 2) * kstep; const char* b2 = last ? nB : cB + (size_t)(t + 2) * kstep;
;     ...
;             PG8_LDA(At, 1, 1); PG8_STAGE(PG8_SB(1, 0), b3, voffB); PG8_STAGE(PG8_SB(1, 1), b3 + hstep, voffB); PG8_STAGE(PG8_SA(1, 0), a3, voffA);
;             PG8_WAIT_V(8); PG8_WAIT_L(0); PG8_BAR; PG8_MMA(1, 0, At, B0); PG8_MMA(1, 1, At, B1); PG8_BAR; PG8_SCHED;
	s_setprio 0
	s_add_i32 s28, s51, s14
	v_lshl_add_u64 v[204:205], v[204:205], 0, s[20:21]
	s_mov_b32 m0, s28
	ds_read_b128 v[160:163], v211 offset:49152
	ds_read_b128 v[164:167], v211 offset:50176
	ds_read_b128 v[168:171], v211 offset:51200
	ds_read_b128 v[172:175], v211 offset:52224
	ds_read_b128 v[188:191], v211 offset:53248
	ds_read_b128 v[192:195], v211 offset:54272
	ds_read_b128 v[196:199], v211 offset:55296
	ds_read_b128 v[200:203], v211 offset:56320
	global_load_lds_dwordx4 v[204:205], off
	s_add_i32 m0, s28, 0x2000
	s_add_u32 s28, s36, 0x160080
	v_lshl_add_u64 v[204:205], v[212:213], 0, s[20:21]
	s_addc_u32 s29, s37, 0
	s_add_i32 s36, s52, s14
	global_load_lds_dwordx4 v[204:205], off
	v_lshl_add_u64 v[204:205], s[28:29], 0, v[176:177]
	s_mov_b32 m0, s36
	s_nop 0
	global_load_lds_dwordx4 v[204:205], off
	v_lshl_add_u64 v[204:205], s[28:29], 0, v[178:179]
	s_add_i32 m0, s36, 0x2000
	s_nop 0
	global_load_lds_dwordx4 v[204:205], off
	v_lshl_add_u64 v[204:205], v[214:215], 0, s[20:21]
	s_mov_b32 m0, s42
	s_nop 0
	global_load_lds_dwordx4 v[204:205], off
	v_lshl_add_u64 v[204:205], v[216:217], 0, s[20:21]
	s_mov_b32 m0, s43
	s_nop 0
	global_load_lds_dwordx4 v[204:205], off
	s_waitcnt vmcnt(8)
	s_waitcnt lgkmcnt(0)
	s_setprio 1
	s_barrier
	v_mfma_f32_16x16x32_bf16 v[60:63], v[128:131], v[160:163], v[60:63]
	v_mfma_f32_16x16x32_bf16 v[56:59], v[136:139], v[160:163], v[56:59]
	v_mfma_f32_16x16x32_bf16 v[44:47], v[128:131], v[168:171], v[44:47]
	v_mfma_f32_16x16x32_bf16 v[40:43], v[136:139], v[168:171], v[40:43]
	v_mfma_f32_16x16x32_bf16 v[28:31], v[128:131], v[188:191], v[28:31]
	v_mfma_f32_16x16x32_bf16 v[24:27], v[136:139], v[188:191], v[24:27]
	v_mfma_f32_16x16x32_bf16 v[12:15], v[128:131], v[196:199], v[12:15]
	v_mfma_f32_16x16x32_bf16 v[8:11], v[136:139], v[196:199], v[8:11]
	v_mfma_f32_16x16x32_bf16 v[60:63], v[132:135], v[164:167], v[60:63]
	v_mfma_f32_16x16x32_bf16 v[56:59], v[140:143], v[164:167], v[56:59]
	v_mfma_f32_16x16x32_bf16 v[44:47], v[132:135], v[172:175], v[44:47]
	v_mfma_f32_16x16x32_bf16 v[40:43], v[140:143], v[172:175], v[40:43]
	v_mfma_f32_16x16x32_bf16 v[28:31], v[132:135], v[192:195], v[28:31]
	v_mfma_f32_16x16x32_bf16 v[24:27], v[140:143], v[192:195], v[24:27]
	v_mfma_f32_16x16x32_bf16 v[12:15], v[132:135], v[200:203], v[12:15]
	v_mfma_f32_16x16x32_bf16 v[8:11], v[140:143], v[200:203], v[8:11]
	v_mfma_f32_16x16x32_bf16 v[52:55], v[144:147], v[160:163], v[52:55]
	v_mfma_f32_16x16x32_bf16 v[48:51], v[152:155], v[160:163], v[48:51]
	v_mfma_f32_16x16x32_bf16 v[36:39], v[144:147], v[168:171], v[36:39]
	v_mfma_f32_16x16x32_bf16 v[32:35], v[152:155], v[168:171], v[32:35]
	v_mfma_f32_16x16x32_bf16 v[20:23], v[144:147], v[188:191], v[20:23]
	v_mfma_f32_16x16x32_bf16 v[16:19], v[152:155], v[188:191], v[16:19]
	v_mfma_f32_16x16x32_bf16 v[4:7], v[144:147], v[196:199], v[4:7]
	v_mfma_f32_16x16x32_bf16 v[0:3], v[152:155], v[196:199], v[0:3]
	v_mfma_f32_16x16x32_bf16 v[52:55], v[148:151], v[164:167], v[52:55]
	v_mfma_f32_16x16x32_bf16 v[48:51], v[156:159], v[164:167], v[48:51]
	v_mfma_f32_16x16x32_bf16 v[36:39], v[148:151], v[172:175], v[36:39]
	v_mfma_f32_16x16x32_bf16 v[32:35], v[156:159], v[172:175], v[32:35]
	v_mfma_f32_16x16x32_bf16 v[20:23], v[148:151], v[192:195], v[20:23]
	v_mfma_f32_16x16x32_bf16 v[16:19], v[156:159], v[192:195], v[16:19]
	v_mfma_f32_16x16x32_bf16 v[4:7], v[148:151], v[200:203], v[4:7]
	v_mfma_f32_16x16x32_bf16 v[0:3], v[156:159], v[200:203], v[0:3]
	s_barrier
	s_setprio 0
	s_add_i32 s50, s50, 2
	s_add_u32 s13, s13, 0x100
	s_addc_u32 s49, s49, 0
	s_cmpk_gt_u32 s50, 0x55
	s_mov_b64 s[28:29], s[30:31]
